# K-loops: setprio before barrier, drop compiler-redundant lgkmcnt(0) after barrier and mid-segment setprio pair
# speedup vs baseline: 1.0117x; 1.0031x over previous
; #define PG8_STAGE(bufoff, gbase, voff) do { _Pragma("unroll") for (int _i = 0; _i < 2; ++_i) \
;         __builtin_amdgcn_global_load_lds((const unsigned*)((const char*)(gbase) + (voff)[_i]), (PG8_LAS unsigned*)(lds + (bufoff) + ldsw + _i * 8192), 16, 0, 0); } while (0)
; #define PG8_LDA(dst, b, h) do { _Pragma("unroll") for (int m = 0; m < 4; ++m) _Pragma("unroll") for (int k = 0; k < 2; ++k) dst[m][k] = *(const PG8_LAS bf16x8*)(lds + PG8_SA(b, h) + aoff + m * 2048 + k * 1024); } while (0)
; #define PG8_LDB(dst, b, h) do { _Pragma("unroll") for (int n = 0; n < 2; ++n) _Pragma("unroll") for (int k = 0; k < 2; ++k) dst[n][k] = *(const PG8_LAS bf16x8*)(lds + PG8_SB(b, h) + boff + n * 2048 + k * 1024); } while (0)
; #define PG8_MMA(ai, bj, At, Bt) do { __builtin_amdgcn_s_setprio(1); _Pragma("unroll") for (int m = 0; m < 4; ++m) _Pragma("unroll") for (int n = 0; n < 2; ++n) _Pragma("unroll") for (int k = 0; k < 2; ++k) \
;         acc[ai][bj][m][n] = __builtin_amdgcn_mfma_f32_16x16x32_bf16(Bt[n][k], At[m][k], acc[ai][bj][m][n], 0, 0, 0); __builtin_amdgcn_s_setprio(0); } while (0)
; #define PG8_WAIT_V(n) asm volatile("s_waitcnt vmcnt(" #n ")" ::: "memory")
; #define PG8_WAIT_L(n) asm volatile("s_waitcnt lgkmcnt(" #n ")" ::: "memory")
; template <class Epi, class Sched, bool ALIGN_EPI, bool SP2, int KK, int LDA, int APN>
; __device__ __forceinline__ void gemm_phase(PG8_LAS unsigned char* lds, const Gemm g, const Sched& S, const Epi& E, const int wid) {
;     ...
;             const bool last = (t == nt - 2);
;             const char* a1 = cA + (size_t)(t + 1) * kstep;
;             const char* a2 = last ? nA : cA + (size_t)(t + 2) * kstep; const char* b2 = last ? nB : cB + (size_t)(t + 2) * kstep;
;             const char* a3 = a2 + kstep; const char* b3 = b2 + kstep;
;             if (last && has_next) S.a_ready(nxt);
;             if constexpr (SP2) {
;             PG8_LDB(B0, 0, 0); PG8_LDB(B1, 0, 1); PG8_SCHED; PG8_LDA(At, 0, 0); PG8_STAGE(PG8_SA(1, 1), a1 + hstepA, voffA);
;             PG8_WAIT_V(8); PG8_WAIT_L(0); PG8_BAR; PG8_MMA(0, 0, At, B0); PG8_MMA(0, 1, At, B1); PG8_BAR; PG8_SCHED;
;             PG8_LDA(At, 0, 1); PG8_STAGE(PG8_SB(0, 0), b2, voffB); PG8_STAGE(PG8_SB(0, 1), b2 + hstep, voffB); PG8_STAGE(PG8_SA(0, 0), a2, voffA);
;             PG8_WAIT_V(8); PG8_WAIT_L(0); PG8_BAR; PG8_MMA(1, 0, At, B0); PG8_MMA(1, 1, At, B1); PG8_BAR; PG8_SCHED;
.LBB0_220:
	s_add_u32 s44, s30, 0xfff80080
	s_addc_u32 s45, s31, -1
	s_add_i32 s67, 0, 0x10000
	s_cmp_eq_u32 s66, 28
	s_cselect_b32 s47, s37, s45
	s_cselect_b32 s46, s60, s44
	v_add_u32_e32 v140, s67, v143
	s_cselect_b32 s45, s27, s65
	s_cselect_b32 s44, s61, s64
	s_add_i32 s70, 0, 0x14000
	ds_read_b128 v[148:151], v140
	ds_read_b128 v[152:155], v140 offset:1024
	ds_read_b128 v[156:159], v140 offset:2048
	ds_read_b128 v[160:163], v140 offset:3072
	v_add_u32_e32 v140, s70, v143
	ds_read_b128 v[164:167], v140
	ds_read_b128 v[168:171], v140 offset:1024
	ds_read_b128 v[172:175], v140 offset:2048
	ds_read_b128 v[176:179], v140 offset:3072
	v_lshl_add_u64 v[140:141], s[30:31], 0, v[138:139]
	s_add_i32 m0, s51, 0xc000
	ds_read_b128 v[180:183], v146
	ds_read_b128 v[184:187], v146 offset:1024
	ds_read_b128 v[188:191], v146 offset:2048
	ds_read_b128 v[202:205], v146 offset:3072
	ds_read_b128 v[206:209], v146 offset:4096
	ds_read_b128 v[212:215], v146 offset:5120
	ds_read_b128 v[226:229], v146 offset:6144
	ds_read_b128 v[230:233], v146 offset:7168
	global_load_lds_dwordx4 v[140:141], off
	v_lshl_add_u64 v[140:141], s[30:31], 0, v[136:137]
	s_add_i32 m0, s51, 0xe000
	s_nop 0
	global_load_lds_dwordx4 v[140:141], off
	s_waitcnt vmcnt(8)
	s_waitcnt lgkmcnt(0)
	s_setprio 1
	s_barrier
	v_mfma_f32_16x16x32_bf16 v[126:129], v[148:151], v[180:183], v[126:129]
	v_mfma_f32_16x16x32_bf16 v[118:121], v[156:159], v[180:183], v[118:121]
	v_mfma_f32_16x16x32_bf16 v[110:113], v[148:151], v[188:191], v[110:113]
	v_mfma_f32_16x16x32_bf16 v[102:105], v[156:159], v[188:191], v[102:105]
	v_mfma_f32_16x16x32_bf16 v[92:95], v[148:151], v[206:209], v[92:95]
	v_mfma_f32_16x16x32_bf16 v[84:87], v[156:159], v[206:209], v[84:87]
	v_mfma_f32_16x16x32_bf16 v[76:79], v[148:151], v[226:229], v[76:79]
	v_mfma_f32_16x16x32_bf16 v[68:71], v[156:159], v[226:229], v[68:71]
	v_mfma_f32_16x16x32_bf16 v[126:129], v[152:155], v[184:187], v[126:129]
	v_mfma_f32_16x16x32_bf16 v[118:121], v[160:163], v[184:187], v[118:121]
	v_mfma_f32_16x16x32_bf16 v[110:113], v[152:155], v[202:205], v[110:113]
	v_mfma_f32_16x16x32_bf16 v[102:105], v[160:163], v[202:205], v[102:105]
	v_mfma_f32_16x16x32_bf16 v[92:95], v[152:155], v[212:215], v[92:95]
	v_mfma_f32_16x16x32_bf16 v[84:87], v[160:163], v[212:215], v[84:87]
	v_mfma_f32_16x16x32_bf16 v[76:79], v[152:155], v[230:233], v[76:79]
	v_mfma_f32_16x16x32_bf16 v[68:71], v[160:163], v[230:233], v[68:71]
	v_mfma_f32_16x16x32_bf16 v[122:125], v[164:167], v[180:183], v[122:125]
	v_mfma_f32_16x16x32_bf16 v[114:117], v[172:175], v[180:183], v[114:117]
	v_mfma_f32_16x16x32_bf16 v[106:109], v[164:167], v[188:191], v[106:109]
	v_mfma_f32_16x16x32_bf16 v[98:101], v[172:175], v[188:191], v[98:101]
	v_mfma_f32_16x16x32_bf16 v[88:91], v[164:167], v[206:209], v[88:91]
	v_mfma_f32_16x16x32_bf16 v[80:83], v[172:175], v[206:209], v[80:83]
	v_mfma_f32_16x16x32_bf16 v[72:75], v[164:167], v[226:229], v[72:75]
	v_mfma_f32_16x16x32_bf16 v[64:67], v[172:175], v[226:229], v[64:67]
	v_mfma_f32_16x16x32_bf16 v[122:125], v[168:171], v[184:187], v[122:125]
	v_mfma_f32_16x16x32_bf16 v[114:117], v[176:179], v[184:187], v[114:117]
	v_mfma_f32_16x16x32_bf16 v[106:109], v[168:171], v[202:205], v[106:109]
	v_mfma_f32_16x16x32_bf16 v[98:101], v[176:179], v[202:205], v[98:101]
	v_mfma_f32_16x16x32_bf16 v[88:91], v[168:171], v[212:215], v[88:91]
	v_mfma_f32_16x16x32_bf16 v[80:83], v[176:179], v[212:215], v[80:83]
	v_mfma_f32_16x16x32_bf16 v[72:75], v[168:171], v[230:233], v[72:75]
	v_mfma_f32_16x16x32_bf16 v[64:67], v[176:179], v[230:233], v[64:67]
	s_setprio 0
	s_barrier
	s_add_i32 s67, s67, s48
	v_lshl_add_u64 v[140:141], s[44:45], 0, v[96:97]
	s_mov_b32 m0, s67
	ds_read_b128 v[180:183], v146 offset:16384
	ds_read_b128 v[184:187], v146 offset:17408
	ds_read_b128 v[188:191], v146 offset:18432
	ds_read_b128 v[202:205], v146 offset:19456
	ds_read_b128 v[206:209], v146 offset:20480
	ds_read_b128 v[212:215], v146 offset:21504
	ds_read_b128 v[226:229], v146 offset:22528
	ds_read_b128 v[230:233], v146 offset:23552
	global_load_lds_dwordx4 v[140:141], off
	s_add_i32 m0, s67, 0x2000
	s_add_u32 s68, s44, 0x80000
	v_lshl_add_u64 v[192:193], s[44:45], 0, v[134:135]
	s_addc_u32 s69, s45, 0
	s_add_i32 s67, s70, s48
	global_load_lds_dwordx4 v[192:193], off
	v_lshl_add_u64 v[196:197], s[68:69], 0, v[96:97]
	s_mov_b32 m0, s67
	v_lshl_add_u64 v[198:199], s[46:47], 0, v[132:133]
	global_load_lds_dwordx4 v[196:197], off
	v_lshl_add_u64 v[196:197], s[68:69], 0, v[134:135]
	s_add_i32 m0, s67, 0x2000
	s_nop 0
	global_load_lds_dwordx4 v[196:197], off
	v_lshl_add_u64 v[196:197], s[46:47], 0, v[130:131]
	s_mov_b32 m0, s51
	s_nop 0
	global_load_lds_dwordx4 v[196:197], off
	s_mov_b32 m0, s52
	s_nop 0
	global_load_lds_dwordx4 v[198:199], off
	s_waitcnt vmcnt(8)
	s_waitcnt lgkmcnt(0)
	s_setprio 1
	s_barrier
; #define PG8_STAGE(bufoff, gbase, voff) do { _Pragma("unroll") for (int _i = 0; _i < 2; ++_i) \
;         __builtin_amdgcn_global_load_lds((const unsigned*)((const char*)(gbase) + (voff)[_i]), (PG8_LAS unsigned*)(lds + (bufoff) + ldsw + _i * 8192), 16, 0, 0); } while (0)
; #define PG8_LDA(dst, b, h) do { _Pragma("unroll") for (int m = 0; m < 4; ++m) _Pragma("unroll") for (int k = 0; k < 2; ++k) dst[m][k] = *(const PG8_LAS bf16x8*)(lds + PG8_SA(b, h) + aoff + m * 2048 + k * 1024); } while (0)
; #define PG8_LDB(dst, b, h) do { _Pragma("unroll") for (int n = 0; n < 2; ++n) _Pragma("unroll") for (int k = 0; k < 2; ++k) dst[n][k] = *(const PG8_LAS bf16x8*)(lds + PG8_SB(b, h) + boff + n * 2048 + k * 1024); } while (0)
; #define PG8_MMA(ai, bj, At, Bt) do { __builtin_amdgcn_s_setprio(1); _Pragma("unroll") for (int m = 0; m < 4; ++m) _Pragma("unroll") for (int n = 0; n < 2; ++n) _Pragma("unroll") for (int k = 0; k < 2; ++k) \
;         acc[ai][bj][m][n] = __builtin_amdgcn_mfma_f32_16x16x32_bf16(Bt[n][k], At[m][k], acc[ai][bj][m][n], 0, 0, 0); __builtin_amdgcn_s_setprio(0); } while (0)
; #define PG8_WAIT_V(n) asm volatile("s_waitcnt vmcnt(" #n ")" ::: "memory")
; #define PG8_WAIT_L(n) asm volatile("s_waitcnt lgkmcnt(" #n ")" ::: "memory")
; #define PG8_BAR __builtin_amdgcn_s_barrier()
; #define PG8_SCHED __builtin_amdgcn_sched_barrier(0)
; template <class Epi, class Sched, bool ALIGN_EPI, bool SP2, int KK, int LDA, int APN>
; __device__ __forceinline__ void gemm_phase(PG8_LAS unsigned char* lds, const Gemm g, const Sched& S, const Epi& E, const int wid) {
;     ...
;             PG8_WAIT_V(8); PG8_WAIT_L(0); PG8_BAR; PG8_MMA(1, 0, At, B0); PG8_MMA(1, 1, At, B1); PG8_BAR; PG8_SCHED;
;             PG8_LDB(B0, 1, 0); PG8_LDB(B1, 1, 1); PG8_SCHED; PG8_LDA(At, 1, 0); PG8_STAGE(PG8_SA(0, 1), a2 + hstepA, voffA);
;             PG8_WAIT_V(8); PG8_WAIT_L(0); PG8_BAR; PG8_MMA(0, 0, At, B0); PG8_MMA(0, 1, At, B1); PG8_BAR; PG8_SCHED;
	v_mfma_f32_16x16x32_bf16 v[60:63], v[148:151], v[180:183], v[60:63]
	v_mfma_f32_16x16x32_bf16 v[52:55], v[156:159], v[180:183], v[52:55]
	v_mfma_f32_16x16x32_bf16 v[44:47], v[148:151], v[188:191], v[44:47]
	v_mfma_f32_16x16x32_bf16 v[36:39], v[156:159], v[188:191], v[36:39]
	v_mfma_f32_16x16x32_bf16 v[28:31], v[148:151], v[206:209], v[28:31]
	v_mfma_f32_16x16x32_bf16 v[20:23], v[156:159], v[206:209], v[20:23]
	v_mfma_f32_16x16x32_bf16 v[12:15], v[148:151], v[226:229], v[12:15]
	v_mfma_f32_16x16x32_bf16 v[4:7], v[156:159], v[226:229], v[4:7]
	v_mfma_f32_16x16x32_bf16 v[60:63], v[152:155], v[184:187], v[60:63]
	v_mfma_f32_16x16x32_bf16 v[52:55], v[160:163], v[184:187], v[52:55]
	v_mfma_f32_16x16x32_bf16 v[44:47], v[152:155], v[202:205], v[44:47]
	v_mfma_f32_16x16x32_bf16 v[36:39], v[160:163], v[202:205], v[36:39]
	v_mfma_f32_16x16x32_bf16 v[28:31], v[152:155], v[212:215], v[28:31]
	v_mfma_f32_16x16x32_bf16 v[20:23], v[160:163], v[212:215], v[20:23]
	v_mfma_f32_16x16x32_bf16 v[12:15], v[152:155], v[230:233], v[12:15]
	v_mfma_f32_16x16x32_bf16 v[4:7], v[160:163], v[230:233], v[4:7]
	v_mfma_f32_16x16x32_bf16 v[56:59], v[164:167], v[180:183], v[56:59]
	v_mfma_f32_16x16x32_bf16 v[48:51], v[172:175], v[180:183], v[48:51]
	v_mfma_f32_16x16x32_bf16 v[40:43], v[164:167], v[188:191], v[40:43]
	v_mfma_f32_16x16x32_bf16 v[32:35], v[172:175], v[188:191], v[32:35]
	v_mfma_f32_16x16x32_bf16 v[24:27], v[164:167], v[206:209], v[24:27]
	v_mfma_f32_16x16x32_bf16 v[16:19], v[172:175], v[206:209], v[16:19]
	v_mfma_f32_16x16x32_bf16 v[8:11], v[164:167], v[226:229], v[8:11]
	v_mfma_f32_16x16x32_bf16 v[0:3], v[172:175], v[226:229], v[0:3]
	v_mfma_f32_16x16x32_bf16 v[56:59], v[168:171], v[184:187], v[56:59]
	v_mfma_f32_16x16x32_bf16 v[48:51], v[176:179], v[184:187], v[48:51]
	v_mfma_f32_16x16x32_bf16 v[40:43], v[168:171], v[202:205], v[40:43]
	v_mfma_f32_16x16x32_bf16 v[32:35], v[176:179], v[202:205], v[32:35]
	v_mfma_f32_16x16x32_bf16 v[24:27], v[168:171], v[212:215], v[24:27]
	v_mfma_f32_16x16x32_bf16 v[16:19], v[176:179], v[212:215], v[16:19]
	v_mfma_f32_16x16x32_bf16 v[8:11], v[168:171], v[230:233], v[8:11]
	v_mfma_f32_16x16x32_bf16 v[0:3], v[176:179], v[230:233], v[0:3]
	s_setprio 0
	s_barrier
	s_add_i32 s67, 0, 0x18000
	v_add_u32_e32 v147, s67, v143
	s_add_i32 s68, 0, 0x1c000
	ds_read_b128 v[148:151], v147
	ds_read_b128 v[152:155], v147 offset:1024
	ds_read_b128 v[156:159], v147 offset:2048
	ds_read_b128 v[160:163], v147 offset:3072
	v_add_u32_e32 v147, s68, v143
	ds_read_b128 v[164:167], v147
	ds_read_b128 v[168:171], v147 offset:1024
	ds_read_b128 v[172:175], v147 offset:2048
	ds_read_b128 v[176:179], v147 offset:3072
	s_add_u32 s46, s46, 0x80000
	s_addc_u32 s47, s47, 0
	s_mov_b32 m0, s53
	v_lshl_add_u64 v[216:217], s[46:47], 0, v[130:131]
	ds_read_b128 v[180:183], v146 offset:32768
	ds_read_b128 v[184:187], v146 offset:33792
	ds_read_b128 v[188:191], v146 offset:34816
	ds_read_b128 v[202:205], v146 offset:35840
	ds_read_b128 v[206:209], v146 offset:36864
	ds_read_b128 v[212:215], v146 offset:37888
	ds_read_b128 v[226:229], v146 offset:38912
	ds_read_b128 v[230:233], v146 offset:39936
	global_load_lds_dwordx4 v[216:217], off
	v_lshl_add_u64 v[216:217], s[46:47], 0, v[132:133]
	s_mov_b32 m0, s54
	s_nop 0
	global_load_lds_dwordx4 v[216:217], off
	s_waitcnt vmcnt(8)
	s_waitcnt lgkmcnt(0)
	s_setprio 1
	s_barrier
	v_mfma_f32_16x16x32_bf16 v[126:129], v[148:151], v[180:183], v[126:129]
	v_mfma_f32_16x16x32_bf16 v[118:121], v[156:159], v[180:183], v[118:121]
	v_mfma_f32_16x16x32_bf16 v[110:113], v[148:151], v[188:191], v[110:113]
	v_mfma_f32_16x16x32_bf16 v[102:105], v[156:159], v[188:191], v[102:105]
	v_mfma_f32_16x16x32_bf16 v[92:95], v[148:151], v[206:209], v[92:95]
	v_mfma_f32_16x16x32_bf16 v[84:87], v[156:159], v[206:209], v[84:87]
	v_mfma_f32_16x16x32_bf16 v[76:79], v[148:151], v[226:229], v[76:79]
	v_mfma_f32_16x16x32_bf16 v[68:71], v[156:159], v[226:229], v[68:71]
	v_mfma_f32_16x16x32_bf16 v[126:129], v[152:155], v[184:187], v[126:129]
	v_mfma_f32_16x16x32_bf16 v[118:121], v[160:163], v[184:187], v[118:121]
	v_mfma_f32_16x16x32_bf16 v[110:113], v[152:155], v[202:205], v[110:113]
	v_mfma_f32_16x16x32_bf16 v[102:105], v[160:163], v[202:205], v[102:105]
	v_mfma_f32_16x16x32_bf16 v[92:95], v[152:155], v[212:215], v[92:95]
	v_mfma_f32_16x16x32_bf16 v[84:87], v[160:163], v[212:215], v[84:87]
	v_mfma_f32_16x16x32_bf16 v[76:79], v[152:155], v[230:233], v[76:79]
	v_mfma_f32_16x16x32_bf16 v[68:71], v[160:163], v[230:233], v[68:71]
	v_mfma_f32_16x16x32_bf16 v[122:125], v[164:167], v[180:183], v[122:125]
	v_mfma_f32_16x16x32_bf16 v[114:117], v[172:175], v[180:183], v[114:117]
	v_mfma_f32_16x16x32_bf16 v[106:109], v[164:167], v[188:191], v[106:109]
	v_mfma_f32_16x16x32_bf16 v[98:101], v[172:175], v[188:191], v[98:101]
	v_mfma_f32_16x16x32_bf16 v[88:91], v[164:167], v[206:209], v[88:91]
	v_mfma_f32_16x16x32_bf16 v[80:83], v[172:175], v[206:209], v[80:83]
	v_mfma_f32_16x16x32_bf16 v[72:75], v[164:167], v[226:229], v[72:75]
	v_mfma_f32_16x16x32_bf16 v[64:67], v[172:175], v[226:229], v[64:67]
	v_mfma_f32_16x16x32_bf16 v[122:125], v[168:171], v[184:187], v[122:125]
	v_mfma_f32_16x16x32_bf16 v[114:117], v[176:179], v[184:187], v[114:117]
	v_mfma_f32_16x16x32_bf16 v[106:109], v[168:171], v[202:205], v[106:109]
	v_mfma_f32_16x16x32_bf16 v[98:101], v[176:179], v[202:205], v[98:101]
	v_mfma_f32_16x16x32_bf16 v[88:91], v[168:171], v[212:215], v[88:91]
	v_mfma_f32_16x16x32_bf16 v[80:83], v[176:179], v[212:215], v[80:83]
	v_mfma_f32_16x16x32_bf16 v[72:75], v[168:171], v[230:233], v[72:75]
	v_mfma_f32_16x16x32_bf16 v[64:67], v[176:179], v[230:233], v[64:67]
	s_setprio 0
	s_barrier
; #define PG8_STAGE(bufoff, gbase, voff) do { _Pragma("unroll") for (int _i = 0; _i < 2; ++_i) \
;         __builtin_amdgcn_global_load_lds((const unsigned*)((const char*)(gbase) + (voff)[_i]), (PG8_LAS unsigned*)(lds + (bufoff) + ldsw + _i * 8192), 16, 0, 0); } while (0)
; #define PG8_LDA(dst, b, h) do { _Pragma("unroll") for (int m = 0; m < 4; ++m) _Pragma("unroll") for (int k = 0; k < 2; ++k) dst[m][k] = *(const PG8_LAS bf16x8*)(lds + PG8_SA(b, h) + aoff + m * 2048 + k * 1024); } while (0)
; #define PG8_MMA(ai, bj, At, Bt) do { __builtin_amdgcn_s_setprio(1); _Pragma("unroll") for (int m = 0; m < 4; ++m) _Pragma("unroll") for (int n = 0; n < 2; ++n) _Pragma("unroll") for (int k = 0; k < 2; ++k) \
;         acc[ai][bj][m][n] = __builtin_amdgcn_mfma_f32_16x16x32_bf16(Bt[n][k], At[m][k], acc[ai][bj][m][n], 0, 0, 0); __builtin_amdgcn_s_setprio(0); } while (0)
; #define PG8_WAIT_V(n) asm volatile("s_waitcnt vmcnt(" #n ")" ::: "memory")
; #define PG8_WAIT_L(n) asm volatile("s_waitcnt lgkmcnt(" #n ")" ::: "memory")
; #define PG8_BAR __builtin_amdgcn_s_barrier()
; #define PG8_SCHED __builtin_amdgcn_sched_barrier(0)
; template <class Epi, class Sched, bool ALIGN_EPI, bool SP2, int KK, int LDA, int APN>
; __device__ __forceinline__ void gemm_phase(PG8_LAS unsigned char* lds, const Gemm g, const Sched& S, const Epi& E, const int wid) {
;     ...
;         for (int t = 0; t < nt; t += 2) {
;             const bool last = (t == nt - 2);
;             const char* a1 = cA + (size_t)(t + 1) * kstep;
;             const char* a2 = last ? nA : cA + (size_t)(t + 2) * kstep; const char* b2 = last ? nB : cB + (size_t)(t + 2) * kstep;
;             const char* a3 = a2 + kstep; const char* b3 = b2 + kstep;
;     ...
;             PG8_LDA(At, 1, 1); PG8_STAGE(PG8_SB(1, 0), b3, voffB); PG8_STAGE(PG8_SB(1, 1), b3 + hstep, voffB); PG8_STAGE(PG8_SA(1, 0), a3, voffA);
;             PG8_WAIT_V(8); PG8_WAIT_L(0); PG8_BAR; PG8_MMA(1, 0, At, B0); PG8_MMA(1, 1, At, B1); PG8_BAR; PG8_SCHED;
	s_add_i32 s46, s67, s48
	v_lshl_add_u64 v[140:141], v[140:141], 0, s[22:23]
	s_mov_b32 m0, s46
	ds_read_b128 v[180:183], v146 offset:49152
	ds_read_b128 v[184:187], v146 offset:50176
	ds_read_b128 v[188:191], v146 offset:51200
	ds_read_b128 v[202:205], v146 offset:52224
	ds_read_b128 v[206:209], v146 offset:53248
	ds_read_b128 v[212:215], v146 offset:54272
	ds_read_b128 v[226:229], v146 offset:55296
	ds_read_b128 v[230:233], v146 offset:56320
	global_load_lds_dwordx4 v[140:141], off
	s_add_i32 m0, s46, 0x2000
	s_add_u32 s44, s44, 0x80080
	v_lshl_add_u64 v[140:141], v[192:193], 0, s[22:23]
	s_addc_u32 s45, s45, 0
	s_add_i32 s46, s68, s48
	global_load_lds_dwordx4 v[140:141], off
	v_lshl_add_u64 v[140:141], s[44:45], 0, v[96:97]
	s_mov_b32 m0, s46
	s_nop 0
	global_load_lds_dwordx4 v[140:141], off
	v_lshl_add_u64 v[140:141], s[44:45], 0, v[134:135]
	s_add_i32 m0, s46, 0x2000
	s_nop 0
	global_load_lds_dwordx4 v[140:141], off
	v_lshl_add_u64 v[140:141], v[196:197], 0, s[22:23]
	s_mov_b32 m0, s55
	s_nop 0
	global_load_lds_dwordx4 v[140:141], off
	v_lshl_add_u64 v[140:141], v[198:199], 0, s[22:23]
	s_mov_b32 m0, s57
	s_nop 0
	global_load_lds_dwordx4 v[140:141], off
	s_waitcnt vmcnt(8)
	s_waitcnt lgkmcnt(0)
	s_setprio 1
	s_barrier
	v_mfma_f32_16x16x32_bf16 v[60:63], v[148:151], v[180:183], v[60:63]
	v_mfma_f32_16x16x32_bf16 v[52:55], v[156:159], v[180:183], v[52:55]
	v_mfma_f32_16x16x32_bf16 v[44:47], v[148:151], v[188:191], v[44:47]
	v_mfma_f32_16x16x32_bf16 v[36:39], v[156:159], v[188:191], v[36:39]
	v_mfma_f32_16x16x32_bf16 v[28:31], v[148:151], v[206:209], v[28:31]
	v_mfma_f32_16x16x32_bf16 v[20:23], v[156:159], v[206:209], v[20:23]
	v_mfma_f32_16x16x32_bf16 v[12:15], v[148:151], v[226:229], v[12:15]
	v_mfma_f32_16x16x32_bf16 v[4:7], v[156:159], v[226:229], v[4:7]
	v_mfma_f32_16x16x32_bf16 v[60:63], v[152:155], v[184:187], v[60:63]
	v_mfma_f32_16x16x32_bf16 v[52:55], v[160:163], v[184:187], v[52:55]
	v_mfma_f32_16x16x32_bf16 v[44:47], v[152:155], v[202:205], v[44:47]
	v_mfma_f32_16x16x32_bf16 v[36:39], v[160:163], v[202:205], v[36:39]
	v_mfma_f32_16x16x32_bf16 v[28:31], v[152:155], v[212:215], v[28:31]
	v_mfma_f32_16x16x32_bf16 v[20:23], v[160:163], v[212:215], v[20:23]
	v_mfma_f32_16x16x32_bf16 v[12:15], v[152:155], v[230:233], v[12:15]
	v_mfma_f32_16x16x32_bf16 v[4:7], v[160:163], v[230:233], v[4:7]
	v_mfma_f32_16x16x32_bf16 v[56:59], v[164:167], v[180:183], v[56:59]
	v_mfma_f32_16x16x32_bf16 v[48:51], v[172:175], v[180:183], v[48:51]
	v_mfma_f32_16x16x32_bf16 v[40:43], v[164:167], v[188:191], v[40:43]
	v_mfma_f32_16x16x32_bf16 v[32:35], v[172:175], v[188:191], v[32:35]
	v_mfma_f32_16x16x32_bf16 v[24:27], v[164:167], v[206:209], v[24:27]
	v_mfma_f32_16x16x32_bf16 v[16:19], v[172:175], v[206:209], v[16:19]
	v_mfma_f32_16x16x32_bf16 v[8:11], v[164:167], v[226:229], v[8:11]
	v_mfma_f32_16x16x32_bf16 v[0:3], v[172:175], v[226:229], v[0:3]
	v_mfma_f32_16x16x32_bf16 v[56:59], v[168:171], v[184:187], v[56:59]
	v_mfma_f32_16x16x32_bf16 v[48:51], v[176:179], v[184:187], v[48:51]
	v_mfma_f32_16x16x32_bf16 v[40:43], v[168:171], v[202:205], v[40:43]
	v_mfma_f32_16x16x32_bf16 v[32:35], v[176:179], v[202:205], v[32:35]
	v_mfma_f32_16x16x32_bf16 v[24:27], v[168:171], v[212:215], v[24:27]
	v_mfma_f32_16x16x32_bf16 v[16:19], v[176:179], v[212:215], v[16:19]
	v_mfma_f32_16x16x32_bf16 v[8:11], v[168:171], v[230:233], v[8:11]
	v_mfma_f32_16x16x32_bf16 v[0:3], v[176:179], v[230:233], v[0:3]
	s_setprio 0
	s_barrier
	s_add_i32 s66, s66, 2
	s_add_u32 s64, s64, 0x100
	s_addc_u32 s65, s65, 0
	s_add_u32 s30, s30, 0x100
	s_addc_u32 s31, s31, 0
	s_cmp_gt_u32 s66, 29
	s_cbranch_scc0 .LBB0_220
	s_and_b64 vcc, exec, s[18:19]
	s_cbranch_vccz .LBB0_223
	s_barrier

; #define PG8_STAGE(bufoff, gbase, voff) do { _Pragma("unroll") for (int _i = 0; _i < 2; ++_i) \
;         __builtin_amdgcn_global_load_lds((const unsigned*)((const char*)(gbase) + (voff)[_i]), (PG8_LAS unsigned*)(lds + (bufoff) + ldsw + _i * 8192), 16, 0, 0); } while (0)
; #define PG8_LDA(dst, b, h) do { _Pragma("unroll") for (int m = 0; m < 4; ++m) _Pragma("unroll") for (int k = 0; k < 2; ++k) dst[m][k] = *(const PG8_LAS bf16x8*)(lds + PG8_SA(b, h) + aoff + m * 2048 + k * 1024); } while (0)
; #define PG8_LDB(dst, b, h) do { _Pragma("unroll") for (int n = 0; n < 2; ++n) _Pragma("unroll") for (int k = 0; k < 2; ++k) dst[n][k] = *(const PG8_LAS bf16x8*)(lds + PG8_SB(b, h) + boff + n * 2048 + k * 1024); } while (0)
; #define PG8_WAIT_V(n) asm volatile("s_waitcnt vmcnt(" #n ")" ::: "memory")
; #define PG8_WAIT_L(n) asm volatile("s_waitcnt lgkmcnt(" #n ")" ::: "memory")
; #define PG8_BAR __builtin_amdgcn_s_barrier()
; #define PG8_SCHED __builtin_amdgcn_sched_barrier(0)
; template <class Epi, class Sched, bool ALIGN_EPI, bool SP2, int KK, int LDA, int APN>
; __device__ __forceinline__ void gemm_phase(PG8_LAS unsigned char* lds, const Gemm g, const Sched& S, const Epi& E, const int wid) {
;     ...
;         const char* nA = has_next ? (const char*)g.A + (size_t)nxt.pm * tstepA + (size_t)nxt.pn * APN : cA; const char* nB = has_next ? (const char*)g.Bt + (size_t)nxt.pn * tstep : cB;
; #pragma unroll 1
;         for (int t = 0; t < nt; t += 2) {
;             const bool last = (t == nt - 2);
;             const char* a1 = cA + (size_t)(t + 1) * kstep;
;             const char* a2 = last ? nA : cA + (size_t)(t + 2) * kstep; const char* b2 = last ? nB : cB + (size_t)(t + 2) * kstep;
;             const char* a3 = a2 + kstep; const char* b3 = b2 + kstep;
;             if (last && has_next) S.a_ready(nxt);
;             if constexpr (SP2) {
;             PG8_LDB(B0, 0, 0); PG8_LDB(B1, 0, 1); PG8_SCHED; PG8_LDA(At, 0, 0); PG8_STAGE(PG8_SA(1, 1), a1 + hstepA, voffA);
;             PG8_WAIT_V(8); PG8_WAIT_L(0); PG8_BAR; PG8_MMA(0, 0, At, B0); PG8_MMA(0, 1, At, B1); PG8_BAR; PG8_SCHED;
;             PG8_LDA(At, 0, 1); PG8_STAGE(PG8_SB(0, 0), b2, voffB); PG8_STAGE(PG8_SB(0, 1), b2 + hstep, voffB); PG8_STAGE(PG8_SA(0, 0), a2, voffA);
;             PG8_WAIT_V(8); PG8_WAIT_L(0); PG8_BAR; PG8_MMA(1, 0, At, B0); PG8_MMA(1, 1, At, B1); PG8_BAR; PG8_SCHED;
.LBB0_231:
	s_add_u32 s36, s14, s26
	s_addc_u32 s37, s15, s27
	s_add_u32 s28, s36, 0x100
	s_addc_u32 s29, s37, 0
	s_and_b64 s[8:9], s[18:19], exec
	s_cselect_b32 s29, s15, s29
	s_cselect_b32 s28, s14, s28
	s_add_u32 s8, s2, s26
	s_addc_u32 s9, s3, s27
	s_add_u32 s26, s8, 0x100
	s_addc_u32 s27, s9, 0
	s_add_i32 s51, 0, 0x10000
	s_and_b64 s[8:9], s[18:19], exec
	s_cselect_b32 s31, s3, s27
	s_cselect_b32 s30, s2, s26
	s_add_i32 s19, 0, 0x14000
	s_add_u32 s38, s36, 0x80080
	s_addc_u32 s39, s37, 0
	s_add_i32 s50, s51, s48
	s_add_i32 m0, s10, 0xc000
	s_add_i32 s53, s10, 0xe000
	s_add_i32 s46, s50, 0x2000
	s_add_u32 s36, s30, 0x10000
	v_add_u32_e32 v152, s51, v138
	v_add_u32_e32 v168, s19, v138
	s_addc_u32 s37, s31, 0
	s_add_i32 s49, s19, s48
	ds_read_b128 v[140:143], v152
	ds_read_b128 v[144:147], v152 offset:1024
	ds_read_b128 v[148:151], v152 offset:2048
	ds_read_b128 v[152:155], v152 offset:3072
	ds_read_b128 v[156:159], v168
	ds_read_b128 v[160:163], v168 offset:1024
	ds_read_b128 v[164:167], v168 offset:2048
	ds_read_b128 v[168:171], v168 offset:3072
	s_add_i32 s47, s49, 0x2000
	s_add_i32 s45, 0, 0x18000
	s_add_i32 s44, 0, 0x1c000
	s_add_u32 s26, s28, 0x80000
	s_addc_u32 s27, s29, 0
	s_add_i32 s9, s45, s48
	s_add_i32 s8, s9, 0x2000
	s_add_u32 s18, s30, 0x10080
	s_addc_u32 s19, s31, 0
	s_add_i32 s52, s44, s48
	s_add_i32 s51, s52, 0x2000
	v_lshl_add_u64 v[192:193], s[38:39], 0, v[134:135]
	ds_read_b128 v[172:175], v139
	ds_read_b128 v[176:179], v139 offset:1024
	ds_read_b128 v[180:183], v139 offset:2048
	ds_read_b128 v[184:187], v139 offset:3072
	ds_read_b128 v[188:191], v139 offset:4096
	ds_read_b128 v[202:205], v139 offset:5120
	ds_read_b128 v[206:209], v139 offset:6144
	ds_read_b128 v[212:215], v139 offset:7168
	global_load_lds_dwordx4 v[192:193], off
	v_lshl_add_u64 v[192:193], s[38:39], 0, v[132:133]
	s_mov_b32 m0, s53
	s_nop 0
	global_load_lds_dwordx4 v[192:193], off
	s_waitcnt vmcnt(8)
	s_waitcnt lgkmcnt(0)
	s_setprio 1
	s_barrier
	v_mfma_f32_16x16x32_bf16 v[126:129], v[140:143], v[172:175], v[126:129]
	v_mfma_f32_16x16x32_bf16 v[122:125], v[148:151], v[172:175], v[122:125]
	v_mfma_f32_16x16x32_bf16 v[118:121], v[140:143], v[180:183], v[118:121]
	v_mfma_f32_16x16x32_bf16 v[110:113], v[148:151], v[180:183], v[110:113]
	v_mfma_f32_16x16x32_bf16 v[102:105], v[140:143], v[188:191], v[102:105]
	v_mfma_f32_16x16x32_bf16 v[92:95], v[148:151], v[188:191], v[92:95]
	v_mfma_f32_16x16x32_bf16 v[84:87], v[140:143], v[206:209], v[84:87]
	v_mfma_f32_16x16x32_bf16 v[76:79], v[148:151], v[206:209], v[76:79]
	v_mfma_f32_16x16x32_bf16 v[126:129], v[144:147], v[176:179], v[126:129]
	v_mfma_f32_16x16x32_bf16 v[122:125], v[152:155], v[176:179], v[122:125]
	v_mfma_f32_16x16x32_bf16 v[118:121], v[144:147], v[184:187], v[118:121]
	v_mfma_f32_16x16x32_bf16 v[110:113], v[152:155], v[184:187], v[110:113]
	v_mfma_f32_16x16x32_bf16 v[102:105], v[144:147], v[202:205], v[102:105]
	v_mfma_f32_16x16x32_bf16 v[92:95], v[152:155], v[202:205], v[92:95]
	v_mfma_f32_16x16x32_bf16 v[84:87], v[144:147], v[212:215], v[84:87]
	v_mfma_f32_16x16x32_bf16 v[76:79], v[152:155], v[212:215], v[76:79]
	v_mfma_f32_16x16x32_bf16 v[114:117], v[156:159], v[172:175], v[114:117]
	v_mfma_f32_16x16x32_bf16 v[106:109], v[164:167], v[172:175], v[106:109]
	v_mfma_f32_16x16x32_bf16 v[98:101], v[156:159], v[180:183], v[98:101]
	v_mfma_f32_16x16x32_bf16 v[88:91], v[164:167], v[180:183], v[88:91]
	v_mfma_f32_16x16x32_bf16 v[80:83], v[156:159], v[188:191], v[80:83]
	v_mfma_f32_16x16x32_bf16 v[72:75], v[164:167], v[188:191], v[72:75]
	v_mfma_f32_16x16x32_bf16 v[68:71], v[156:159], v[206:209], v[68:71]
	v_mfma_f32_16x16x32_bf16 v[64:67], v[164:167], v[206:209], v[64:67]
	v_mfma_f32_16x16x32_bf16 v[114:117], v[160:163], v[176:179], v[114:117]
	v_mfma_f32_16x16x32_bf16 v[106:109], v[168:171], v[176:179], v[106:109]
	v_mfma_f32_16x16x32_bf16 v[98:101], v[160:163], v[184:187], v[98:101]
	v_mfma_f32_16x16x32_bf16 v[88:91], v[168:171], v[184:187], v[88:91]
	v_mfma_f32_16x16x32_bf16 v[80:83], v[160:163], v[202:205], v[80:83]
	v_mfma_f32_16x16x32_bf16 v[72:75], v[168:171], v[202:205], v[72:75]
	v_mfma_f32_16x16x32_bf16 v[68:71], v[160:163], v[212:215], v[68:71]
	v_mfma_f32_16x16x32_bf16 v[64:67], v[168:171], v[212:215], v[64:67]
	s_setprio 0
	s_barrier
	s_mov_b32 m0, s50
	v_lshl_add_u64 v[192:193], s[30:31], 0, v[96:97]
	ds_read_b128 v[172:175], v139 offset:16384
	ds_read_b128 v[176:179], v139 offset:17408
	ds_read_b128 v[180:183], v139 offset:18432
	ds_read_b128 v[184:187], v139 offset:19456
	ds_read_b128 v[188:191], v139 offset:20480
	ds_read_b128 v[202:205], v139 offset:21504
	ds_read_b128 v[206:209], v139 offset:22528
	ds_read_b128 v[212:215], v139 offset:23552
	global_load_lds_dwordx4 v[192:193], off
	v_lshl_add_u64 v[196:197], s[30:31], 0, v[130:131]
	s_mov_b32 m0, s46
	v_lshl_add_u64 v[198:199], s[36:37], 0, v[96:97]
	global_load_lds_dwordx4 v[196:197], off
	s_mov_b32 m0, s49
	v_lshl_add_u64 v[216:217], s[28:29], 0, v[132:133]
	global_load_lds_dwordx4 v[198:199], off
	v_lshl_add_u64 v[198:199], s[36:37], 0, v[130:131]
	s_mov_b32 m0, s47
	s_nop 0
	global_load_lds_dwordx4 v[198:199], off
	v_lshl_add_u64 v[198:199], s[28:29], 0, v[134:135]
	s_mov_b32 m0, s10
	s_nop 0
	global_load_lds_dwordx4 v[198:199], off
	s_mov_b32 m0, s11
	s_nop 0
	global_load_lds_dwordx4 v[216:217], off
	s_waitcnt vmcnt(8)
	s_waitcnt lgkmcnt(0)
	s_setprio 1
	s_barrier
; #define PG8_STAGE(bufoff, gbase, voff) do { _Pragma("unroll") for (int _i = 0; _i < 2; ++_i) \
;         __builtin_amdgcn_global_load_lds((const unsigned*)((const char*)(gbase) + (voff)[_i]), (PG8_LAS unsigned*)(lds + (bufoff) + ldsw + _i * 8192), 16, 0, 0); } while (0)
; #define PG8_LDA(dst, b, h) do { _Pragma("unroll") for (int m = 0; m < 4; ++m) _Pragma("unroll") for (int k = 0; k < 2; ++k) dst[m][k] = *(const PG8_LAS bf16x8*)(lds + PG8_SA(b, h) + aoff + m * 2048 + k * 1024); } while (0)
; #define PG8_LDB(dst, b, h) do { _Pragma("unroll") for (int n = 0; n < 2; ++n) _Pragma("unroll") for (int k = 0; k < 2; ++k) dst[n][k] = *(const PG8_LAS bf16x8*)(lds + PG8_SB(b, h) + boff + n * 2048 + k * 1024); } while (0)
; #define PG8_MMA(ai, bj, At, Bt) do { __builtin_amdgcn_s_setprio(1); _Pragma("unroll") for (int m = 0; m < 4; ++m) _Pragma("unroll") for (int n = 0; n < 2; ++n) _Pragma("unroll") for (int k = 0; k < 2; ++k) \
;         acc[ai][bj][m][n] = __builtin_amdgcn_mfma_f32_16x16x32_bf16(Bt[n][k], At[m][k], acc[ai][bj][m][n], 0, 0, 0); __builtin_amdgcn_s_setprio(0); } while (0)
; #define PG8_WAIT_V(n) asm volatile("s_waitcnt vmcnt(" #n ")" ::: "memory")
; #define PG8_WAIT_L(n) asm volatile("s_waitcnt lgkmcnt(" #n ")" ::: "memory")
; #define PG8_BAR __builtin_amdgcn_s_barrier()
; #define PG8_SCHED __builtin_amdgcn_sched_barrier(0)
; template <class Epi, class Sched, bool ALIGN_EPI, bool SP2, int KK, int LDA, int APN>
; __device__ __forceinline__ void gemm_phase(PG8_LAS unsigned char* lds, const Gemm g, const Sched& S, const Epi& E, const int wid) {
;     ...
;             PG8_WAIT_V(8); PG8_WAIT_L(0); PG8_BAR; PG8_MMA(1, 0, At, B0); PG8_MMA(1, 1, At, B1); PG8_BAR; PG8_SCHED;
;             PG8_LDB(B0, 1, 0); PG8_LDB(B1, 1, 1); PG8_SCHED; PG8_LDA(At, 1, 0); PG8_STAGE(PG8_SA(0, 1), a2 + hstepA, voffA);
;             PG8_WAIT_V(8); PG8_WAIT_L(0); PG8_BAR; PG8_MMA(0, 0, At, B0); PG8_MMA(0, 1, At, B1); PG8_BAR; PG8_SCHED;
	v_mfma_f32_16x16x32_bf16 v[60:63], v[140:143], v[172:175], v[60:63]
	v_mfma_f32_16x16x32_bf16 v[56:59], v[148:151], v[172:175], v[56:59]
	v_mfma_f32_16x16x32_bf16 v[52:55], v[140:143], v[180:183], v[52:55]
	v_mfma_f32_16x16x32_bf16 v[44:47], v[148:151], v[180:183], v[44:47]
	v_mfma_f32_16x16x32_bf16 v[36:39], v[140:143], v[188:191], v[36:39]
	v_mfma_f32_16x16x32_bf16 v[28:31], v[148:151], v[188:191], v[28:31]
	v_mfma_f32_16x16x32_bf16 v[20:23], v[140:143], v[206:209], v[20:23]
	v_mfma_f32_16x16x32_bf16 v[12:15], v[148:151], v[206:209], v[12:15]
	v_mfma_f32_16x16x32_bf16 v[60:63], v[144:147], v[176:179], v[60:63]
	v_mfma_f32_16x16x32_bf16 v[56:59], v[152:155], v[176:179], v[56:59]
	v_mfma_f32_16x16x32_bf16 v[52:55], v[144:147], v[184:187], v[52:55]
	v_mfma_f32_16x16x32_bf16 v[44:47], v[152:155], v[184:187], v[44:47]
	v_mfma_f32_16x16x32_bf16 v[36:39], v[144:147], v[202:205], v[36:39]
	v_mfma_f32_16x16x32_bf16 v[28:31], v[152:155], v[202:205], v[28:31]
	v_mfma_f32_16x16x32_bf16 v[20:23], v[144:147], v[212:215], v[20:23]
	v_mfma_f32_16x16x32_bf16 v[12:15], v[152:155], v[212:215], v[12:15]
	v_mfma_f32_16x16x32_bf16 v[48:51], v[156:159], v[172:175], v[48:51]
	v_mfma_f32_16x16x32_bf16 v[40:43], v[164:167], v[172:175], v[40:43]
	v_mfma_f32_16x16x32_bf16 v[32:35], v[156:159], v[180:183], v[32:35]
	v_mfma_f32_16x16x32_bf16 v[24:27], v[164:167], v[180:183], v[24:27]
	v_mfma_f32_16x16x32_bf16 v[16:19], v[156:159], v[188:191], v[16:19]
	v_mfma_f32_16x16x32_bf16 v[8:11], v[164:167], v[188:191], v[8:11]
	v_mfma_f32_16x16x32_bf16 v[4:7], v[156:159], v[206:209], v[4:7]
	v_mfma_f32_16x16x32_bf16 v[0:3], v[164:167], v[206:209], v[0:3]
	v_mfma_f32_16x16x32_bf16 v[48:51], v[160:163], v[176:179], v[48:51]
	v_mfma_f32_16x16x32_bf16 v[40:43], v[168:171], v[176:179], v[40:43]
	v_mfma_f32_16x16x32_bf16 v[32:35], v[160:163], v[184:187], v[32:35]
	v_mfma_f32_16x16x32_bf16 v[24:27], v[168:171], v[184:187], v[24:27]
	v_mfma_f32_16x16x32_bf16 v[16:19], v[160:163], v[202:205], v[16:19]
	v_mfma_f32_16x16x32_bf16 v[8:11], v[168:171], v[202:205], v[8:11]
	v_mfma_f32_16x16x32_bf16 v[4:7], v[160:163], v[212:215], v[4:7]
	v_mfma_f32_16x16x32_bf16 v[0:3], v[168:171], v[212:215], v[0:3]
	s_setprio 0
	s_barrier
	v_add_u32_e32 v152, s45, v138
	v_add_u32_e32 v168, s44, v138
	ds_read_b128 v[140:143], v152
	ds_read_b128 v[144:147], v152 offset:1024
	ds_read_b128 v[148:151], v152 offset:2048
	ds_read_b128 v[152:155], v152 offset:3072
	ds_read_b128 v[156:159], v168
	ds_read_b128 v[160:163], v168 offset:1024
	ds_read_b128 v[164:167], v168 offset:2048
	ds_read_b128 v[168:171], v168 offset:3072
	s_mov_b32 m0, s42
	v_lshl_add_u64 v[226:227], s[26:27], 0, v[134:135]
	ds_read_b128 v[172:175], v139 offset:32768
	ds_read_b128 v[176:179], v139 offset:33792
	ds_read_b128 v[180:183], v139 offset:34816
	ds_read_b128 v[184:187], v139 offset:35840
	ds_read_b128 v[188:191], v139 offset:36864
	ds_read_b128 v[202:205], v139 offset:37888
	ds_read_b128 v[206:209], v139 offset:38912
	ds_read_b128 v[212:215], v139 offset:39936
	global_load_lds_dwordx4 v[226:227], off
	v_lshl_add_u64 v[226:227], s[26:27], 0, v[132:133]
	s_mov_b32 m0, s43
	s_nop 0
	global_load_lds_dwordx4 v[226:227], off
	s_waitcnt vmcnt(8)
	s_waitcnt lgkmcnt(0)
	s_setprio 1
	s_barrier
	v_mfma_f32_16x16x32_bf16 v[126:129], v[140:143], v[172:175], v[126:129]
	v_mfma_f32_16x16x32_bf16 v[122:125], v[148:151], v[172:175], v[122:125]
	v_mfma_f32_16x16x32_bf16 v[118:121], v[140:143], v[180:183], v[118:121]
	v_mfma_f32_16x16x32_bf16 v[110:113], v[148:151], v[180:183], v[110:113]
	v_mfma_f32_16x16x32_bf16 v[102:105], v[140:143], v[188:191], v[102:105]
	v_mfma_f32_16x16x32_bf16 v[92:95], v[148:151], v[188:191], v[92:95]
	v_mfma_f32_16x16x32_bf16 v[84:87], v[140:143], v[206:209], v[84:87]
	v_mfma_f32_16x16x32_bf16 v[76:79], v[148:151], v[206:209], v[76:79]
	v_mfma_f32_16x16x32_bf16 v[126:129], v[144:147], v[176:179], v[126:129]
	v_mfma_f32_16x16x32_bf16 v[122:125], v[152:155], v[176:179], v[122:125]
	v_mfma_f32_16x16x32_bf16 v[118:121], v[144:147], v[184:187], v[118:121]
	v_mfma_f32_16x16x32_bf16 v[110:113], v[152:155], v[184:187], v[110:113]
	v_mfma_f32_16x16x32_bf16 v[102:105], v[144:147], v[202:205], v[102:105]
	v_mfma_f32_16x16x32_bf16 v[92:95], v[152:155], v[202:205], v[92:95]
	v_mfma_f32_16x16x32_bf16 v[84:87], v[144:147], v[212:215], v[84:87]
	v_mfma_f32_16x16x32_bf16 v[76:79], v[152:155], v[212:215], v[76:79]
	v_mfma_f32_16x16x32_bf16 v[114:117], v[156:159], v[172:175], v[114:117]
	v_mfma_f32_16x16x32_bf16 v[106:109], v[164:167], v[172:175], v[106:109]
	v_mfma_f32_16x16x32_bf16 v[98:101], v[156:159], v[180:183], v[98:101]
	v_mfma_f32_16x16x32_bf16 v[88:91], v[164:167], v[180:183], v[88:91]
	v_mfma_f32_16x16x32_bf16 v[80:83], v[156:159], v[188:191], v[80:83]
	v_mfma_f32_16x16x32_bf16 v[72:75], v[164:167], v[188:191], v[72:75]
	v_mfma_f32_16x16x32_bf16 v[68:71], v[156:159], v[206:209], v[68:71]
	v_mfma_f32_16x16x32_bf16 v[64:67], v[164:167], v[206:209], v[64:67]
	v_mfma_f32_16x16x32_bf16 v[114:117], v[160:163], v[176:179], v[114:117]
	v_mfma_f32_16x16x32_bf16 v[106:109], v[168:171], v[176:179], v[106:109]
	v_mfma_f32_16x16x32_bf16 v[98:101], v[160:163], v[184:187], v[98:101]
	v_mfma_f32_16x16x32_bf16 v[88:91], v[168:171], v[184:187], v[88:91]
	v_mfma_f32_16x16x32_bf16 v[80:83], v[160:163], v[202:205], v[80:83]
	v_mfma_f32_16x16x32_bf16 v[72:75], v[168:171], v[202:205], v[72:75]
	v_mfma_f32_16x16x32_bf16 v[68:71], v[160:163], v[212:215], v[68:71]
	v_mfma_f32_16x16x32_bf16 v[64:67], v[168:171], v[212:215], v[64:67]
	s_setprio 0
	s_barrier
; #define PG8_STAGE(bufoff, gbase, voff) do { _Pragma("unroll") for (int _i = 0; _i < 2; ++_i) \
;         __builtin_amdgcn_global_load_lds((const unsigned*)((const char*)(gbase) + (voff)[_i]), (PG8_LAS unsigned*)(lds + (bufoff) + ldsw + _i * 8192), 16, 0, 0); } while (0)
; #define PG8_LDA(dst, b, h) do { _Pragma("unroll") for (int m = 0; m < 4; ++m) _Pragma("unroll") for (int k = 0; k < 2; ++k) dst[m][k] = *(const PG8_LAS bf16x8*)(lds + PG8_SA(b, h) + aoff + m * 2048 + k * 1024); } while (0)
; #define PG8_MMA(ai, bj, At, Bt) do { __builtin_amdgcn_s_setprio(1); _Pragma("unroll") for (int m = 0; m < 4; ++m) _Pragma("unroll") for (int n = 0; n < 2; ++n) _Pragma("unroll") for (int k = 0; k < 2; ++k) \
;         acc[ai][bj][m][n] = __builtin_amdgcn_mfma_f32_16x16x32_bf16(Bt[n][k], At[m][k], acc[ai][bj][m][n], 0, 0, 0); __builtin_amdgcn_s_setprio(0); } while (0)
; #define PG8_WAIT_V(n) asm volatile("s_waitcnt vmcnt(" #n ")" ::: "memory")
; #define PG8_WAIT_L(n) asm volatile("s_waitcnt lgkmcnt(" #n ")" ::: "memory")
; #define PG8_BAR __builtin_amdgcn_s_barrier()
; #define PG8_SCHED __builtin_amdgcn_sched_barrier(0)
; template <class Epi, class Sched, bool ALIGN_EPI, bool SP2, int KK, int LDA, int APN>
; __device__ __forceinline__ void gemm_phase(PG8_LAS unsigned char* lds, const Gemm g, const Sched& S, const Epi& E, const int wid) {
;     ...
;             PG8_LDA(At, 1, 1); PG8_STAGE(PG8_SB(1, 0), b3, voffB); PG8_STAGE(PG8_SB(1, 1), b3 + hstep, voffB); PG8_STAGE(PG8_SA(1, 0), a3, voffA);
;             PG8_WAIT_V(8); PG8_WAIT_L(0); PG8_BAR; PG8_MMA(1, 0, At, B0); PG8_MMA(1, 1, At, B1); PG8_BAR; PG8_SCHED;
;     ...
;         if constexpr (ALIGN_EPI) { if (wr == 0) PG8_BAR; }
	s_mov_b32 m0, s9
	v_lshl_add_u64 v[192:193], v[192:193], 0, s[22:23]
	ds_read_b128 v[172:175], v139 offset:49152
	ds_read_b128 v[176:179], v139 offset:50176
	ds_read_b128 v[180:183], v139 offset:51200
	ds_read_b128 v[184:187], v139 offset:52224
	ds_read_b128 v[188:191], v139 offset:53248
	ds_read_b128 v[202:205], v139 offset:54272
	ds_read_b128 v[206:209], v139 offset:55296
	ds_read_b128 v[212:215], v139 offset:56320
	global_load_lds_dwordx4 v[192:193], off
	v_lshl_add_u64 v[192:193], v[196:197], 0, s[22:23]
	s_mov_b32 m0, s8
	s_nop 0
	global_load_lds_dwordx4 v[192:193], off
	v_lshl_add_u64 v[192:193], s[18:19], 0, v[96:97]
	s_mov_b32 m0, s52
	s_nop 0
	global_load_lds_dwordx4 v[192:193], off
	v_lshl_add_u64 v[192:193], s[18:19], 0, v[130:131]
	s_mov_b32 m0, s51
	s_nop 0
	global_load_lds_dwordx4 v[192:193], off
	v_lshl_add_u64 v[192:193], v[198:199], 0, s[22:23]
	s_mov_b32 m0, s6
	s_nop 0
	global_load_lds_dwordx4 v[192:193], off
	v_lshl_add_u64 v[192:193], v[216:217], 0, s[22:23]
	s_mov_b32 m0, s7
	s_nop 0
	global_load_lds_dwordx4 v[192:193], off
	s_waitcnt vmcnt(8)
	s_waitcnt lgkmcnt(0)
	s_setprio 1
	s_barrier
	v_mfma_f32_16x16x32_bf16 v[60:63], v[140:143], v[172:175], v[60:63]
	v_mfma_f32_16x16x32_bf16 v[56:59], v[148:151], v[172:175], v[56:59]
	v_mfma_f32_16x16x32_bf16 v[52:55], v[140:143], v[180:183], v[52:55]
	v_mfma_f32_16x16x32_bf16 v[44:47], v[148:151], v[180:183], v[44:47]
	v_mfma_f32_16x16x32_bf16 v[36:39], v[140:143], v[188:191], v[36:39]
	v_mfma_f32_16x16x32_bf16 v[28:31], v[148:151], v[188:191], v[28:31]
	v_mfma_f32_16x16x32_bf16 v[20:23], v[140:143], v[206:209], v[20:23]
	v_mfma_f32_16x16x32_bf16 v[12:15], v[148:151], v[206:209], v[12:15]
	v_mfma_f32_16x16x32_bf16 v[60:63], v[144:147], v[176:179], v[60:63]
	v_mfma_f32_16x16x32_bf16 v[56:59], v[152:155], v[176:179], v[56:59]
	v_mfma_f32_16x16x32_bf16 v[52:55], v[144:147], v[184:187], v[52:55]
	v_mfma_f32_16x16x32_bf16 v[44:47], v[152:155], v[184:187], v[44:47]
	v_mfma_f32_16x16x32_bf16 v[36:39], v[144:147], v[202:205], v[36:39]
	v_mfma_f32_16x16x32_bf16 v[28:31], v[152:155], v[202:205], v[28:31]
	v_mfma_f32_16x16x32_bf16 v[20:23], v[144:147], v[212:215], v[20:23]
	v_mfma_f32_16x16x32_bf16 v[12:15], v[152:155], v[212:215], v[12:15]
	v_mfma_f32_16x16x32_bf16 v[48:51], v[156:159], v[172:175], v[48:51]
	v_mfma_f32_16x16x32_bf16 v[40:43], v[164:167], v[172:175], v[40:43]
	v_mfma_f32_16x16x32_bf16 v[32:35], v[156:159], v[180:183], v[32:35]
	v_mfma_f32_16x16x32_bf16 v[24:27], v[164:167], v[180:183], v[24:27]
	v_mfma_f32_16x16x32_bf16 v[16:19], v[156:159], v[188:191], v[16:19]
	v_mfma_f32_16x16x32_bf16 v[8:11], v[164:167], v[188:191], v[8:11]
	v_mfma_f32_16x16x32_bf16 v[4:7], v[156:159], v[206:209], v[4:7]
	v_mfma_f32_16x16x32_bf16 v[0:3], v[164:167], v[206:209], v[0:3]
	v_mfma_f32_16x16x32_bf16 v[48:51], v[160:163], v[176:179], v[48:51]
	v_mfma_f32_16x16x32_bf16 v[40:43], v[168:171], v[176:179], v[40:43]
	v_mfma_f32_16x16x32_bf16 v[32:35], v[160:163], v[184:187], v[32:35]
	v_mfma_f32_16x16x32_bf16 v[24:27], v[168:171], v[184:187], v[24:27]
	v_mfma_f32_16x16x32_bf16 v[16:19], v[160:163], v[202:205], v[16:19]
	v_mfma_f32_16x16x32_bf16 v[8:11], v[168:171], v[202:205], v[8:11]
	v_mfma_f32_16x16x32_bf16 v[4:7], v[160:163], v[212:215], v[4:7]
	v_mfma_f32_16x16x32_bf16 v[0:3], v[168:171], v[212:215], v[0:3]
	s_setprio 0
	s_barrier
	s_andn2_b64 vcc, exec, s[16:17]
	s_mov_b64 s[18:19], -1
	s_mov_b64 s[16:17], 0
	s_mov_b64 s[26:27], 0x100
	s_cbranch_vccz .LBB0_231
	s_cmp_lt_u32 s40, 4
	s_cbranch_scc0 .LBB0_234
	s_barrier

; #define PG8_STAGE(bufoff, gbase, voff) do { _Pragma("unroll") for (int _i = 0; _i < 2; ++_i) \
;         __builtin_amdgcn_global_load_lds((const unsigned*)((const char*)(gbase) + (voff)[_i]), (PG8_LAS unsigned*)(lds + (bufoff) + ldsw + _i * 8192), 16, 0, 0); } while (0)
; #define PG8_LDA(dst, b, h) do { _Pragma("unroll") for (int m = 0; m < 4; ++m) _Pragma("unroll") for (int k = 0; k < 2; ++k) dst[m][k] = *(const PG8_LAS bf16x8*)(lds + PG8_SA(b, h) + aoff + m * 2048 + k * 1024); } while (0)
; #define PG8_LDB(dst, b, h) do { _Pragma("unroll") for (int n = 0; n < 2; ++n) _Pragma("unroll") for (int k = 0; k < 2; ++k) dst[n][k] = *(const PG8_LAS bf16x8*)(lds + PG8_SB(b, h) + boff + n * 2048 + k * 1024); } while (0)
; #define PG8_MMA(ai, bj, At, Bt) do { __builtin_amdgcn_s_setprio(1); _Pragma("unroll") for (int m = 0; m < 4; ++m) _Pragma("unroll") for (int n = 0; n < 2; ++n) _Pragma("unroll") for (int k = 0; k < 2; ++k) \
;         acc[ai][bj][m][n] = __builtin_amdgcn_mfma_f32_16x16x32_bf16(Bt[n][k], At[m][k], acc[ai][bj][m][n], 0, 0, 0); __builtin_amdgcn_s_setprio(0); } while (0)
; #define PG8_WAIT_V(n) asm volatile("s_waitcnt vmcnt(" #n ")" ::: "memory")
; #define PG8_WAIT_L(n) asm volatile("s_waitcnt lgkmcnt(" #n ")" ::: "memory")
; template <class Epi, class Sched, bool ALIGN_EPI, bool SP2, int KK, int LDA, int APN>
; __device__ __forceinline__ void gemm_phase(PG8_LAS unsigned char* lds, const Gemm g, const Sched& S, const Epi& E, const int wid) {
;     ...
;             const bool last = (t == nt - 2);
;             const char* a1 = cA + (size_t)(t + 1) * kstep;
;             const char* a2 = last ? nA : cA + (size_t)(t + 2) * kstep; const char* b2 = last ? nB : cB + (size_t)(t + 2) * kstep;
;             const char* a3 = a2 + kstep; const char* b3 = b2 + kstep;
;             if (last && has_next) S.a_ready(nxt);
;             if constexpr (SP2) {
;             PG8_LDB(B0, 0, 0); PG8_LDB(B1, 0, 1); PG8_SCHED; PG8_LDA(At, 0, 0); PG8_STAGE(PG8_SA(1, 1), a1 + hstepA, voffA);
;             PG8_WAIT_V(8); PG8_WAIT_L(0); PG8_BAR; PG8_MMA(0, 0, At, B0); PG8_MMA(0, 1, At, B1); PG8_BAR; PG8_SCHED;
;             PG8_LDA(At, 0, 1); PG8_STAGE(PG8_SB(0, 0), b2, voffB); PG8_STAGE(PG8_SB(0, 1), b2 + hstep, voffB); PG8_STAGE(PG8_SA(0, 0), a2, voffA);
;             PG8_WAIT_V(8); PG8_WAIT_L(0); PG8_BAR; PG8_MMA(1, 0, At, B0); PG8_MMA(1, 1, At, B1); PG8_BAR; PG8_SCHED;
.LBB0_309:
	s_add_u32 s40, s26, s42
	s_addc_u32 s41, s27, s43
	s_add_u32 s40, s40, 0x100
	s_addc_u32 s41, s41, 0
	s_add_u32 s48, s68, s42
	s_addc_u32 s49, s69, s43
	s_add_i32 s70, 0, 0x10000
	s_cmpk_eq_i32 s42, 0x2b00
	s_cselect_b32 s51, s31, s41
	s_cselect_b32 s50, s30, s40
	v_add_u32_e32 v144, s70, v148
	s_cselect_b32 s49, s29, s49
	s_cselect_b32 s48, s28, s48
	s_add_i32 s71, 0, 0x14000
	ds_read_b128 v[154:157], v144
	ds_read_b128 v[158:161], v144 offset:1024
	ds_read_b128 v[162:165], v144 offset:2048
	ds_read_b128 v[166:169], v144 offset:3072
	v_add_u32_e32 v144, s71, v148
	ds_read_b128 v[170:173], v144
	ds_read_b128 v[174:177], v144 offset:1024
	ds_read_b128 v[178:181], v144 offset:2048
	ds_read_b128 v[182:185], v144 offset:3072
	v_lshl_add_u64 v[144:145], v[142:143], 0, s[42:43]
	s_add_i32 m0, s13, 0xc000
	ds_read_b128 v[186:189], v150
	ds_read_b128 v[190:193], v150 offset:1024
	ds_read_b128 v[202:205], v150 offset:2048
	ds_read_b128 v[206:209], v150 offset:3072
	ds_read_b128 v[212:215], v150 offset:4096
	ds_read_b128 v[226:229], v150 offset:5120
	ds_read_b128 v[230:233], v150 offset:6144
	ds_read_b128 v[234:237], v150 offset:7168
	global_load_lds_dwordx4 v[144:145], off
	v_lshl_add_u64 v[144:145], v[140:141], 0, s[42:43]
	s_add_i32 m0, s13, 0xe000
	s_nop 0
	global_load_lds_dwordx4 v[144:145], off
	s_waitcnt vmcnt(8)
	s_waitcnt lgkmcnt(0)
	s_setprio 1
	s_barrier
	v_mfma_f32_16x16x32_bf16 v[0:3], v[154:157], v[186:189], v[0:3]
	v_mfma_f32_16x16x32_bf16 v[4:7], v[162:165], v[186:189], v[4:7]
	v_mfma_f32_16x16x32_bf16 v[16:19], v[154:157], v[202:205], v[16:19]
	v_mfma_f32_16x16x32_bf16 v[20:23], v[162:165], v[202:205], v[20:23]
	v_mfma_f32_16x16x32_bf16 v[32:35], v[154:157], v[212:215], v[32:35]
	v_mfma_f32_16x16x32_bf16 v[36:39], v[162:165], v[212:215], v[36:39]
	v_mfma_f32_16x16x32_bf16 v[48:51], v[154:157], v[230:233], v[48:51]
	v_mfma_f32_16x16x32_bf16 v[52:55], v[162:165], v[230:233], v[52:55]
	v_mfma_f32_16x16x32_bf16 v[0:3], v[158:161], v[190:193], v[0:3]
	v_mfma_f32_16x16x32_bf16 v[4:7], v[166:169], v[190:193], v[4:7]
	v_mfma_f32_16x16x32_bf16 v[16:19], v[158:161], v[206:209], v[16:19]
	v_mfma_f32_16x16x32_bf16 v[20:23], v[166:169], v[206:209], v[20:23]
	v_mfma_f32_16x16x32_bf16 v[32:35], v[158:161], v[226:229], v[32:35]
	v_mfma_f32_16x16x32_bf16 v[36:39], v[166:169], v[226:229], v[36:39]
	v_mfma_f32_16x16x32_bf16 v[48:51], v[158:161], v[234:237], v[48:51]
	v_mfma_f32_16x16x32_bf16 v[52:55], v[166:169], v[234:237], v[52:55]
	v_mfma_f32_16x16x32_bf16 v[8:11], v[170:173], v[186:189], v[8:11]
	v_mfma_f32_16x16x32_bf16 v[12:15], v[178:181], v[186:189], v[12:15]
	v_mfma_f32_16x16x32_bf16 v[24:27], v[170:173], v[202:205], v[24:27]
	v_mfma_f32_16x16x32_bf16 v[28:31], v[178:181], v[202:205], v[28:31]
	v_mfma_f32_16x16x32_bf16 v[40:43], v[170:173], v[212:215], v[40:43]
	v_mfma_f32_16x16x32_bf16 v[44:47], v[178:181], v[212:215], v[44:47]
	v_mfma_f32_16x16x32_bf16 v[56:59], v[170:173], v[230:233], v[56:59]
	v_mfma_f32_16x16x32_bf16 v[60:63], v[178:181], v[230:233], v[60:63]
	v_mfma_f32_16x16x32_bf16 v[8:11], v[174:177], v[190:193], v[8:11]
	v_mfma_f32_16x16x32_bf16 v[12:15], v[182:185], v[190:193], v[12:15]
	v_mfma_f32_16x16x32_bf16 v[24:27], v[174:177], v[206:209], v[24:27]
	v_mfma_f32_16x16x32_bf16 v[28:31], v[182:185], v[206:209], v[28:31]
	v_mfma_f32_16x16x32_bf16 v[40:43], v[174:177], v[226:229], v[40:43]
	v_mfma_f32_16x16x32_bf16 v[44:47], v[182:185], v[226:229], v[44:47]
	v_mfma_f32_16x16x32_bf16 v[56:59], v[174:177], v[234:237], v[56:59]
	v_mfma_f32_16x16x32_bf16 v[60:63], v[182:185], v[234:237], v[60:63]
	s_setprio 0
	s_barrier
	s_add_i32 s40, s70, s12
	v_lshl_add_u64 v[144:145], s[48:49], 0, v[96:97]
	s_mov_b32 m0, s40
	ds_read_b128 v[186:189], v150 offset:16384
	ds_read_b128 v[190:193], v150 offset:17408
	ds_read_b128 v[202:205], v150 offset:18432
	ds_read_b128 v[206:209], v150 offset:19456
	ds_read_b128 v[212:215], v150 offset:20480
	ds_read_b128 v[226:229], v150 offset:21504
	ds_read_b128 v[230:233], v150 offset:22528
	ds_read_b128 v[234:237], v150 offset:23552
	global_load_lds_dwordx4 v[144:145], off
	s_add_i32 m0, s40, 0x2000
	s_add_u32 s40, s48, 0x160000
	v_lshl_add_u64 v[196:197], s[48:49], 0, v[134:135]
	s_addc_u32 s41, s49, 0
	s_add_i32 s70, s71, s12
	global_load_lds_dwordx4 v[196:197], off
	v_lshl_add_u64 v[198:199], s[40:41], 0, v[96:97]
	s_mov_b32 m0, s70
	v_lshl_add_u64 v[216:217], s[50:51], 0, v[132:133]
	global_load_lds_dwordx4 v[198:199], off
	v_lshl_add_u64 v[198:199], s[40:41], 0, v[134:135]
	s_add_i32 m0, s70, 0x2000
	s_nop 0
	global_load_lds_dwordx4 v[198:199], off
	v_lshl_add_u64 v[198:199], s[50:51], 0, v[130:131]
	s_mov_b32 m0, s13
	s_nop 0
	global_load_lds_dwordx4 v[198:199], off
	s_mov_b32 m0, s52
	s_nop 0
	global_load_lds_dwordx4 v[216:217], off
	s_waitcnt vmcnt(8)
	s_waitcnt lgkmcnt(0)
	s_setprio 1
	s_barrier
; #define PG8_STAGE(bufoff, gbase, voff) do { _Pragma("unroll") for (int _i = 0; _i < 2; ++_i) \
;         __builtin_amdgcn_global_load_lds((const unsigned*)((const char*)(gbase) + (voff)[_i]), (PG8_LAS unsigned*)(lds + (bufoff) + ldsw + _i * 8192), 16, 0, 0); } while (0)
; #define PG8_LDA(dst, b, h) do { _Pragma("unroll") for (int m = 0; m < 4; ++m) _Pragma("unroll") for (int k = 0; k < 2; ++k) dst[m][k] = *(const PG8_LAS bf16x8*)(lds + PG8_SA(b, h) + aoff + m * 2048 + k * 1024); } while (0)
; #define PG8_LDB(dst, b, h) do { _Pragma("unroll") for (int n = 0; n < 2; ++n) _Pragma("unroll") for (int k = 0; k < 2; ++k) dst[n][k] = *(const PG8_LAS bf16x8*)(lds + PG8_SB(b, h) + boff + n * 2048 + k * 1024); } while (0)
; #define PG8_MMA(ai, bj, At, Bt) do { __builtin_amdgcn_s_setprio(1); _Pragma("unroll") for (int m = 0; m < 4; ++m) _Pragma("unroll") for (int n = 0; n < 2; ++n) _Pragma("unroll") for (int k = 0; k < 2; ++k) \
;         acc[ai][bj][m][n] = __builtin_amdgcn_mfma_f32_16x16x32_bf16(Bt[n][k], At[m][k], acc[ai][bj][m][n], 0, 0, 0); __builtin_amdgcn_s_setprio(0); } while (0)
; #define PG8_WAIT_V(n) asm volatile("s_waitcnt vmcnt(" #n ")" ::: "memory")
; #define PG8_WAIT_L(n) asm volatile("s_waitcnt lgkmcnt(" #n ")" ::: "memory")
; #define PG8_BAR __builtin_amdgcn_s_barrier()
; #define PG8_SCHED __builtin_amdgcn_sched_barrier(0)
; template <class Epi, class Sched, bool ALIGN_EPI, bool SP2, int KK, int LDA, int APN>
; __device__ __forceinline__ void gemm_phase(PG8_LAS unsigned char* lds, const Gemm g, const Sched& S, const Epi& E, const int wid) {
;     ...
;             PG8_WAIT_V(8); PG8_WAIT_L(0); PG8_BAR; PG8_MMA(1, 0, At, B0); PG8_MMA(1, 1, At, B1); PG8_BAR; PG8_SCHED;
;             PG8_LDB(B0, 1, 0); PG8_LDB(B1, 1, 1); PG8_SCHED; PG8_LDA(At, 1, 0); PG8_STAGE(PG8_SA(0, 1), a2 + hstepA, voffA);
;             PG8_WAIT_V(8); PG8_WAIT_L(0); PG8_BAR; PG8_MMA(0, 0, At, B0); PG8_MMA(0, 1, At, B1); PG8_BAR; PG8_SCHED;
	v_mfma_f32_16x16x32_bf16 v[64:67], v[154:157], v[186:189], v[64:67]
	v_mfma_f32_16x16x32_bf16 v[68:71], v[162:165], v[186:189], v[68:71]
	v_mfma_f32_16x16x32_bf16 v[80:83], v[154:157], v[202:205], v[80:83]
	v_mfma_f32_16x16x32_bf16 v[84:87], v[162:165], v[202:205], v[84:87]
	v_mfma_f32_16x16x32_bf16 v[98:101], v[154:157], v[212:215], v[98:101]
	v_mfma_f32_16x16x32_bf16 v[102:105], v[162:165], v[212:215], v[102:105]
	v_mfma_f32_16x16x32_bf16 v[114:117], v[154:157], v[230:233], v[114:117]
	v_mfma_f32_16x16x32_bf16 v[118:121], v[162:165], v[230:233], v[118:121]
	v_mfma_f32_16x16x32_bf16 v[64:67], v[158:161], v[190:193], v[64:67]
	v_mfma_f32_16x16x32_bf16 v[68:71], v[166:169], v[190:193], v[68:71]
	v_mfma_f32_16x16x32_bf16 v[80:83], v[158:161], v[206:209], v[80:83]
	v_mfma_f32_16x16x32_bf16 v[84:87], v[166:169], v[206:209], v[84:87]
	v_mfma_f32_16x16x32_bf16 v[98:101], v[158:161], v[226:229], v[98:101]
	v_mfma_f32_16x16x32_bf16 v[102:105], v[166:169], v[226:229], v[102:105]
	v_mfma_f32_16x16x32_bf16 v[114:117], v[158:161], v[234:237], v[114:117]
	v_mfma_f32_16x16x32_bf16 v[118:121], v[166:169], v[234:237], v[118:121]
	v_mfma_f32_16x16x32_bf16 v[72:75], v[170:173], v[186:189], v[72:75]
	v_mfma_f32_16x16x32_bf16 v[76:79], v[178:181], v[186:189], v[76:79]
	v_mfma_f32_16x16x32_bf16 v[88:91], v[170:173], v[202:205], v[88:91]
	v_mfma_f32_16x16x32_bf16 v[92:95], v[178:181], v[202:205], v[92:95]
	v_mfma_f32_16x16x32_bf16 v[106:109], v[170:173], v[212:215], v[106:109]
	v_mfma_f32_16x16x32_bf16 v[110:113], v[178:181], v[212:215], v[110:113]
	v_mfma_f32_16x16x32_bf16 v[122:125], v[170:173], v[230:233], v[122:125]
	v_mfma_f32_16x16x32_bf16 v[126:129], v[178:181], v[230:233], v[126:129]
	v_mfma_f32_16x16x32_bf16 v[72:75], v[174:177], v[190:193], v[72:75]
	v_mfma_f32_16x16x32_bf16 v[76:79], v[182:185], v[190:193], v[76:79]
	v_mfma_f32_16x16x32_bf16 v[88:91], v[174:177], v[206:209], v[88:91]
	v_mfma_f32_16x16x32_bf16 v[92:95], v[182:185], v[206:209], v[92:95]
	v_mfma_f32_16x16x32_bf16 v[106:109], v[174:177], v[226:229], v[106:109]
	v_mfma_f32_16x16x32_bf16 v[110:113], v[182:185], v[226:229], v[110:113]
	v_mfma_f32_16x16x32_bf16 v[122:125], v[174:177], v[234:237], v[122:125]
	v_mfma_f32_16x16x32_bf16 v[126:129], v[182:185], v[234:237], v[126:129]
	s_setprio 0
	s_barrier
	s_add_i32 s70, 0, 0x18000
	v_add_u32_e32 v153, s70, v148
	s_add_i32 s71, 0, 0x1c000
	ds_read_b128 v[154:157], v153
	ds_read_b128 v[158:161], v153 offset:1024
	ds_read_b128 v[162:165], v153 offset:2048
	ds_read_b128 v[166:169], v153 offset:3072
	v_add_u32_e32 v153, s71, v148
	ds_read_b128 v[170:173], v153
	ds_read_b128 v[174:177], v153 offset:1024
	ds_read_b128 v[178:181], v153 offset:2048
	ds_read_b128 v[182:185], v153 offset:3072
	s_add_u32 s40, s50, 0x160000
	s_addc_u32 s41, s51, 0
	s_mov_b32 m0, s53
	v_lshl_add_u64 v[238:239], s[40:41], 0, v[130:131]
	ds_read_b128 v[186:189], v150 offset:32768
	ds_read_b128 v[190:193], v150 offset:33792
	ds_read_b128 v[202:205], v150 offset:34816
	ds_read_b128 v[206:209], v150 offset:35840
	ds_read_b128 v[212:215], v150 offset:36864
	ds_read_b128 v[226:229], v150 offset:37888
	ds_read_b128 v[230:233], v150 offset:38912
	ds_read_b128 v[234:237], v150 offset:39936
	global_load_lds_dwordx4 v[238:239], off
	v_lshl_add_u64 v[238:239], s[40:41], 0, v[132:133]
	s_mov_b32 m0, s54
	s_nop 0
	global_load_lds_dwordx4 v[238:239], off
	s_waitcnt vmcnt(8)
	s_waitcnt lgkmcnt(0)
	s_setprio 1
	s_barrier
	v_mfma_f32_16x16x32_bf16 v[0:3], v[154:157], v[186:189], v[0:3]
	v_mfma_f32_16x16x32_bf16 v[4:7], v[162:165], v[186:189], v[4:7]
	v_mfma_f32_16x16x32_bf16 v[16:19], v[154:157], v[202:205], v[16:19]
	v_mfma_f32_16x16x32_bf16 v[20:23], v[162:165], v[202:205], v[20:23]
	v_mfma_f32_16x16x32_bf16 v[32:35], v[154:157], v[212:215], v[32:35]
	v_mfma_f32_16x16x32_bf16 v[36:39], v[162:165], v[212:215], v[36:39]
	v_mfma_f32_16x16x32_bf16 v[48:51], v[154:157], v[230:233], v[48:51]
	v_mfma_f32_16x16x32_bf16 v[52:55], v[162:165], v[230:233], v[52:55]
	v_mfma_f32_16x16x32_bf16 v[0:3], v[158:161], v[190:193], v[0:3]
	v_mfma_f32_16x16x32_bf16 v[4:7], v[166:169], v[190:193], v[4:7]
	v_mfma_f32_16x16x32_bf16 v[16:19], v[158:161], v[206:209], v[16:19]
	v_mfma_f32_16x16x32_bf16 v[20:23], v[166:169], v[206:209], v[20:23]
	v_mfma_f32_16x16x32_bf16 v[32:35], v[158:161], v[226:229], v[32:35]
	v_mfma_f32_16x16x32_bf16 v[36:39], v[166:169], v[226:229], v[36:39]
	v_mfma_f32_16x16x32_bf16 v[48:51], v[158:161], v[234:237], v[48:51]
	v_mfma_f32_16x16x32_bf16 v[52:55], v[166:169], v[234:237], v[52:55]
	v_mfma_f32_16x16x32_bf16 v[8:11], v[170:173], v[186:189], v[8:11]
	v_mfma_f32_16x16x32_bf16 v[12:15], v[178:181], v[186:189], v[12:15]
	v_mfma_f32_16x16x32_bf16 v[24:27], v[170:173], v[202:205], v[24:27]
	v_mfma_f32_16x16x32_bf16 v[28:31], v[178:181], v[202:205], v[28:31]
	v_mfma_f32_16x16x32_bf16 v[40:43], v[170:173], v[212:215], v[40:43]
	v_mfma_f32_16x16x32_bf16 v[44:47], v[178:181], v[212:215], v[44:47]
	v_mfma_f32_16x16x32_bf16 v[56:59], v[170:173], v[230:233], v[56:59]
	v_mfma_f32_16x16x32_bf16 v[60:63], v[178:181], v[230:233], v[60:63]
	v_mfma_f32_16x16x32_bf16 v[8:11], v[174:177], v[190:193], v[8:11]
	v_mfma_f32_16x16x32_bf16 v[12:15], v[182:185], v[190:193], v[12:15]
	v_mfma_f32_16x16x32_bf16 v[24:27], v[174:177], v[206:209], v[24:27]
	v_mfma_f32_16x16x32_bf16 v[28:31], v[182:185], v[206:209], v[28:31]
	v_mfma_f32_16x16x32_bf16 v[40:43], v[174:177], v[226:229], v[40:43]
	v_mfma_f32_16x16x32_bf16 v[44:47], v[182:185], v[226:229], v[44:47]
	v_mfma_f32_16x16x32_bf16 v[56:59], v[174:177], v[234:237], v[56:59]
	v_mfma_f32_16x16x32_bf16 v[60:63], v[182:185], v[234:237], v[60:63]
	s_setprio 0
	s_barrier
; #define PG8_STAGE(bufoff, gbase, voff) do { _Pragma("unroll") for (int _i = 0; _i < 2; ++_i) \
;         __builtin_amdgcn_global_load_lds((const unsigned*)((const char*)(gbase) + (voff)[_i]), (PG8_LAS unsigned*)(lds + (bufoff) + ldsw + _i * 8192), 16, 0, 0); } while (0)
; #define PG8_LDA(dst, b, h) do { _Pragma("unroll") for (int m = 0; m < 4; ++m) _Pragma("unroll") for (int k = 0; k < 2; ++k) dst[m][k] = *(const PG8_LAS bf16x8*)(lds + PG8_SA(b, h) + aoff + m * 2048 + k * 1024); } while (0)
; #define PG8_MMA(ai, bj, At, Bt) do { __builtin_amdgcn_s_setprio(1); _Pragma("unroll") for (int m = 0; m < 4; ++m) _Pragma("unroll") for (int n = 0; n < 2; ++n) _Pragma("unroll") for (int k = 0; k < 2; ++k) \
;         acc[ai][bj][m][n] = __builtin_amdgcn_mfma_f32_16x16x32_bf16(Bt[n][k], At[m][k], acc[ai][bj][m][n], 0, 0, 0); __builtin_amdgcn_s_setprio(0); } while (0)
; #define PG8_WAIT_V(n) asm volatile("s_waitcnt vmcnt(" #n ")" ::: "memory")
; #define PG8_WAIT_L(n) asm volatile("s_waitcnt lgkmcnt(" #n ")" ::: "memory")
; #define PG8_BAR __builtin_amdgcn_s_barrier()
; #define PG8_SCHED __builtin_amdgcn_sched_barrier(0)
; template <class Epi, class Sched, bool ALIGN_EPI, bool SP2, int KK, int LDA, int APN>
; __device__ __forceinline__ void gemm_phase(PG8_LAS unsigned char* lds, const Gemm g, const Sched& S, const Epi& E, const int wid) {
;     ...
;         for (int t = 0; t < nt; t += 2) {
;             const bool last = (t == nt - 2);
;             const char* a1 = cA + (size_t)(t + 1) * kstep;
;             const char* a2 = last ? nA : cA + (size_t)(t + 2) * kstep; const char* b2 = last ? nB : cB + (size_t)(t + 2) * kstep;
;             const char* a3 = a2 + kstep; const char* b3 = b2 + kstep;
;     ...
;             PG8_LDA(At, 1, 1); PG8_STAGE(PG8_SB(1, 0), b3, voffB); PG8_STAGE(PG8_SB(1, 1), b3 + hstep, voffB); PG8_STAGE(PG8_SA(1, 0), a3, voffA);
;             PG8_WAIT_V(8); PG8_WAIT_L(0); PG8_BAR; PG8_MMA(1, 0, At, B0); PG8_MMA(1, 1, At, B1); PG8_BAR; PG8_SCHED;
	s_add_i32 s40, s70, s12
	v_lshl_add_u64 v[144:145], v[144:145], 0, s[22:23]
	s_mov_b32 m0, s40
	ds_read_b128 v[186:189], v150 offset:49152
	ds_read_b128 v[190:193], v150 offset:50176
	ds_read_b128 v[202:205], v150 offset:51200
	ds_read_b128 v[206:209], v150 offset:52224
	ds_read_b128 v[212:215], v150 offset:53248
	ds_read_b128 v[226:229], v150 offset:54272
	ds_read_b128 v[230:233], v150 offset:55296
	ds_read_b128 v[234:237], v150 offset:56320
	global_load_lds_dwordx4 v[144:145], off
	s_add_i32 m0, s40, 0x2000
	s_add_u32 s40, s48, 0x160080
	v_lshl_add_u64 v[144:145], v[196:197], 0, s[22:23]
	s_addc_u32 s41, s49, 0
	s_add_i32 s48, s71, s12
	global_load_lds_dwordx4 v[144:145], off
	v_lshl_add_u64 v[144:145], s[40:41], 0, v[96:97]
	s_mov_b32 m0, s48
	s_nop 0
	global_load_lds_dwordx4 v[144:145], off
	v_lshl_add_u64 v[144:145], s[40:41], 0, v[134:135]
	s_add_i32 m0, s48, 0x2000
	s_nop 0
	global_load_lds_dwordx4 v[144:145], off
	v_lshl_add_u64 v[144:145], v[198:199], 0, s[22:23]
	s_mov_b32 m0, s57
	s_nop 0
	global_load_lds_dwordx4 v[144:145], off
	v_lshl_add_u64 v[144:145], v[216:217], 0, s[22:23]
	s_mov_b32 m0, s58
	s_nop 0
	global_load_lds_dwordx4 v[144:145], off
	s_waitcnt vmcnt(8)
	s_waitcnt lgkmcnt(0)
	s_setprio 1
	s_barrier
	v_mfma_f32_16x16x32_bf16 v[64:67], v[154:157], v[186:189], v[64:67]
	v_mfma_f32_16x16x32_bf16 v[68:71], v[162:165], v[186:189], v[68:71]
	v_mfma_f32_16x16x32_bf16 v[80:83], v[154:157], v[202:205], v[80:83]
	v_mfma_f32_16x16x32_bf16 v[84:87], v[162:165], v[202:205], v[84:87]
	v_mfma_f32_16x16x32_bf16 v[98:101], v[154:157], v[212:215], v[98:101]
	v_mfma_f32_16x16x32_bf16 v[102:105], v[162:165], v[212:215], v[102:105]
	v_mfma_f32_16x16x32_bf16 v[114:117], v[154:157], v[230:233], v[114:117]
	v_mfma_f32_16x16x32_bf16 v[118:121], v[162:165], v[230:233], v[118:121]
	v_mfma_f32_16x16x32_bf16 v[64:67], v[158:161], v[190:193], v[64:67]
	v_mfma_f32_16x16x32_bf16 v[68:71], v[166:169], v[190:193], v[68:71]
	v_mfma_f32_16x16x32_bf16 v[80:83], v[158:161], v[206:209], v[80:83]
	v_mfma_f32_16x16x32_bf16 v[84:87], v[166:169], v[206:209], v[84:87]
	v_mfma_f32_16x16x32_bf16 v[98:101], v[158:161], v[226:229], v[98:101]
	v_mfma_f32_16x16x32_bf16 v[102:105], v[166:169], v[226:229], v[102:105]
	v_mfma_f32_16x16x32_bf16 v[114:117], v[158:161], v[234:237], v[114:117]
	v_mfma_f32_16x16x32_bf16 v[118:121], v[166:169], v[234:237], v[118:121]
	v_mfma_f32_16x16x32_bf16 v[72:75], v[170:173], v[186:189], v[72:75]
	v_mfma_f32_16x16x32_bf16 v[76:79], v[178:181], v[186:189], v[76:79]
	v_mfma_f32_16x16x32_bf16 v[88:91], v[170:173], v[202:205], v[88:91]
	v_mfma_f32_16x16x32_bf16 v[92:95], v[178:181], v[202:205], v[92:95]
	v_mfma_f32_16x16x32_bf16 v[106:109], v[170:173], v[212:215], v[106:109]
	v_mfma_f32_16x16x32_bf16 v[110:113], v[178:181], v[212:215], v[110:113]
	v_mfma_f32_16x16x32_bf16 v[122:125], v[170:173], v[230:233], v[122:125]
	v_mfma_f32_16x16x32_bf16 v[126:129], v[178:181], v[230:233], v[126:129]
	v_mfma_f32_16x16x32_bf16 v[72:75], v[174:177], v[190:193], v[72:75]
	v_mfma_f32_16x16x32_bf16 v[76:79], v[182:185], v[190:193], v[76:79]
	v_mfma_f32_16x16x32_bf16 v[88:91], v[174:177], v[206:209], v[88:91]
	v_mfma_f32_16x16x32_bf16 v[92:95], v[182:185], v[206:209], v[92:95]
	v_mfma_f32_16x16x32_bf16 v[106:109], v[174:177], v[226:229], v[106:109]
	v_mfma_f32_16x16x32_bf16 v[110:113], v[182:185], v[226:229], v[110:113]
	v_mfma_f32_16x16x32_bf16 v[122:125], v[174:177], v[234:237], v[122:125]
	v_mfma_f32_16x16x32_bf16 v[126:129], v[182:185], v[234:237], v[126:129]
	s_setprio 0
	s_barrier
	s_add_i32 s17, s17, 2
	s_add_u32 s42, s42, 0x100
	s_addc_u32 s43, s43, 0
	s_cmpk_gt_u32 s17, 0x55
	s_cbranch_scc0 .LBB0_309
	s_and_b64 vcc, exec, s[46:47]
	s_cbranch_vccz .LBB0_312
	s_barrier

; #define PG8_STAGE(bufoff, gbase, voff) do { _Pragma("unroll") for (int _i = 0; _i < 2; ++_i) \
;         __builtin_amdgcn_global_load_lds((const unsigned*)((const char*)(gbase) + (voff)[_i]), (PG8_LAS unsigned*)(lds + (bufoff) + ldsw + _i * 8192), 16, 0, 0); } while (0)
; #define PG8_LDA(dst, b, h) do { _Pragma("unroll") for (int m = 0; m < 4; ++m) _Pragma("unroll") for (int k = 0; k < 2; ++k) dst[m][k] = *(const PG8_LAS bf16x8*)(lds + PG8_SA(b, h) + aoff + m * 2048 + k * 1024); } while (0)
; #define PG8_LDB(dst, b, h) do { _Pragma("unroll") for (int n = 0; n < 2; ++n) _Pragma("unroll") for (int k = 0; k < 2; ++k) dst[n][k] = *(const PG8_LAS bf16x8*)(lds + PG8_SB(b, h) + boff + n * 2048 + k * 1024); } while (0)
; #define PG8_MMA(ai, bj, At, Bt) do { __builtin_amdgcn_s_setprio(1); _Pragma("unroll") for (int m = 0; m < 4; ++m) _Pragma("unroll") for (int n = 0; n < 2; ++n) _Pragma("unroll") for (int k = 0; k < 2; ++k) \
;         acc[ai][bj][m][n] = __builtin_amdgcn_mfma_f32_16x16x32_bf16(Bt[n][k], At[m][k], acc[ai][bj][m][n], 0, 0, 0); __builtin_amdgcn_s_setprio(0); } while (0)
; #define PG8_WAIT_V(n) asm volatile("s_waitcnt vmcnt(" #n ")" ::: "memory")
; #define PG8_WAIT_L(n) asm volatile("s_waitcnt lgkmcnt(" #n ")" ::: "memory")
; template <class Epi, class Sched, bool ALIGN_EPI, bool SP2, int KK, int LDA, int APN>
; __device__ __forceinline__ void gemm_phase(PG8_LAS unsigned char* lds, const Gemm g, const Sched& S, const Epi& E, const int wid) {
;     ...
;             const bool last = (t == nt - 2);
;             const char* a1 = cA + (size_t)(t + 1) * kstep;
;             const char* a2 = last ? nA : cA + (size_t)(t + 2) * kstep; const char* b2 = last ? nB : cB + (size_t)(t + 2) * kstep;
;             const char* a3 = a2 + kstep; const char* b3 = b2 + kstep;
;             if (last && has_next) S.a_ready(nxt);
;             if constexpr (SP2) {
;             PG8_LDB(B0, 0, 0); PG8_LDB(B1, 0, 1); PG8_SCHED; PG8_LDA(At, 0, 0); PG8_STAGE(PG8_SA(1, 1), a1 + hstepA, voffA);
;             PG8_WAIT_V(8); PG8_WAIT_L(0); PG8_BAR; PG8_MMA(0, 0, At, B0); PG8_MMA(0, 1, At, B1); PG8_BAR; PG8_SCHED;
;             PG8_LDA(At, 0, 1); PG8_STAGE(PG8_SB(0, 0), b2, voffB); PG8_STAGE(PG8_SB(0, 1), b2 + hstep, voffB); PG8_STAGE(PG8_SA(0, 0), a2, voffA);
;             PG8_WAIT_V(8); PG8_WAIT_L(0); PG8_BAR; PG8_MMA(1, 0, At, B0); PG8_MMA(1, 1, At, B1); PG8_BAR; PG8_SCHED;
.LBB0_406:
	s_add_u32 s12, s16, 0xfff80080
	s_addc_u32 s13, s17, -1
	s_add_i32 s15, 0, 0x10000
	s_cmp_eq_u32 s11, 28
	s_cselect_b32 s27, s3, s13
	s_cselect_b32 s26, s6, s12
	s_cselect_b32 s19, s7, s10
	s_cselect_b32 s18, s8, s9
	s_add_i32 s55, 0, 0x14000
	v_add_u32_e32 v142, s15, v169
	v_add_u32_e32 v166, s55, v169
	ds_read_b128 v[130:133], v142
	ds_read_b128 v[134:137], v142 offset:1024
	ds_read_b128 v[138:141], v142 offset:2048
	ds_read_b128 v[142:145], v142 offset:3072
	ds_read_b128 v[162:165], v166
	ds_read_b128 v[176:179], v166 offset:1024
	ds_read_b128 v[180:183], v166 offset:2048
	ds_read_b128 v[184:187], v166 offset:3072
	v_lshl_add_u64 v[166:167], s[16:17], 0, v[160:161]
	s_add_i32 m0, s69, 0xc000
	ds_read_b128 v[188:191], v172
	ds_read_b128 v[202:205], v172 offset:1024
	ds_read_b128 v[206:209], v172 offset:2048
	ds_read_b128 v[212:215], v172 offset:3072
	ds_read_b128 v[226:229], v172 offset:4096
	ds_read_b128 v[230:233], v172 offset:5120
	ds_read_b128 v[234:237], v172 offset:6144
	ds_read_b128 v[238:241], v172 offset:7168
	global_load_lds_dwordx4 v[166:167], off
	v_lshl_add_u64 v[166:167], s[16:17], 0, v[158:159]
	s_add_i32 m0, s69, 0xe000
	s_nop 0
	global_load_lds_dwordx4 v[166:167], off
	s_waitcnt vmcnt(8)
	s_waitcnt lgkmcnt(0)
	s_setprio 1
	s_barrier
	v_mfma_f32_16x16x32_bf16 v[126:129], v[130:133], v[188:191], v[126:129]
	v_mfma_f32_16x16x32_bf16 v[122:125], v[138:141], v[188:191], v[122:125]
	v_mfma_f32_16x16x32_bf16 v[110:113], v[130:133], v[206:209], v[110:113]
	v_mfma_f32_16x16x32_bf16 v[106:109], v[138:141], v[206:209], v[106:109]
	v_mfma_f32_16x16x32_bf16 v[92:95], v[130:133], v[226:229], v[92:95]
	v_mfma_f32_16x16x32_bf16 v[88:91], v[138:141], v[226:229], v[88:91]
	v_mfma_f32_16x16x32_bf16 v[76:79], v[130:133], v[234:237], v[76:79]
	v_mfma_f32_16x16x32_bf16 v[72:75], v[138:141], v[234:237], v[72:75]
	v_mfma_f32_16x16x32_bf16 v[126:129], v[134:137], v[202:205], v[126:129]
	v_mfma_f32_16x16x32_bf16 v[122:125], v[142:145], v[202:205], v[122:125]
	v_mfma_f32_16x16x32_bf16 v[110:113], v[134:137], v[212:215], v[110:113]
	v_mfma_f32_16x16x32_bf16 v[106:109], v[142:145], v[212:215], v[106:109]
	v_mfma_f32_16x16x32_bf16 v[92:95], v[134:137], v[230:233], v[92:95]
	v_mfma_f32_16x16x32_bf16 v[88:91], v[142:145], v[230:233], v[88:91]
	v_mfma_f32_16x16x32_bf16 v[76:79], v[134:137], v[238:241], v[76:79]
	v_mfma_f32_16x16x32_bf16 v[72:75], v[142:145], v[238:241], v[72:75]
	v_mfma_f32_16x16x32_bf16 v[118:121], v[162:165], v[188:191], v[118:121]
	v_mfma_f32_16x16x32_bf16 v[114:117], v[180:183], v[188:191], v[114:117]
	v_mfma_f32_16x16x32_bf16 v[102:105], v[162:165], v[206:209], v[102:105]
	v_mfma_f32_16x16x32_bf16 v[98:101], v[180:183], v[206:209], v[98:101]
	v_mfma_f32_16x16x32_bf16 v[84:87], v[162:165], v[226:229], v[84:87]
	v_mfma_f32_16x16x32_bf16 v[80:83], v[180:183], v[226:229], v[80:83]
	v_mfma_f32_16x16x32_bf16 v[68:71], v[162:165], v[234:237], v[68:71]
	v_mfma_f32_16x16x32_bf16 v[64:67], v[180:183], v[234:237], v[64:67]
	v_mfma_f32_16x16x32_bf16 v[118:121], v[176:179], v[202:205], v[118:121]
	v_mfma_f32_16x16x32_bf16 v[114:117], v[184:187], v[202:205], v[114:117]
	v_mfma_f32_16x16x32_bf16 v[102:105], v[176:179], v[212:215], v[102:105]
	v_mfma_f32_16x16x32_bf16 v[98:101], v[184:187], v[212:215], v[98:101]
	v_mfma_f32_16x16x32_bf16 v[84:87], v[176:179], v[230:233], v[84:87]
	v_mfma_f32_16x16x32_bf16 v[80:83], v[184:187], v[230:233], v[80:83]
	v_mfma_f32_16x16x32_bf16 v[68:71], v[176:179], v[238:241], v[68:71]
	v_mfma_f32_16x16x32_bf16 v[64:67], v[184:187], v[238:241], v[64:67]
	s_setprio 0
	s_barrier
	s_add_i32 s12, s15, s68
	v_lshl_add_u64 v[166:167], s[18:19], 0, v[146:147]
	s_mov_b32 m0, s12
	ds_read_b128 v[188:191], v172 offset:16384
	ds_read_b128 v[202:205], v172 offset:17408
	ds_read_b128 v[206:209], v172 offset:18432
	ds_read_b128 v[212:215], v172 offset:19456
	ds_read_b128 v[226:229], v172 offset:20480
	ds_read_b128 v[230:233], v172 offset:21504
	ds_read_b128 v[234:237], v172 offset:22528
	ds_read_b128 v[238:241], v172 offset:23552
	global_load_lds_dwordx4 v[166:167], off
	s_add_i32 m0, s12, 0x2000
	s_add_u32 s12, s18, 0x80000
	v_lshl_add_u64 v[192:193], s[18:19], 0, v[148:149]
	s_addc_u32 s13, s19, 0
	s_add_i32 s15, s55, s68
	global_load_lds_dwordx4 v[192:193], off
	v_lshl_add_u64 v[196:197], s[12:13], 0, v[146:147]
	s_mov_b32 m0, s15
	v_lshl_add_u64 v[198:199], s[26:27], 0, v[148:149]
	global_load_lds_dwordx4 v[196:197], off
	v_lshl_add_u64 v[196:197], s[12:13], 0, v[148:149]
	s_add_i32 m0, s15, 0x2000
	s_nop 0
	global_load_lds_dwordx4 v[196:197], off
	v_lshl_add_u64 v[196:197], s[26:27], 0, v[146:147]
	s_mov_b32 m0, s69
	s_nop 0
	global_load_lds_dwordx4 v[196:197], off
	s_mov_b32 m0, s70
	s_nop 0
	global_load_lds_dwordx4 v[198:199], off
	s_waitcnt vmcnt(8)
	s_waitcnt lgkmcnt(0)
	s_setprio 1
	s_barrier
; #define PG8_STAGE(bufoff, gbase, voff) do { _Pragma("unroll") for (int _i = 0; _i < 2; ++_i) \
;         __builtin_amdgcn_global_load_lds((const unsigned*)((const char*)(gbase) + (voff)[_i]), (PG8_LAS unsigned*)(lds + (bufoff) + ldsw + _i * 8192), 16, 0, 0); } while (0)
; #define PG8_LDA(dst, b, h) do { _Pragma("unroll") for (int m = 0; m < 4; ++m) _Pragma("unroll") for (int k = 0; k < 2; ++k) dst[m][k] = *(const PG8_LAS bf16x8*)(lds + PG8_SA(b, h) + aoff + m * 2048 + k * 1024); } while (0)
; #define PG8_LDB(dst, b, h) do { _Pragma("unroll") for (int n = 0; n < 2; ++n) _Pragma("unroll") for (int k = 0; k < 2; ++k) dst[n][k] = *(const PG8_LAS bf16x8*)(lds + PG8_SB(b, h) + boff + n * 2048 + k * 1024); } while (0)
; #define PG8_MMA(ai, bj, At, Bt) do { __builtin_amdgcn_s_setprio(1); _Pragma("unroll") for (int m = 0; m < 4; ++m) _Pragma("unroll") for (int n = 0; n < 2; ++n) _Pragma("unroll") for (int k = 0; k < 2; ++k) \
;         acc[ai][bj][m][n] = __builtin_amdgcn_mfma_f32_16x16x32_bf16(Bt[n][k], At[m][k], acc[ai][bj][m][n], 0, 0, 0); __builtin_amdgcn_s_setprio(0); } while (0)
; #define PG8_WAIT_V(n) asm volatile("s_waitcnt vmcnt(" #n ")" ::: "memory")
; #define PG8_WAIT_L(n) asm volatile("s_waitcnt lgkmcnt(" #n ")" ::: "memory")
; #define PG8_BAR __builtin_amdgcn_s_barrier()
; #define PG8_SCHED __builtin_amdgcn_sched_barrier(0)
; template <class Epi, class Sched, bool ALIGN_EPI, bool SP2, int KK, int LDA, int APN>
; __device__ __forceinline__ void gemm_phase(PG8_LAS unsigned char* lds, const Gemm g, const Sched& S, const Epi& E, const int wid) {
;     ...
;             PG8_WAIT_V(8); PG8_WAIT_L(0); PG8_BAR; PG8_MMA(1, 0, At, B0); PG8_MMA(1, 1, At, B1); PG8_BAR; PG8_SCHED;
;             PG8_LDB(B0, 1, 0); PG8_LDB(B1, 1, 1); PG8_SCHED; PG8_LDA(At, 1, 0); PG8_STAGE(PG8_SA(0, 1), a2 + hstepA, voffA);
;             PG8_WAIT_V(8); PG8_WAIT_L(0); PG8_BAR; PG8_MMA(0, 0, At, B0); PG8_MMA(0, 1, At, B1); PG8_BAR; PG8_SCHED;
	v_mfma_f32_16x16x32_bf16 v[60:63], v[130:133], v[188:191], v[60:63]
	v_mfma_f32_16x16x32_bf16 v[56:59], v[138:141], v[188:191], v[56:59]
	v_mfma_f32_16x16x32_bf16 v[44:47], v[130:133], v[206:209], v[44:47]
	v_mfma_f32_16x16x32_bf16 v[40:43], v[138:141], v[206:209], v[40:43]
	v_mfma_f32_16x16x32_bf16 v[28:31], v[130:133], v[226:229], v[28:31]
	v_mfma_f32_16x16x32_bf16 v[24:27], v[138:141], v[226:229], v[24:27]
	v_mfma_f32_16x16x32_bf16 v[12:15], v[130:133], v[234:237], v[12:15]
	v_mfma_f32_16x16x32_bf16 v[8:11], v[138:141], v[234:237], v[8:11]
	v_mfma_f32_16x16x32_bf16 v[60:63], v[134:137], v[202:205], v[60:63]
	v_mfma_f32_16x16x32_bf16 v[56:59], v[142:145], v[202:205], v[56:59]
	v_mfma_f32_16x16x32_bf16 v[44:47], v[134:137], v[212:215], v[44:47]
	v_mfma_f32_16x16x32_bf16 v[40:43], v[142:145], v[212:215], v[40:43]
	v_mfma_f32_16x16x32_bf16 v[28:31], v[134:137], v[230:233], v[28:31]
	v_mfma_f32_16x16x32_bf16 v[24:27], v[142:145], v[230:233], v[24:27]
	v_mfma_f32_16x16x32_bf16 v[12:15], v[134:137], v[238:241], v[12:15]
	v_mfma_f32_16x16x32_bf16 v[8:11], v[142:145], v[238:241], v[8:11]
	v_mfma_f32_16x16x32_bf16 v[52:55], v[162:165], v[188:191], v[52:55]
	v_mfma_f32_16x16x32_bf16 v[48:51], v[180:183], v[188:191], v[48:51]
	v_mfma_f32_16x16x32_bf16 v[36:39], v[162:165], v[206:209], v[36:39]
	v_mfma_f32_16x16x32_bf16 v[32:35], v[180:183], v[206:209], v[32:35]
	v_mfma_f32_16x16x32_bf16 v[20:23], v[162:165], v[226:229], v[20:23]
	v_mfma_f32_16x16x32_bf16 v[16:19], v[180:183], v[226:229], v[16:19]
	v_mfma_f32_16x16x32_bf16 v[4:7], v[162:165], v[234:237], v[4:7]
	v_mfma_f32_16x16x32_bf16 v[0:3], v[180:183], v[234:237], v[0:3]
	v_mfma_f32_16x16x32_bf16 v[52:55], v[176:179], v[202:205], v[52:55]
	v_mfma_f32_16x16x32_bf16 v[48:51], v[184:187], v[202:205], v[48:51]
	v_mfma_f32_16x16x32_bf16 v[36:39], v[176:179], v[212:215], v[36:39]
	v_mfma_f32_16x16x32_bf16 v[32:35], v[184:187], v[212:215], v[32:35]
	v_mfma_f32_16x16x32_bf16 v[20:23], v[176:179], v[230:233], v[20:23]
	v_mfma_f32_16x16x32_bf16 v[16:19], v[184:187], v[230:233], v[16:19]
	v_mfma_f32_16x16x32_bf16 v[4:7], v[176:179], v[238:241], v[4:7]
	v_mfma_f32_16x16x32_bf16 v[0:3], v[184:187], v[238:241], v[0:3]
	s_setprio 0
	s_barrier
	s_add_i32 s15, 0, 0x18000
	s_add_i32 s55, 0, 0x1c000
	v_add_u32_e32 v142, s15, v169
	v_add_u32_e32 v175, s55, v169
	ds_read_b128 v[130:133], v142
	ds_read_b128 v[134:137], v142 offset:1024
	ds_read_b128 v[138:141], v142 offset:2048
	ds_read_b128 v[142:145], v142 offset:3072
	ds_read_b128 v[162:165], v175
	ds_read_b128 v[176:179], v175 offset:1024
	ds_read_b128 v[180:183], v175 offset:2048
	ds_read_b128 v[184:187], v175 offset:3072
	s_add_u32 s12, s26, 0x80000
	s_addc_u32 s13, s27, 0
	s_mov_b32 m0, s71
	v_lshl_add_u64 v[216:217], s[12:13], 0, v[146:147]
	ds_read_b128 v[188:191], v172 offset:32768
	ds_read_b128 v[202:205], v172 offset:33792
	ds_read_b128 v[206:209], v172 offset:34816
	ds_read_b128 v[212:215], v172 offset:35840
	ds_read_b128 v[226:229], v172 offset:36864
	ds_read_b128 v[230:233], v172 offset:37888
	ds_read_b128 v[234:237], v172 offset:38912
	ds_read_b128 v[238:241], v172 offset:39936
	global_load_lds_dwordx4 v[216:217], off
	v_lshl_add_u64 v[216:217], s[12:13], 0, v[148:149]
	s_mov_b32 m0, s72
	s_nop 0
	global_load_lds_dwordx4 v[216:217], off
	s_waitcnt vmcnt(8)
	s_waitcnt lgkmcnt(0)
	s_setprio 1
	s_barrier
	v_mfma_f32_16x16x32_bf16 v[126:129], v[130:133], v[188:191], v[126:129]
	v_mfma_f32_16x16x32_bf16 v[122:125], v[138:141], v[188:191], v[122:125]
	v_mfma_f32_16x16x32_bf16 v[110:113], v[130:133], v[206:209], v[110:113]
	v_mfma_f32_16x16x32_bf16 v[106:109], v[138:141], v[206:209], v[106:109]
	v_mfma_f32_16x16x32_bf16 v[92:95], v[130:133], v[226:229], v[92:95]
	v_mfma_f32_16x16x32_bf16 v[88:91], v[138:141], v[226:229], v[88:91]
	v_mfma_f32_16x16x32_bf16 v[76:79], v[130:133], v[234:237], v[76:79]
	v_mfma_f32_16x16x32_bf16 v[72:75], v[138:141], v[234:237], v[72:75]
	v_mfma_f32_16x16x32_bf16 v[126:129], v[134:137], v[202:205], v[126:129]
	v_mfma_f32_16x16x32_bf16 v[122:125], v[142:145], v[202:205], v[122:125]
	v_mfma_f32_16x16x32_bf16 v[110:113], v[134:137], v[212:215], v[110:113]
	v_mfma_f32_16x16x32_bf16 v[106:109], v[142:145], v[212:215], v[106:109]
	v_mfma_f32_16x16x32_bf16 v[92:95], v[134:137], v[230:233], v[92:95]
	v_mfma_f32_16x16x32_bf16 v[88:91], v[142:145], v[230:233], v[88:91]
	v_mfma_f32_16x16x32_bf16 v[76:79], v[134:137], v[238:241], v[76:79]
	v_mfma_f32_16x16x32_bf16 v[72:75], v[142:145], v[238:241], v[72:75]
	v_mfma_f32_16x16x32_bf16 v[118:121], v[162:165], v[188:191], v[118:121]
	v_mfma_f32_16x16x32_bf16 v[114:117], v[180:183], v[188:191], v[114:117]
	v_mfma_f32_16x16x32_bf16 v[102:105], v[162:165], v[206:209], v[102:105]
	v_mfma_f32_16x16x32_bf16 v[98:101], v[180:183], v[206:209], v[98:101]
	v_mfma_f32_16x16x32_bf16 v[84:87], v[162:165], v[226:229], v[84:87]
	v_mfma_f32_16x16x32_bf16 v[80:83], v[180:183], v[226:229], v[80:83]
	v_mfma_f32_16x16x32_bf16 v[68:71], v[162:165], v[234:237], v[68:71]
	v_mfma_f32_16x16x32_bf16 v[64:67], v[180:183], v[234:237], v[64:67]
	v_mfma_f32_16x16x32_bf16 v[118:121], v[176:179], v[202:205], v[118:121]
	v_mfma_f32_16x16x32_bf16 v[114:117], v[184:187], v[202:205], v[114:117]
	v_mfma_f32_16x16x32_bf16 v[102:105], v[176:179], v[212:215], v[102:105]
	v_mfma_f32_16x16x32_bf16 v[98:101], v[184:187], v[212:215], v[98:101]
	v_mfma_f32_16x16x32_bf16 v[84:87], v[176:179], v[230:233], v[84:87]
	v_mfma_f32_16x16x32_bf16 v[80:83], v[184:187], v[230:233], v[80:83]
	v_mfma_f32_16x16x32_bf16 v[68:71], v[176:179], v[238:241], v[68:71]
	v_mfma_f32_16x16x32_bf16 v[64:67], v[184:187], v[238:241], v[64:67]
	s_setprio 0
	s_barrier
; #define PG8_STAGE(bufoff, gbase, voff) do { _Pragma("unroll") for (int _i = 0; _i < 2; ++_i) \
;         __builtin_amdgcn_global_load_lds((const unsigned*)((const char*)(gbase) + (voff)[_i]), (PG8_LAS unsigned*)(lds + (bufoff) + ldsw + _i * 8192), 16, 0, 0); } while (0)
; #define PG8_LDA(dst, b, h) do { _Pragma("unroll") for (int m = 0; m < 4; ++m) _Pragma("unroll") for (int k = 0; k < 2; ++k) dst[m][k] = *(const PG8_LAS bf16x8*)(lds + PG8_SA(b, h) + aoff + m * 2048 + k * 1024); } while (0)
; #define PG8_MMA(ai, bj, At, Bt) do { __builtin_amdgcn_s_setprio(1); _Pragma("unroll") for (int m = 0; m < 4; ++m) _Pragma("unroll") for (int n = 0; n < 2; ++n) _Pragma("unroll") for (int k = 0; k < 2; ++k) \
;         acc[ai][bj][m][n] = __builtin_amdgcn_mfma_f32_16x16x32_bf16(Bt[n][k], At[m][k], acc[ai][bj][m][n], 0, 0, 0); __builtin_amdgcn_s_setprio(0); } while (0)
; #define PG8_WAIT_V(n) asm volatile("s_waitcnt vmcnt(" #n ")" ::: "memory")
; #define PG8_WAIT_L(n) asm volatile("s_waitcnt lgkmcnt(" #n ")" ::: "memory")
; #define PG8_BAR __builtin_amdgcn_s_barrier()
; #define PG8_SCHED __builtin_amdgcn_sched_barrier(0)
; template <class Epi, class Sched, bool ALIGN_EPI, bool SP2, int KK, int LDA, int APN>
; __device__ __forceinline__ void gemm_phase(PG8_LAS unsigned char* lds, const Gemm g, const Sched& S, const Epi& E, const int wid) {
;     ...
;         for (int t = 0; t < nt; t += 2) {
;             const bool last = (t == nt - 2);
;             const char* a1 = cA + (size_t)(t + 1) * kstep;
;             const char* a2 = last ? nA : cA + (size_t)(t + 2) * kstep; const char* b2 = last ? nB : cB + (size_t)(t + 2) * kstep;
;             const char* a3 = a2 + kstep; const char* b3 = b2 + kstep;
;     ...
;             PG8_LDA(At, 1, 1); PG8_STAGE(PG8_SB(1, 0), b3, voffB); PG8_STAGE(PG8_SB(1, 1), b3 + hstep, voffB); PG8_STAGE(PG8_SA(1, 0), a3, voffA);
;             PG8_WAIT_V(8); PG8_WAIT_L(0); PG8_BAR; PG8_MMA(1, 0, At, B0); PG8_MMA(1, 1, At, B1); PG8_BAR; PG8_SCHED;
	s_add_i32 s12, s15, s68
	v_lshl_add_u64 v[166:167], v[166:167], 0, s[22:23]
	s_mov_b32 m0, s12
	ds_read_b128 v[188:191], v172 offset:49152
	ds_read_b128 v[202:205], v172 offset:50176
	ds_read_b128 v[206:209], v172 offset:51200
	ds_read_b128 v[212:215], v172 offset:52224
	ds_read_b128 v[226:229], v172 offset:53248
	ds_read_b128 v[230:233], v172 offset:54272
	ds_read_b128 v[234:237], v172 offset:55296
	ds_read_b128 v[238:241], v172 offset:56320
	global_load_lds_dwordx4 v[166:167], off
	s_add_i32 m0, s12, 0x2000
	s_add_u32 s12, s18, 0x80080
	v_lshl_add_u64 v[166:167], v[192:193], 0, s[22:23]
	s_addc_u32 s13, s19, 0
	s_add_i32 s15, s55, s68
	global_load_lds_dwordx4 v[166:167], off
	v_lshl_add_u64 v[166:167], s[12:13], 0, v[146:147]
	s_mov_b32 m0, s15
	s_nop 0
	global_load_lds_dwordx4 v[166:167], off
	v_lshl_add_u64 v[166:167], s[12:13], 0, v[148:149]
	s_add_i32 m0, s15, 0x2000
	s_nop 0
	global_load_lds_dwordx4 v[166:167], off
	v_lshl_add_u64 v[166:167], v[196:197], 0, s[22:23]
	s_mov_b32 m0, s73
	s_nop 0
	global_load_lds_dwordx4 v[166:167], off
	v_lshl_add_u64 v[166:167], v[198:199], 0, s[22:23]
	s_mov_b32 m0, s78
	s_nop 0
	global_load_lds_dwordx4 v[166:167], off
	s_waitcnt vmcnt(8)
	s_waitcnt lgkmcnt(0)
	s_setprio 1
	s_barrier
	v_mfma_f32_16x16x32_bf16 v[60:63], v[130:133], v[188:191], v[60:63]
	v_mfma_f32_16x16x32_bf16 v[56:59], v[138:141], v[188:191], v[56:59]
	v_mfma_f32_16x16x32_bf16 v[44:47], v[130:133], v[206:209], v[44:47]
	v_mfma_f32_16x16x32_bf16 v[40:43], v[138:141], v[206:209], v[40:43]
	v_mfma_f32_16x16x32_bf16 v[28:31], v[130:133], v[226:229], v[28:31]
	v_mfma_f32_16x16x32_bf16 v[24:27], v[138:141], v[226:229], v[24:27]
	v_mfma_f32_16x16x32_bf16 v[12:15], v[130:133], v[234:237], v[12:15]
	v_mfma_f32_16x16x32_bf16 v[8:11], v[138:141], v[234:237], v[8:11]
	v_mfma_f32_16x16x32_bf16 v[60:63], v[134:137], v[202:205], v[60:63]
	v_mfma_f32_16x16x32_bf16 v[56:59], v[142:145], v[202:205], v[56:59]
	v_mfma_f32_16x16x32_bf16 v[44:47], v[134:137], v[212:215], v[44:47]
	v_mfma_f32_16x16x32_bf16 v[40:43], v[142:145], v[212:215], v[40:43]
	v_mfma_f32_16x16x32_bf16 v[28:31], v[134:137], v[230:233], v[28:31]
	v_mfma_f32_16x16x32_bf16 v[24:27], v[142:145], v[230:233], v[24:27]
	v_mfma_f32_16x16x32_bf16 v[12:15], v[134:137], v[238:241], v[12:15]
	v_mfma_f32_16x16x32_bf16 v[8:11], v[142:145], v[238:241], v[8:11]
	v_mfma_f32_16x16x32_bf16 v[52:55], v[162:165], v[188:191], v[52:55]
	v_mfma_f32_16x16x32_bf16 v[48:51], v[180:183], v[188:191], v[48:51]
	v_mfma_f32_16x16x32_bf16 v[36:39], v[162:165], v[206:209], v[36:39]
	v_mfma_f32_16x16x32_bf16 v[32:35], v[180:183], v[206:209], v[32:35]
	v_mfma_f32_16x16x32_bf16 v[20:23], v[162:165], v[226:229], v[20:23]
	v_mfma_f32_16x16x32_bf16 v[16:19], v[180:183], v[226:229], v[16:19]
	v_mfma_f32_16x16x32_bf16 v[4:7], v[162:165], v[234:237], v[4:7]
	v_mfma_f32_16x16x32_bf16 v[0:3], v[180:183], v[234:237], v[0:3]
	v_mfma_f32_16x16x32_bf16 v[52:55], v[176:179], v[202:205], v[52:55]
	v_mfma_f32_16x16x32_bf16 v[48:51], v[184:187], v[202:205], v[48:51]
	v_mfma_f32_16x16x32_bf16 v[36:39], v[176:179], v[212:215], v[36:39]
	v_mfma_f32_16x16x32_bf16 v[32:35], v[184:187], v[212:215], v[32:35]
	v_mfma_f32_16x16x32_bf16 v[20:23], v[176:179], v[230:233], v[20:23]
	v_mfma_f32_16x16x32_bf16 v[16:19], v[184:187], v[230:233], v[16:19]
	v_mfma_f32_16x16x32_bf16 v[4:7], v[176:179], v[238:241], v[4:7]
	v_mfma_f32_16x16x32_bf16 v[0:3], v[184:187], v[238:241], v[0:3]
	s_setprio 0
	s_barrier
	s_add_i32 s11, s11, 2
	s_add_u32 s9, s9, 0x100
	s_addc_u32 s10, s10, 0
	s_add_u32 s16, s16, 0x100
	s_addc_u32 s17, s17, 0
	s_cmp_gt_u32 s11, 29
	s_cbranch_scc0 .LBB0_406
	s_and_b64 vcc, exec, s[50:51]
	s_cbranch_vccz .LBB0_409
	s_barrier

; #define PG8_STAGE(bufoff, gbase, voff) do { _Pragma("unroll") for (int _i = 0; _i < 2; ++_i) \
;         __builtin_amdgcn_global_load_lds((const unsigned*)((const char*)(gbase) + (voff)[_i]), (PG8_LAS unsigned*)(lds + (bufoff) + ldsw + _i * 8192), 16, 0, 0); } while (0)
; #define PG8_LDA(dst, b, h) do { _Pragma("unroll") for (int m = 0; m < 4; ++m) _Pragma("unroll") for (int k = 0; k < 2; ++k) dst[m][k] = *(const PG8_LAS bf16x8*)(lds + PG8_SA(b, h) + aoff + m * 2048 + k * 1024); } while (0)
; #define PG8_LDB(dst, b, h) do { _Pragma("unroll") for (int n = 0; n < 2; ++n) _Pragma("unroll") for (int k = 0; k < 2; ++k) dst[n][k] = *(const PG8_LAS bf16x8*)(lds + PG8_SB(b, h) + boff + n * 2048 + k * 1024); } while (0)
; #define PG8_MMA(ai, bj, At, Bt) do { __builtin_amdgcn_s_setprio(1); _Pragma("unroll") for (int m = 0; m < 4; ++m) _Pragma("unroll") for (int n = 0; n < 2; ++n) _Pragma("unroll") for (int k = 0; k < 2; ++k) \
;         acc[ai][bj][m][n] = __builtin_amdgcn_mfma_f32_16x16x32_bf16(Bt[n][k], At[m][k], acc[ai][bj][m][n], 0, 0, 0); __builtin_amdgcn_s_setprio(0); } while (0)
; #define PG8_WAIT_V(n) asm volatile("s_waitcnt vmcnt(" #n ")" ::: "memory")
; #define PG8_WAIT_L(n) asm volatile("s_waitcnt lgkmcnt(" #n ")" ::: "memory")
; template <class Epi, class Sched, bool ALIGN_EPI, bool SP2, int KK, int LDA, int APN>
; __device__ __forceinline__ void gemm_phase(PG8_LAS unsigned char* lds, const Gemm g, const Sched& S, const Epi& E, const int wid) {
;     ...
;             const bool last = (t == nt - 2);
;             const char* a1 = cA + (size_t)(t + 1) * kstep;
;             const char* a2 = last ? nA : cA + (size_t)(t + 2) * kstep; const char* b2 = last ? nB : cB + (size_t)(t + 2) * kstep;
;             const char* a3 = a2 + kstep; const char* b3 = b2 + kstep;
;             if (last && has_next) S.a_ready(nxt);
;             if constexpr (SP2) {
;             PG8_LDB(B0, 0, 0); PG8_LDB(B1, 0, 1); PG8_SCHED; PG8_LDA(At, 0, 0); PG8_STAGE(PG8_SA(1, 1), a1 + hstepA, voffA);
;             PG8_WAIT_V(8); PG8_WAIT_L(0); PG8_BAR; PG8_MMA(0, 0, At, B0); PG8_MMA(0, 1, At, B1); PG8_BAR; PG8_SCHED;
;             PG8_LDA(At, 0, 1); PG8_STAGE(PG8_SB(0, 0), b2, voffB); PG8_STAGE(PG8_SB(0, 1), b2 + hstep, voffB); PG8_STAGE(PG8_SA(0, 0), a2, voffA);
;             PG8_WAIT_V(8); PG8_WAIT_L(0); PG8_BAR; PG8_MMA(1, 0, At, B0); PG8_MMA(1, 1, At, B1); PG8_BAR; PG8_SCHED;
.LBB0_686:
	s_add_u32 s52, s28, s50
	s_addc_u32 s53, s29, s51
	s_add_u32 s52, s52, 0x100
	s_addc_u32 s53, s53, 0
	s_add_u32 s69, s67, s50
	s_addc_u32 s70, s68, s51
	s_add_i32 s71, 0, 0x10000
	s_cmpk_eq_i32 s50, 0xf00
	s_cselect_b32 s55, s19, s53
	s_cselect_b32 s54, s40, s52
	v_add_u32_e32 v144, s71, v148
	s_cselect_b32 s53, s41, s70
	s_cselect_b32 s52, s43, s69
	s_add_i32 s69, 0, 0x14000
	ds_read_b128 v[154:157], v144
	ds_read_b128 v[158:161], v144 offset:1024
	ds_read_b128 v[162:165], v144 offset:2048
	ds_read_b128 v[166:169], v144 offset:3072
	v_add_u32_e32 v144, s69, v148
	ds_read_b128 v[170:173], v144
	ds_read_b128 v[174:177], v144 offset:1024
	ds_read_b128 v[178:181], v144 offset:2048
	ds_read_b128 v[182:185], v144 offset:3072
	v_lshl_add_u64 v[144:145], v[142:143], 0, s[50:51]
	s_add_i32 m0, s13, 0xc000
	ds_read_b128 v[186:189], v150
	ds_read_b128 v[190:193], v150 offset:1024
	ds_read_b128 v[196:199], v150 offset:2048
	ds_read_b128 v[202:205], v150 offset:3072
	ds_read_b128 v[206:209], v150 offset:4096
	ds_read_b128 v[212:215], v150 offset:5120
	ds_read_b128 v[226:229], v150 offset:6144
	ds_read_b128 v[230:233], v150 offset:7168
	global_load_lds_dwordx4 v[144:145], off
	v_lshl_add_u64 v[144:145], v[140:141], 0, s[50:51]
	s_add_i32 m0, s13, 0xe000
	s_nop 0
	global_load_lds_dwordx4 v[144:145], off
	s_waitcnt vmcnt(8)
	s_waitcnt lgkmcnt(0)
	s_setprio 1
	s_barrier
	v_mfma_f32_16x16x32_bf16 v[0:3], v[154:157], v[186:189], v[0:3]
	v_mfma_f32_16x16x32_bf16 v[4:7], v[162:165], v[186:189], v[4:7]
	v_mfma_f32_16x16x32_bf16 v[16:19], v[154:157], v[196:199], v[16:19]
	v_mfma_f32_16x16x32_bf16 v[20:23], v[162:165], v[196:199], v[20:23]
	v_mfma_f32_16x16x32_bf16 v[32:35], v[154:157], v[206:209], v[32:35]
	v_mfma_f32_16x16x32_bf16 v[36:39], v[162:165], v[206:209], v[36:39]
	v_mfma_f32_16x16x32_bf16 v[48:51], v[154:157], v[226:229], v[48:51]
	v_mfma_f32_16x16x32_bf16 v[52:55], v[162:165], v[226:229], v[52:55]
	v_mfma_f32_16x16x32_bf16 v[0:3], v[158:161], v[190:193], v[0:3]
	v_mfma_f32_16x16x32_bf16 v[4:7], v[166:169], v[190:193], v[4:7]
	v_mfma_f32_16x16x32_bf16 v[16:19], v[158:161], v[202:205], v[16:19]
	v_mfma_f32_16x16x32_bf16 v[20:23], v[166:169], v[202:205], v[20:23]
	v_mfma_f32_16x16x32_bf16 v[32:35], v[158:161], v[212:215], v[32:35]
	v_mfma_f32_16x16x32_bf16 v[36:39], v[166:169], v[212:215], v[36:39]
	v_mfma_f32_16x16x32_bf16 v[48:51], v[158:161], v[230:233], v[48:51]
	v_mfma_f32_16x16x32_bf16 v[52:55], v[166:169], v[230:233], v[52:55]
	v_mfma_f32_16x16x32_bf16 v[8:11], v[170:173], v[186:189], v[8:11]
	v_mfma_f32_16x16x32_bf16 v[12:15], v[178:181], v[186:189], v[12:15]
	v_mfma_f32_16x16x32_bf16 v[24:27], v[170:173], v[196:199], v[24:27]
	v_mfma_f32_16x16x32_bf16 v[28:31], v[178:181], v[196:199], v[28:31]
	v_mfma_f32_16x16x32_bf16 v[40:43], v[170:173], v[206:209], v[40:43]
	v_mfma_f32_16x16x32_bf16 v[44:47], v[178:181], v[206:209], v[44:47]
	v_mfma_f32_16x16x32_bf16 v[56:59], v[170:173], v[226:229], v[56:59]
	v_mfma_f32_16x16x32_bf16 v[60:63], v[178:181], v[226:229], v[60:63]
	v_mfma_f32_16x16x32_bf16 v[8:11], v[174:177], v[190:193], v[8:11]
	v_mfma_f32_16x16x32_bf16 v[12:15], v[182:185], v[190:193], v[12:15]
	v_mfma_f32_16x16x32_bf16 v[24:27], v[174:177], v[202:205], v[24:27]
	v_mfma_f32_16x16x32_bf16 v[28:31], v[182:185], v[202:205], v[28:31]
	v_mfma_f32_16x16x32_bf16 v[40:43], v[174:177], v[212:215], v[40:43]
	v_mfma_f32_16x16x32_bf16 v[44:47], v[182:185], v[212:215], v[44:47]
	v_mfma_f32_16x16x32_bf16 v[56:59], v[174:177], v[230:233], v[56:59]
	v_mfma_f32_16x16x32_bf16 v[60:63], v[182:185], v[230:233], v[60:63]
	s_setprio 0
	s_barrier
	s_add_i32 s70, s71, s12
	v_lshl_add_u64 v[144:145], s[52:53], 0, v[96:97]
	s_mov_b32 m0, s70
	ds_read_b128 v[186:189], v150 offset:16384
	ds_read_b128 v[190:193], v150 offset:17408
	ds_read_b128 v[196:199], v150 offset:18432
	ds_read_b128 v[202:205], v150 offset:19456
	ds_read_b128 v[206:209], v150 offset:20480
	ds_read_b128 v[212:215], v150 offset:21504
	ds_read_b128 v[226:229], v150 offset:22528
	ds_read_b128 v[230:233], v150 offset:23552
	global_load_lds_dwordx4 v[144:145], off
	s_add_i32 m0, s70, 0x2000
	s_add_u32 s70, s52, 0x80000
	v_lshl_add_u64 v[216:217], s[52:53], 0, v[134:135]
	s_addc_u32 s71, s53, 0
	s_add_i32 s69, s69, s12
	global_load_lds_dwordx4 v[216:217], off
	v_lshl_add_u64 v[234:235], s[70:71], 0, v[96:97]
	s_mov_b32 m0, s69
	v_lshl_add_u64 v[236:237], s[54:55], 0, v[132:133]
	global_load_lds_dwordx4 v[234:235], off
	v_lshl_add_u64 v[234:235], s[70:71], 0, v[134:135]
	s_add_i32 m0, s69, 0x2000
	s_nop 0
	global_load_lds_dwordx4 v[234:235], off
	v_lshl_add_u64 v[234:235], s[54:55], 0, v[130:131]
	s_mov_b32 m0, s13
	s_nop 0
	global_load_lds_dwordx4 v[234:235], off
	s_mov_b32 m0, s17
	s_nop 0
	global_load_lds_dwordx4 v[236:237], off
	s_waitcnt vmcnt(8)
	s_waitcnt lgkmcnt(0)
	s_setprio 1
	s_barrier
; #define PG8_STAGE(bufoff, gbase, voff) do { _Pragma("unroll") for (int _i = 0; _i < 2; ++_i) \
;         __builtin_amdgcn_global_load_lds((const unsigned*)((const char*)(gbase) + (voff)[_i]), (PG8_LAS unsigned*)(lds + (bufoff) + ldsw + _i * 8192), 16, 0, 0); } while (0)
; #define PG8_LDA(dst, b, h) do { _Pragma("unroll") for (int m = 0; m < 4; ++m) _Pragma("unroll") for (int k = 0; k < 2; ++k) dst[m][k] = *(const PG8_LAS bf16x8*)(lds + PG8_SA(b, h) + aoff + m * 2048 + k * 1024); } while (0)
; #define PG8_LDB(dst, b, h) do { _Pragma("unroll") for (int n = 0; n < 2; ++n) _Pragma("unroll") for (int k = 0; k < 2; ++k) dst[n][k] = *(const PG8_LAS bf16x8*)(lds + PG8_SB(b, h) + boff + n * 2048 + k * 1024); } while (0)
; #define PG8_MMA(ai, bj, At, Bt) do { __builtin_amdgcn_s_setprio(1); _Pragma("unroll") for (int m = 0; m < 4; ++m) _Pragma("unroll") for (int n = 0; n < 2; ++n) _Pragma("unroll") for (int k = 0; k < 2; ++k) \
;         acc[ai][bj][m][n] = __builtin_amdgcn_mfma_f32_16x16x32_bf16(Bt[n][k], At[m][k], acc[ai][bj][m][n], 0, 0, 0); __builtin_amdgcn_s_setprio(0); } while (0)
; #define PG8_WAIT_V(n) asm volatile("s_waitcnt vmcnt(" #n ")" ::: "memory")
; #define PG8_WAIT_L(n) asm volatile("s_waitcnt lgkmcnt(" #n ")" ::: "memory")
; #define PG8_BAR __builtin_amdgcn_s_barrier()
; #define PG8_SCHED __builtin_amdgcn_sched_barrier(0)
; template <class Epi, class Sched, bool ALIGN_EPI, bool SP2, int KK, int LDA, int APN>
; __device__ __forceinline__ void gemm_phase(PG8_LAS unsigned char* lds, const Gemm g, const Sched& S, const Epi& E, const int wid) {
;     ...
;             PG8_WAIT_V(8); PG8_WAIT_L(0); PG8_BAR; PG8_MMA(1, 0, At, B0); PG8_MMA(1, 1, At, B1); PG8_BAR; PG8_SCHED;
;             PG8_LDB(B0, 1, 0); PG8_LDB(B1, 1, 1); PG8_SCHED; PG8_LDA(At, 1, 0); PG8_STAGE(PG8_SA(0, 1), a2 + hstepA, voffA);
;             PG8_WAIT_V(8); PG8_WAIT_L(0); PG8_BAR; PG8_MMA(0, 0, At, B0); PG8_MMA(0, 1, At, B1); PG8_BAR; PG8_SCHED;
	v_mfma_f32_16x16x32_bf16 v[64:67], v[154:157], v[186:189], v[64:67]
	v_mfma_f32_16x16x32_bf16 v[68:71], v[162:165], v[186:189], v[68:71]
	v_mfma_f32_16x16x32_bf16 v[80:83], v[154:157], v[196:199], v[80:83]
	v_mfma_f32_16x16x32_bf16 v[84:87], v[162:165], v[196:199], v[84:87]
	v_mfma_f32_16x16x32_bf16 v[98:101], v[154:157], v[206:209], v[98:101]
	v_mfma_f32_16x16x32_bf16 v[102:105], v[162:165], v[206:209], v[102:105]
	v_mfma_f32_16x16x32_bf16 v[114:117], v[154:157], v[226:229], v[114:117]
	v_mfma_f32_16x16x32_bf16 v[118:121], v[162:165], v[226:229], v[118:121]
	v_mfma_f32_16x16x32_bf16 v[64:67], v[158:161], v[190:193], v[64:67]
	v_mfma_f32_16x16x32_bf16 v[68:71], v[166:169], v[190:193], v[68:71]
	v_mfma_f32_16x16x32_bf16 v[80:83], v[158:161], v[202:205], v[80:83]
	v_mfma_f32_16x16x32_bf16 v[84:87], v[166:169], v[202:205], v[84:87]
	v_mfma_f32_16x16x32_bf16 v[98:101], v[158:161], v[212:215], v[98:101]
	v_mfma_f32_16x16x32_bf16 v[102:105], v[166:169], v[212:215], v[102:105]
	v_mfma_f32_16x16x32_bf16 v[114:117], v[158:161], v[230:233], v[114:117]
	v_mfma_f32_16x16x32_bf16 v[118:121], v[166:169], v[230:233], v[118:121]
	v_mfma_f32_16x16x32_bf16 v[72:75], v[170:173], v[186:189], v[72:75]
	v_mfma_f32_16x16x32_bf16 v[76:79], v[178:181], v[186:189], v[76:79]
	v_mfma_f32_16x16x32_bf16 v[88:91], v[170:173], v[196:199], v[88:91]
	v_mfma_f32_16x16x32_bf16 v[92:95], v[178:181], v[196:199], v[92:95]
	v_mfma_f32_16x16x32_bf16 v[106:109], v[170:173], v[206:209], v[106:109]
	v_mfma_f32_16x16x32_bf16 v[110:113], v[178:181], v[206:209], v[110:113]
	v_mfma_f32_16x16x32_bf16 v[122:125], v[170:173], v[226:229], v[122:125]
	v_mfma_f32_16x16x32_bf16 v[126:129], v[178:181], v[226:229], v[126:129]
	v_mfma_f32_16x16x32_bf16 v[72:75], v[174:177], v[190:193], v[72:75]
	v_mfma_f32_16x16x32_bf16 v[76:79], v[182:185], v[190:193], v[76:79]
	v_mfma_f32_16x16x32_bf16 v[88:91], v[174:177], v[202:205], v[88:91]
	v_mfma_f32_16x16x32_bf16 v[92:95], v[182:185], v[202:205], v[92:95]
	v_mfma_f32_16x16x32_bf16 v[106:109], v[174:177], v[212:215], v[106:109]
	v_mfma_f32_16x16x32_bf16 v[110:113], v[182:185], v[212:215], v[110:113]
	v_mfma_f32_16x16x32_bf16 v[122:125], v[174:177], v[230:233], v[122:125]
	v_mfma_f32_16x16x32_bf16 v[126:129], v[182:185], v[230:233], v[126:129]
	s_setprio 0
	s_barrier
	s_add_i32 s69, 0, 0x18000
	v_add_u32_e32 v153, s69, v148
	s_add_i32 s70, 0, 0x1c000
	ds_read_b128 v[154:157], v153
	ds_read_b128 v[158:161], v153 offset:1024
	ds_read_b128 v[162:165], v153 offset:2048
	ds_read_b128 v[166:169], v153 offset:3072
	v_add_u32_e32 v153, s70, v148
	ds_read_b128 v[170:173], v153
	ds_read_b128 v[174:177], v153 offset:1024
	ds_read_b128 v[178:181], v153 offset:2048
	ds_read_b128 v[182:185], v153 offset:3072
	s_add_u32 s54, s54, 0x80000
	s_addc_u32 s55, s55, 0
	s_mov_b32 m0, s56
	v_lshl_add_u64 v[238:239], s[54:55], 0, v[130:131]
	ds_read_b128 v[186:189], v150 offset:32768
	ds_read_b128 v[190:193], v150 offset:33792
	ds_read_b128 v[196:199], v150 offset:34816
	ds_read_b128 v[202:205], v150 offset:35840
	ds_read_b128 v[206:209], v150 offset:36864
	ds_read_b128 v[212:215], v150 offset:37888
	ds_read_b128 v[226:229], v150 offset:38912
	ds_read_b128 v[230:233], v150 offset:39936
	global_load_lds_dwordx4 v[238:239], off
	v_lshl_add_u64 v[238:239], s[54:55], 0, v[132:133]
	s_mov_b32 m0, s57
	s_nop 0
	global_load_lds_dwordx4 v[238:239], off
	s_waitcnt vmcnt(8)
	s_waitcnt lgkmcnt(0)
	s_setprio 1
	s_barrier
	v_mfma_f32_16x16x32_bf16 v[0:3], v[154:157], v[186:189], v[0:3]
	v_mfma_f32_16x16x32_bf16 v[4:7], v[162:165], v[186:189], v[4:7]
	v_mfma_f32_16x16x32_bf16 v[16:19], v[154:157], v[196:199], v[16:19]
	v_mfma_f32_16x16x32_bf16 v[20:23], v[162:165], v[196:199], v[20:23]
	v_mfma_f32_16x16x32_bf16 v[32:35], v[154:157], v[206:209], v[32:35]
	v_mfma_f32_16x16x32_bf16 v[36:39], v[162:165], v[206:209], v[36:39]
	v_mfma_f32_16x16x32_bf16 v[48:51], v[154:157], v[226:229], v[48:51]
	v_mfma_f32_16x16x32_bf16 v[52:55], v[162:165], v[226:229], v[52:55]
	v_mfma_f32_16x16x32_bf16 v[0:3], v[158:161], v[190:193], v[0:3]
	v_mfma_f32_16x16x32_bf16 v[4:7], v[166:169], v[190:193], v[4:7]
	v_mfma_f32_16x16x32_bf16 v[16:19], v[158:161], v[202:205], v[16:19]
	v_mfma_f32_16x16x32_bf16 v[20:23], v[166:169], v[202:205], v[20:23]
	v_mfma_f32_16x16x32_bf16 v[32:35], v[158:161], v[212:215], v[32:35]
	v_mfma_f32_16x16x32_bf16 v[36:39], v[166:169], v[212:215], v[36:39]
	v_mfma_f32_16x16x32_bf16 v[48:51], v[158:161], v[230:233], v[48:51]
	v_mfma_f32_16x16x32_bf16 v[52:55], v[166:169], v[230:233], v[52:55]
	v_mfma_f32_16x16x32_bf16 v[8:11], v[170:173], v[186:189], v[8:11]
	v_mfma_f32_16x16x32_bf16 v[12:15], v[178:181], v[186:189], v[12:15]
	v_mfma_f32_16x16x32_bf16 v[24:27], v[170:173], v[196:199], v[24:27]
	v_mfma_f32_16x16x32_bf16 v[28:31], v[178:181], v[196:199], v[28:31]
	v_mfma_f32_16x16x32_bf16 v[40:43], v[170:173], v[206:209], v[40:43]
	v_mfma_f32_16x16x32_bf16 v[44:47], v[178:181], v[206:209], v[44:47]
	v_mfma_f32_16x16x32_bf16 v[56:59], v[170:173], v[226:229], v[56:59]
	v_mfma_f32_16x16x32_bf16 v[60:63], v[178:181], v[226:229], v[60:63]
	v_mfma_f32_16x16x32_bf16 v[8:11], v[174:177], v[190:193], v[8:11]
	v_mfma_f32_16x16x32_bf16 v[12:15], v[182:185], v[190:193], v[12:15]
	v_mfma_f32_16x16x32_bf16 v[24:27], v[174:177], v[202:205], v[24:27]
	v_mfma_f32_16x16x32_bf16 v[28:31], v[182:185], v[202:205], v[28:31]
	v_mfma_f32_16x16x32_bf16 v[40:43], v[174:177], v[212:215], v[40:43]
	v_mfma_f32_16x16x32_bf16 v[44:47], v[182:185], v[212:215], v[44:47]
	v_mfma_f32_16x16x32_bf16 v[56:59], v[174:177], v[230:233], v[56:59]
	v_mfma_f32_16x16x32_bf16 v[60:63], v[182:185], v[230:233], v[60:63]
	s_setprio 0
	s_barrier
; #define PG8_STAGE(bufoff, gbase, voff) do { _Pragma("unroll") for (int _i = 0; _i < 2; ++_i) \
;         __builtin_amdgcn_global_load_lds((const unsigned*)((const char*)(gbase) + (voff)[_i]), (PG8_LAS unsigned*)(lds + (bufoff) + ldsw + _i * 8192), 16, 0, 0); } while (0)
; #define PG8_LDA(dst, b, h) do { _Pragma("unroll") for (int m = 0; m < 4; ++m) _Pragma("unroll") for (int k = 0; k < 2; ++k) dst[m][k] = *(const PG8_LAS bf16x8*)(lds + PG8_SA(b, h) + aoff + m * 2048 + k * 1024); } while (0)
; #define PG8_MMA(ai, bj, At, Bt) do { __builtin_amdgcn_s_setprio(1); _Pragma("unroll") for (int m = 0; m < 4; ++m) _Pragma("unroll") for (int n = 0; n < 2; ++n) _Pragma("unroll") for (int k = 0; k < 2; ++k) \
;         acc[ai][bj][m][n] = __builtin_amdgcn_mfma_f32_16x16x32_bf16(Bt[n][k], At[m][k], acc[ai][bj][m][n], 0, 0, 0); __builtin_amdgcn_s_setprio(0); } while (0)
; #define PG8_WAIT_V(n) asm volatile("s_waitcnt vmcnt(" #n ")" ::: "memory")
; #define PG8_WAIT_L(n) asm volatile("s_waitcnt lgkmcnt(" #n ")" ::: "memory")
; #define PG8_BAR __builtin_amdgcn_s_barrier()
; #define PG8_SCHED __builtin_amdgcn_sched_barrier(0)
; template <class Epi, class Sched, bool ALIGN_EPI, bool SP2, int KK, int LDA, int APN>
; __device__ __forceinline__ void gemm_phase(PG8_LAS unsigned char* lds, const Gemm g, const Sched& S, const Epi& E, const int wid) {
;     ...
;         for (int t = 0; t < nt; t += 2) {
;             const bool last = (t == nt - 2);
;             const char* a1 = cA + (size_t)(t + 1) * kstep;
;             const char* a2 = last ? nA : cA + (size_t)(t + 2) * kstep; const char* b2 = last ? nB : cB + (size_t)(t + 2) * kstep;
;             const char* a3 = a2 + kstep; const char* b3 = b2 + kstep;
;     ...
;             PG8_LDA(At, 1, 1); PG8_STAGE(PG8_SB(1, 0), b3, voffB); PG8_STAGE(PG8_SB(1, 1), b3 + hstep, voffB); PG8_STAGE(PG8_SA(1, 0), a3, voffA);
;             PG8_WAIT_V(8); PG8_WAIT_L(0); PG8_BAR; PG8_MMA(1, 0, At, B0); PG8_MMA(1, 1, At, B1); PG8_BAR; PG8_SCHED;
	s_add_i32 s54, s69, s12
	v_lshl_add_u64 v[144:145], v[144:145], 0, s[22:23]
	s_mov_b32 m0, s54
	ds_read_b128 v[186:189], v150 offset:49152
	ds_read_b128 v[190:193], v150 offset:50176
	ds_read_b128 v[196:199], v150 offset:51200
	ds_read_b128 v[202:205], v150 offset:52224
	ds_read_b128 v[206:209], v150 offset:53248
	ds_read_b128 v[212:215], v150 offset:54272
	ds_read_b128 v[226:229], v150 offset:55296
	ds_read_b128 v[230:233], v150 offset:56320
	global_load_lds_dwordx4 v[144:145], off
	s_add_i32 m0, s54, 0x2000
	s_add_u32 s52, s52, 0x80080
	v_lshl_add_u64 v[144:145], v[216:217], 0, s[22:23]
	s_addc_u32 s53, s53, 0
	s_add_i32 s54, s70, s12
	global_load_lds_dwordx4 v[144:145], off
	v_lshl_add_u64 v[144:145], s[52:53], 0, v[96:97]
	s_mov_b32 m0, s54
	s_nop 0
	global_load_lds_dwordx4 v[144:145], off
	v_lshl_add_u64 v[144:145], s[52:53], 0, v[134:135]
	s_add_i32 m0, s54, 0x2000
	s_nop 0
	global_load_lds_dwordx4 v[144:145], off
	v_lshl_add_u64 v[144:145], v[234:235], 0, s[22:23]
	s_mov_b32 m0, s58
	s_nop 0
	global_load_lds_dwordx4 v[144:145], off
	v_lshl_add_u64 v[144:145], v[236:237], 0, s[22:23]
	s_mov_b32 m0, s59
	s_nop 0
	global_load_lds_dwordx4 v[144:145], off
	s_waitcnt vmcnt(8)
	s_waitcnt lgkmcnt(0)
	s_setprio 1
	s_barrier
	v_mfma_f32_16x16x32_bf16 v[64:67], v[154:157], v[186:189], v[64:67]
	v_mfma_f32_16x16x32_bf16 v[68:71], v[162:165], v[186:189], v[68:71]
	v_mfma_f32_16x16x32_bf16 v[80:83], v[154:157], v[196:199], v[80:83]
	v_mfma_f32_16x16x32_bf16 v[84:87], v[162:165], v[196:199], v[84:87]
	v_mfma_f32_16x16x32_bf16 v[98:101], v[154:157], v[206:209], v[98:101]
	v_mfma_f32_16x16x32_bf16 v[102:105], v[162:165], v[206:209], v[102:105]
	v_mfma_f32_16x16x32_bf16 v[114:117], v[154:157], v[226:229], v[114:117]
	v_mfma_f32_16x16x32_bf16 v[118:121], v[162:165], v[226:229], v[118:121]
	v_mfma_f32_16x16x32_bf16 v[64:67], v[158:161], v[190:193], v[64:67]
	v_mfma_f32_16x16x32_bf16 v[68:71], v[166:169], v[190:193], v[68:71]
	v_mfma_f32_16x16x32_bf16 v[80:83], v[158:161], v[202:205], v[80:83]
	v_mfma_f32_16x16x32_bf16 v[84:87], v[166:169], v[202:205], v[84:87]
	v_mfma_f32_16x16x32_bf16 v[98:101], v[158:161], v[212:215], v[98:101]
	v_mfma_f32_16x16x32_bf16 v[102:105], v[166:169], v[212:215], v[102:105]
	v_mfma_f32_16x16x32_bf16 v[114:117], v[158:161], v[230:233], v[114:117]
	v_mfma_f32_16x16x32_bf16 v[118:121], v[166:169], v[230:233], v[118:121]
	v_mfma_f32_16x16x32_bf16 v[72:75], v[170:173], v[186:189], v[72:75]
	v_mfma_f32_16x16x32_bf16 v[76:79], v[178:181], v[186:189], v[76:79]
	v_mfma_f32_16x16x32_bf16 v[88:91], v[170:173], v[196:199], v[88:91]
	v_mfma_f32_16x16x32_bf16 v[92:95], v[178:181], v[196:199], v[92:95]
	v_mfma_f32_16x16x32_bf16 v[106:109], v[170:173], v[206:209], v[106:109]
	v_mfma_f32_16x16x32_bf16 v[110:113], v[178:181], v[206:209], v[110:113]
	v_mfma_f32_16x16x32_bf16 v[122:125], v[170:173], v[226:229], v[122:125]
	v_mfma_f32_16x16x32_bf16 v[126:129], v[178:181], v[226:229], v[126:129]
	v_mfma_f32_16x16x32_bf16 v[72:75], v[174:177], v[190:193], v[72:75]
	v_mfma_f32_16x16x32_bf16 v[76:79], v[182:185], v[190:193], v[76:79]
	v_mfma_f32_16x16x32_bf16 v[88:91], v[174:177], v[202:205], v[88:91]
	v_mfma_f32_16x16x32_bf16 v[92:95], v[182:185], v[202:205], v[92:95]
	v_mfma_f32_16x16x32_bf16 v[106:109], v[174:177], v[212:215], v[106:109]
	v_mfma_f32_16x16x32_bf16 v[110:113], v[182:185], v[212:215], v[110:113]
	v_mfma_f32_16x16x32_bf16 v[122:125], v[174:177], v[230:233], v[122:125]
	v_mfma_f32_16x16x32_bf16 v[126:129], v[182:185], v[230:233], v[126:129]
	s_setprio 0
	s_barrier
	s_add_i32 s45, s45, 2
	s_add_u32 s50, s50, 0x100
	s_addc_u32 s51, s51, 0
	s_cmp_gt_u32 s45, 29
	s_cbranch_scc0 .LBB0_686
	s_and_b64 vcc, exec, s[30:31]
	s_cbranch_vccz .LBB0_689
	s_barrier

; #define PG8_STAGE(bufoff, gbase, voff) do { _Pragma("unroll") for (int _i = 0; _i < 2; ++_i) \
;         __builtin_amdgcn_global_load_lds((const unsigned*)((const char*)(gbase) + (voff)[_i]), (PG8_LAS unsigned*)(lds + (bufoff) + ldsw + _i * 8192), 16, 0, 0); } while (0)
; #define PG8_LDA(dst, b, h) do { _Pragma("unroll") for (int m = 0; m < 4; ++m) _Pragma("unroll") for (int k = 0; k < 2; ++k) dst[m][k] = *(const PG8_LAS bf16x8*)(lds + PG8_SA(b, h) + aoff + m * 2048 + k * 1024); } while (0)
; #define PG8_LDB(dst, b, h) do { _Pragma("unroll") for (int n = 0; n < 2; ++n) _Pragma("unroll") for (int k = 0; k < 2; ++k) dst[n][k] = *(const PG8_LAS bf16x8*)(lds + PG8_SB(b, h) + boff + n * 2048 + k * 1024); } while (0)
; #define PG8_MMA(ai, bj, At, Bt) do { __builtin_amdgcn_s_setprio(1); _Pragma("unroll") for (int m = 0; m < 4; ++m) _Pragma("unroll") for (int n = 0; n < 2; ++n) _Pragma("unroll") for (int k = 0; k < 2; ++k) \
;         acc[ai][bj][m][n] = __builtin_amdgcn_mfma_f32_16x16x32_bf16(Bt[n][k], At[m][k], acc[ai][bj][m][n], 0, 0, 0); __builtin_amdgcn_s_setprio(0); } while (0)
; #define PG8_WAIT_V(n) asm volatile("s_waitcnt vmcnt(" #n ")" ::: "memory")
; #define PG8_WAIT_L(n) asm volatile("s_waitcnt lgkmcnt(" #n ")" ::: "memory")
; template <class Epi, class Sched, bool ALIGN_EPI, bool SP2, int KK, int LDA, int APN>
; __device__ __forceinline__ void gemm_phase(PG8_LAS unsigned char* lds, const Gemm g, const Sched& S, const Epi& E, const int wid) {
;     ...
;             const bool last = (t == nt - 2);
;             const char* a1 = cA + (size_t)(t + 1) * kstep;
;             const char* a2 = last ? nA : cA + (size_t)(t + 2) * kstep; const char* b2 = last ? nB : cB + (size_t)(t + 2) * kstep;
;             const char* a3 = a2 + kstep; const char* b3 = b2 + kstep;
;             if (last && has_next) S.a_ready(nxt);
;             if constexpr (SP2) {
;             PG8_LDB(B0, 0, 0); PG8_LDB(B1, 0, 1); PG8_SCHED; PG8_LDA(At, 0, 0); PG8_STAGE(PG8_SA(1, 1), a1 + hstepA, voffA);
;             PG8_WAIT_V(8); PG8_WAIT_L(0); PG8_BAR; PG8_MMA(0, 0, At, B0); PG8_MMA(0, 1, At, B1); PG8_BAR; PG8_SCHED;
;             PG8_LDA(At, 0, 1); PG8_STAGE(PG8_SB(0, 0), b2, voffB); PG8_STAGE(PG8_SB(0, 1), b2 + hstep, voffB); PG8_STAGE(PG8_SA(0, 0), a2, voffA);
;             PG8_WAIT_V(8); PG8_WAIT_L(0); PG8_BAR; PG8_MMA(1, 0, At, B0); PG8_MMA(1, 1, At, B1); PG8_BAR; PG8_SCHED;
.LBB0_779:
	s_add_u32 s42, s30, 0xfff80080
	s_addc_u32 s43, s31, -1
	s_add_i32 s56, 0, 0x10000
	s_cmp_eq_u32 s55, 28
	s_cselect_b32 s45, s35, s43
	s_cselect_b32 s44, s51, s42
	v_add_u32_e32 v140, s56, v143
	s_cselect_b32 s43, s27, s54
	s_cselect_b32 s42, s52, s53
	s_add_i32 s58, 0, 0x14000
	ds_read_b128 v[148:151], v140
	ds_read_b128 v[152:155], v140 offset:1024
	ds_read_b128 v[156:159], v140 offset:2048
	ds_read_b128 v[160:163], v140 offset:3072
	v_add_u32_e32 v140, s58, v143
	ds_read_b128 v[164:167], v140
	ds_read_b128 v[168:171], v140 offset:1024
	ds_read_b128 v[172:175], v140 offset:2048
	ds_read_b128 v[176:179], v140 offset:3072
	v_lshl_add_u64 v[140:141], s[30:31], 0, v[138:139]
	s_add_i32 m0, s13, 0xc000
	ds_read_b128 v[180:183], v146
	ds_read_b128 v[184:187], v146 offset:1024
	ds_read_b128 v[188:191], v146 offset:2048
	ds_read_b128 v[196:199], v146 offset:3072
	ds_read_b128 v[202:205], v146 offset:4096
	ds_read_b128 v[206:209], v146 offset:5120
	ds_read_b128 v[212:215], v146 offset:6144
	ds_read_b128 v[226:229], v146 offset:7168
	global_load_lds_dwordx4 v[140:141], off
	v_lshl_add_u64 v[140:141], s[30:31], 0, v[136:137]
	s_add_i32 m0, s13, 0xe000
	s_nop 0
	global_load_lds_dwordx4 v[140:141], off
	s_waitcnt vmcnt(8)
	s_waitcnt lgkmcnt(0)
	s_setprio 1
	s_barrier
	v_mfma_f32_16x16x32_bf16 v[126:129], v[148:151], v[180:183], v[126:129]
	v_mfma_f32_16x16x32_bf16 v[118:121], v[156:159], v[180:183], v[118:121]
	v_mfma_f32_16x16x32_bf16 v[110:113], v[148:151], v[188:191], v[110:113]
	v_mfma_f32_16x16x32_bf16 v[102:105], v[156:159], v[188:191], v[102:105]
	v_mfma_f32_16x16x32_bf16 v[92:95], v[148:151], v[202:205], v[92:95]
	v_mfma_f32_16x16x32_bf16 v[84:87], v[156:159], v[202:205], v[84:87]
	v_mfma_f32_16x16x32_bf16 v[76:79], v[148:151], v[212:215], v[76:79]
	v_mfma_f32_16x16x32_bf16 v[68:71], v[156:159], v[212:215], v[68:71]
	v_mfma_f32_16x16x32_bf16 v[126:129], v[152:155], v[184:187], v[126:129]
	v_mfma_f32_16x16x32_bf16 v[118:121], v[160:163], v[184:187], v[118:121]
	v_mfma_f32_16x16x32_bf16 v[110:113], v[152:155], v[196:199], v[110:113]
	v_mfma_f32_16x16x32_bf16 v[102:105], v[160:163], v[196:199], v[102:105]
	v_mfma_f32_16x16x32_bf16 v[92:95], v[152:155], v[206:209], v[92:95]
	v_mfma_f32_16x16x32_bf16 v[84:87], v[160:163], v[206:209], v[84:87]
	v_mfma_f32_16x16x32_bf16 v[76:79], v[152:155], v[226:229], v[76:79]
	v_mfma_f32_16x16x32_bf16 v[68:71], v[160:163], v[226:229], v[68:71]
	v_mfma_f32_16x16x32_bf16 v[122:125], v[164:167], v[180:183], v[122:125]
	v_mfma_f32_16x16x32_bf16 v[114:117], v[172:175], v[180:183], v[114:117]
	v_mfma_f32_16x16x32_bf16 v[106:109], v[164:167], v[188:191], v[106:109]
	v_mfma_f32_16x16x32_bf16 v[98:101], v[172:175], v[188:191], v[98:101]
	v_mfma_f32_16x16x32_bf16 v[88:91], v[164:167], v[202:205], v[88:91]
	v_mfma_f32_16x16x32_bf16 v[80:83], v[172:175], v[202:205], v[80:83]
	v_mfma_f32_16x16x32_bf16 v[72:75], v[164:167], v[212:215], v[72:75]
	v_mfma_f32_16x16x32_bf16 v[64:67], v[172:175], v[212:215], v[64:67]
	v_mfma_f32_16x16x32_bf16 v[122:125], v[168:171], v[184:187], v[122:125]
	v_mfma_f32_16x16x32_bf16 v[114:117], v[176:179], v[184:187], v[114:117]
	v_mfma_f32_16x16x32_bf16 v[106:109], v[168:171], v[196:199], v[106:109]
	v_mfma_f32_16x16x32_bf16 v[98:101], v[176:179], v[196:199], v[98:101]
	v_mfma_f32_16x16x32_bf16 v[88:91], v[168:171], v[206:209], v[88:91]
	v_mfma_f32_16x16x32_bf16 v[80:83], v[176:179], v[206:209], v[80:83]
	v_mfma_f32_16x16x32_bf16 v[72:75], v[168:171], v[226:229], v[72:75]
	v_mfma_f32_16x16x32_bf16 v[64:67], v[176:179], v[226:229], v[64:67]
	s_setprio 0
	s_barrier
	s_add_i32 s56, s56, s12
	v_lshl_add_u64 v[140:141], s[42:43], 0, v[96:97]
	s_mov_b32 m0, s56
	ds_read_b128 v[180:183], v146 offset:16384
	ds_read_b128 v[184:187], v146 offset:17408
	ds_read_b128 v[188:191], v146 offset:18432
	ds_read_b128 v[196:199], v146 offset:19456
	ds_read_b128 v[202:205], v146 offset:20480
	ds_read_b128 v[206:209], v146 offset:21504
	ds_read_b128 v[212:215], v146 offset:22528
	ds_read_b128 v[226:229], v146 offset:23552
	global_load_lds_dwordx4 v[140:141], off
	s_add_i32 m0, s56, 0x2000
	s_add_u32 s56, s42, 0x80000
	v_lshl_add_u64 v[192:193], s[42:43], 0, v[134:135]
	s_addc_u32 s57, s43, 0
	s_add_i32 s58, s58, s12
	global_load_lds_dwordx4 v[192:193], off
	v_lshl_add_u64 v[216:217], s[56:57], 0, v[96:97]
	s_mov_b32 m0, s58
	v_lshl_add_u64 v[230:231], s[44:45], 0, v[132:133]
	global_load_lds_dwordx4 v[216:217], off
	v_lshl_add_u64 v[216:217], s[56:57], 0, v[134:135]
	s_add_i32 m0, s58, 0x2000
	s_nop 0
	global_load_lds_dwordx4 v[216:217], off
	v_lshl_add_u64 v[216:217], s[44:45], 0, v[130:131]
	s_mov_b32 m0, s13
	s_nop 0
	global_load_lds_dwordx4 v[216:217], off
	s_mov_b32 m0, s40
	s_nop 0
	global_load_lds_dwordx4 v[230:231], off
	s_waitcnt vmcnt(8)
	s_waitcnt lgkmcnt(0)
	s_setprio 1
	s_barrier
; #define PG8_STAGE(bufoff, gbase, voff) do { _Pragma("unroll") for (int _i = 0; _i < 2; ++_i) \
;         __builtin_amdgcn_global_load_lds((const unsigned*)((const char*)(gbase) + (voff)[_i]), (PG8_LAS unsigned*)(lds + (bufoff) + ldsw + _i * 8192), 16, 0, 0); } while (0)
; #define PG8_LDA(dst, b, h) do { _Pragma("unroll") for (int m = 0; m < 4; ++m) _Pragma("unroll") for (int k = 0; k < 2; ++k) dst[m][k] = *(const PG8_LAS bf16x8*)(lds + PG8_SA(b, h) + aoff + m * 2048 + k * 1024); } while (0)
; #define PG8_LDB(dst, b, h) do { _Pragma("unroll") for (int n = 0; n < 2; ++n) _Pragma("unroll") for (int k = 0; k < 2; ++k) dst[n][k] = *(const PG8_LAS bf16x8*)(lds + PG8_SB(b, h) + boff + n * 2048 + k * 1024); } while (0)
; #define PG8_MMA(ai, bj, At, Bt) do { __builtin_amdgcn_s_setprio(1); _Pragma("unroll") for (int m = 0; m < 4; ++m) _Pragma("unroll") for (int n = 0; n < 2; ++n) _Pragma("unroll") for (int k = 0; k < 2; ++k) \
;         acc[ai][bj][m][n] = __builtin_amdgcn_mfma_f32_16x16x32_bf16(Bt[n][k], At[m][k], acc[ai][bj][m][n], 0, 0, 0); __builtin_amdgcn_s_setprio(0); } while (0)
; #define PG8_WAIT_V(n) asm volatile("s_waitcnt vmcnt(" #n ")" ::: "memory")
; #define PG8_WAIT_L(n) asm volatile("s_waitcnt lgkmcnt(" #n ")" ::: "memory")
; #define PG8_BAR __builtin_amdgcn_s_barrier()
; #define PG8_SCHED __builtin_amdgcn_sched_barrier(0)
; template <class Epi, class Sched, bool ALIGN_EPI, bool SP2, int KK, int LDA, int APN>
; __device__ __forceinline__ void gemm_phase(PG8_LAS unsigned char* lds, const Gemm g, const Sched& S, const Epi& E, const int wid) {
;     ...
;             PG8_WAIT_V(8); PG8_WAIT_L(0); PG8_BAR; PG8_MMA(1, 0, At, B0); PG8_MMA(1, 1, At, B1); PG8_BAR; PG8_SCHED;
;             PG8_LDB(B0, 1, 0); PG8_LDB(B1, 1, 1); PG8_SCHED; PG8_LDA(At, 1, 0); PG8_STAGE(PG8_SA(0, 1), a2 + hstepA, voffA);
;             PG8_WAIT_V(8); PG8_WAIT_L(0); PG8_BAR; PG8_MMA(0, 0, At, B0); PG8_MMA(0, 1, At, B1); PG8_BAR; PG8_SCHED;
	v_mfma_f32_16x16x32_bf16 v[60:63], v[148:151], v[180:183], v[60:63]
	v_mfma_f32_16x16x32_bf16 v[52:55], v[156:159], v[180:183], v[52:55]
	v_mfma_f32_16x16x32_bf16 v[44:47], v[148:151], v[188:191], v[44:47]
	v_mfma_f32_16x16x32_bf16 v[36:39], v[156:159], v[188:191], v[36:39]
	v_mfma_f32_16x16x32_bf16 v[28:31], v[148:151], v[202:205], v[28:31]
	v_mfma_f32_16x16x32_bf16 v[20:23], v[156:159], v[202:205], v[20:23]
	v_mfma_f32_16x16x32_bf16 v[12:15], v[148:151], v[212:215], v[12:15]
	v_mfma_f32_16x16x32_bf16 v[4:7], v[156:159], v[212:215], v[4:7]
	v_mfma_f32_16x16x32_bf16 v[60:63], v[152:155], v[184:187], v[60:63]
	v_mfma_f32_16x16x32_bf16 v[52:55], v[160:163], v[184:187], v[52:55]
	v_mfma_f32_16x16x32_bf16 v[44:47], v[152:155], v[196:199], v[44:47]
	v_mfma_f32_16x16x32_bf16 v[36:39], v[160:163], v[196:199], v[36:39]
	v_mfma_f32_16x16x32_bf16 v[28:31], v[152:155], v[206:209], v[28:31]
	v_mfma_f32_16x16x32_bf16 v[20:23], v[160:163], v[206:209], v[20:23]
	v_mfma_f32_16x16x32_bf16 v[12:15], v[152:155], v[226:229], v[12:15]
	v_mfma_f32_16x16x32_bf16 v[4:7], v[160:163], v[226:229], v[4:7]
	v_mfma_f32_16x16x32_bf16 v[56:59], v[164:167], v[180:183], v[56:59]
	v_mfma_f32_16x16x32_bf16 v[48:51], v[172:175], v[180:183], v[48:51]
	v_mfma_f32_16x16x32_bf16 v[40:43], v[164:167], v[188:191], v[40:43]
	v_mfma_f32_16x16x32_bf16 v[32:35], v[172:175], v[188:191], v[32:35]
	v_mfma_f32_16x16x32_bf16 v[24:27], v[164:167], v[202:205], v[24:27]
	v_mfma_f32_16x16x32_bf16 v[16:19], v[172:175], v[202:205], v[16:19]
	v_mfma_f32_16x16x32_bf16 v[8:11], v[164:167], v[212:215], v[8:11]
	v_mfma_f32_16x16x32_bf16 v[0:3], v[172:175], v[212:215], v[0:3]
	v_mfma_f32_16x16x32_bf16 v[56:59], v[168:171], v[184:187], v[56:59]
	v_mfma_f32_16x16x32_bf16 v[48:51], v[176:179], v[184:187], v[48:51]
	v_mfma_f32_16x16x32_bf16 v[40:43], v[168:171], v[196:199], v[40:43]
	v_mfma_f32_16x16x32_bf16 v[32:35], v[176:179], v[196:199], v[32:35]
	v_mfma_f32_16x16x32_bf16 v[24:27], v[168:171], v[206:209], v[24:27]
	v_mfma_f32_16x16x32_bf16 v[16:19], v[176:179], v[206:209], v[16:19]
	v_mfma_f32_16x16x32_bf16 v[8:11], v[168:171], v[226:229], v[8:11]
	v_mfma_f32_16x16x32_bf16 v[0:3], v[176:179], v[226:229], v[0:3]
	s_setprio 0
	s_barrier
	s_add_i32 s56, 0, 0x18000
	v_add_u32_e32 v147, s56, v143
	s_add_i32 s57, 0, 0x1c000
	ds_read_b128 v[148:151], v147
	ds_read_b128 v[152:155], v147 offset:1024
	ds_read_b128 v[156:159], v147 offset:2048
	ds_read_b128 v[160:163], v147 offset:3072
	v_add_u32_e32 v147, s57, v143
	ds_read_b128 v[164:167], v147
	ds_read_b128 v[168:171], v147 offset:1024
	ds_read_b128 v[172:175], v147 offset:2048
	ds_read_b128 v[176:179], v147 offset:3072
	s_add_u32 s44, s44, 0x80000
	s_addc_u32 s45, s45, 0
	s_mov_b32 m0, s41
	v_lshl_add_u64 v[232:233], s[44:45], 0, v[130:131]
	ds_read_b128 v[180:183], v146 offset:32768
	ds_read_b128 v[184:187], v146 offset:33792
	ds_read_b128 v[188:191], v146 offset:34816
	ds_read_b128 v[196:199], v146 offset:35840
	ds_read_b128 v[202:205], v146 offset:36864
	ds_read_b128 v[206:209], v146 offset:37888
	ds_read_b128 v[212:215], v146 offset:38912
	ds_read_b128 v[226:229], v146 offset:39936
	global_load_lds_dwordx4 v[232:233], off
	v_lshl_add_u64 v[232:233], s[44:45], 0, v[132:133]
	s_mov_b32 m0, s46
	s_nop 0
	global_load_lds_dwordx4 v[232:233], off
	s_waitcnt vmcnt(8)
	s_waitcnt lgkmcnt(0)
	s_setprio 1
	s_barrier
	v_mfma_f32_16x16x32_bf16 v[126:129], v[148:151], v[180:183], v[126:129]
	v_mfma_f32_16x16x32_bf16 v[118:121], v[156:159], v[180:183], v[118:121]
	v_mfma_f32_16x16x32_bf16 v[110:113], v[148:151], v[188:191], v[110:113]
	v_mfma_f32_16x16x32_bf16 v[102:105], v[156:159], v[188:191], v[102:105]
	v_mfma_f32_16x16x32_bf16 v[92:95], v[148:151], v[202:205], v[92:95]
	v_mfma_f32_16x16x32_bf16 v[84:87], v[156:159], v[202:205], v[84:87]
	v_mfma_f32_16x16x32_bf16 v[76:79], v[148:151], v[212:215], v[76:79]
	v_mfma_f32_16x16x32_bf16 v[68:71], v[156:159], v[212:215], v[68:71]
	v_mfma_f32_16x16x32_bf16 v[126:129], v[152:155], v[184:187], v[126:129]
	v_mfma_f32_16x16x32_bf16 v[118:121], v[160:163], v[184:187], v[118:121]
	v_mfma_f32_16x16x32_bf16 v[110:113], v[152:155], v[196:199], v[110:113]
	v_mfma_f32_16x16x32_bf16 v[102:105], v[160:163], v[196:199], v[102:105]
	v_mfma_f32_16x16x32_bf16 v[92:95], v[152:155], v[206:209], v[92:95]
	v_mfma_f32_16x16x32_bf16 v[84:87], v[160:163], v[206:209], v[84:87]
	v_mfma_f32_16x16x32_bf16 v[76:79], v[152:155], v[226:229], v[76:79]
	v_mfma_f32_16x16x32_bf16 v[68:71], v[160:163], v[226:229], v[68:71]
	v_mfma_f32_16x16x32_bf16 v[122:125], v[164:167], v[180:183], v[122:125]
	v_mfma_f32_16x16x32_bf16 v[114:117], v[172:175], v[180:183], v[114:117]
	v_mfma_f32_16x16x32_bf16 v[106:109], v[164:167], v[188:191], v[106:109]
	v_mfma_f32_16x16x32_bf16 v[98:101], v[172:175], v[188:191], v[98:101]
	v_mfma_f32_16x16x32_bf16 v[88:91], v[164:167], v[202:205], v[88:91]
	v_mfma_f32_16x16x32_bf16 v[80:83], v[172:175], v[202:205], v[80:83]
	v_mfma_f32_16x16x32_bf16 v[72:75], v[164:167], v[212:215], v[72:75]
	v_mfma_f32_16x16x32_bf16 v[64:67], v[172:175], v[212:215], v[64:67]
	v_mfma_f32_16x16x32_bf16 v[122:125], v[168:171], v[184:187], v[122:125]
	v_mfma_f32_16x16x32_bf16 v[114:117], v[176:179], v[184:187], v[114:117]
	v_mfma_f32_16x16x32_bf16 v[106:109], v[168:171], v[196:199], v[106:109]
	v_mfma_f32_16x16x32_bf16 v[98:101], v[176:179], v[196:199], v[98:101]
	v_mfma_f32_16x16x32_bf16 v[88:91], v[168:171], v[206:209], v[88:91]
	v_mfma_f32_16x16x32_bf16 v[80:83], v[176:179], v[206:209], v[80:83]
	v_mfma_f32_16x16x32_bf16 v[72:75], v[168:171], v[226:229], v[72:75]
	v_mfma_f32_16x16x32_bf16 v[64:67], v[176:179], v[226:229], v[64:67]
	s_setprio 0
	s_barrier
; #define PG8_STAGE(bufoff, gbase, voff) do { _Pragma("unroll") for (int _i = 0; _i < 2; ++_i) \
;         __builtin_amdgcn_global_load_lds((const unsigned*)((const char*)(gbase) + (voff)[_i]), (PG8_LAS unsigned*)(lds + (bufoff) + ldsw + _i * 8192), 16, 0, 0); } while (0)
; #define PG8_LDA(dst, b, h) do { _Pragma("unroll") for (int m = 0; m < 4; ++m) _Pragma("unroll") for (int k = 0; k < 2; ++k) dst[m][k] = *(const PG8_LAS bf16x8*)(lds + PG8_SA(b, h) + aoff + m * 2048 + k * 1024); } while (0)
; #define PG8_MMA(ai, bj, At, Bt) do { __builtin_amdgcn_s_setprio(1); _Pragma("unroll") for (int m = 0; m < 4; ++m) _Pragma("unroll") for (int n = 0; n < 2; ++n) _Pragma("unroll") for (int k = 0; k < 2; ++k) \
;         acc[ai][bj][m][n] = __builtin_amdgcn_mfma_f32_16x16x32_bf16(Bt[n][k], At[m][k], acc[ai][bj][m][n], 0, 0, 0); __builtin_amdgcn_s_setprio(0); } while (0)
; #define PG8_WAIT_V(n) asm volatile("s_waitcnt vmcnt(" #n ")" ::: "memory")
; #define PG8_WAIT_L(n) asm volatile("s_waitcnt lgkmcnt(" #n ")" ::: "memory")
; #define PG8_BAR __builtin_amdgcn_s_barrier()
; #define PG8_SCHED __builtin_amdgcn_sched_barrier(0)
; template <class Epi, class Sched, bool ALIGN_EPI, bool SP2, int KK, int LDA, int APN>
; __device__ __forceinline__ void gemm_phase(PG8_LAS unsigned char* lds, const Gemm g, const Sched& S, const Epi& E, const int wid) {
;     ...
;         for (int t = 0; t < nt; t += 2) {
;             const bool last = (t == nt - 2);
;             const char* a1 = cA + (size_t)(t + 1) * kstep;
;             const char* a2 = last ? nA : cA + (size_t)(t + 2) * kstep; const char* b2 = last ? nB : cB + (size_t)(t + 2) * kstep;
;             const char* a3 = a2 + kstep; const char* b3 = b2 + kstep;
;     ...
;             PG8_LDA(At, 1, 1); PG8_STAGE(PG8_SB(1, 0), b3, voffB); PG8_STAGE(PG8_SB(1, 1), b3 + hstep, voffB); PG8_STAGE(PG8_SA(1, 0), a3, voffA);
;             PG8_WAIT_V(8); PG8_WAIT_L(0); PG8_BAR; PG8_MMA(1, 0, At, B0); PG8_MMA(1, 1, At, B1); PG8_BAR; PG8_SCHED;
	s_add_i32 s44, s56, s12
	v_lshl_add_u64 v[140:141], v[140:141], 0, s[22:23]
	s_mov_b32 m0, s44
	ds_read_b128 v[180:183], v146 offset:49152
	ds_read_b128 v[184:187], v146 offset:50176
	ds_read_b128 v[188:191], v146 offset:51200
	ds_read_b128 v[196:199], v146 offset:52224
	ds_read_b128 v[202:205], v146 offset:53248
	ds_read_b128 v[206:209], v146 offset:54272
	ds_read_b128 v[212:215], v146 offset:55296
	ds_read_b128 v[226:229], v146 offset:56320
	global_load_lds_dwordx4 v[140:141], off
	s_add_i32 m0, s44, 0x2000
	s_add_u32 s42, s42, 0x80080
	v_lshl_add_u64 v[140:141], v[192:193], 0, s[22:23]
	s_addc_u32 s43, s43, 0
	s_add_i32 s44, s57, s12
	global_load_lds_dwordx4 v[140:141], off
	v_lshl_add_u64 v[140:141], s[42:43], 0, v[96:97]
	s_mov_b32 m0, s44
	s_nop 0
	global_load_lds_dwordx4 v[140:141], off
	v_lshl_add_u64 v[140:141], s[42:43], 0, v[134:135]
	s_add_i32 m0, s44, 0x2000
	s_nop 0
	global_load_lds_dwordx4 v[140:141], off
	v_lshl_add_u64 v[140:141], v[216:217], 0, s[22:23]
	s_mov_b32 m0, s47
	s_nop 0
	global_load_lds_dwordx4 v[140:141], off
	v_lshl_add_u64 v[140:141], v[230:231], 0, s[22:23]
	s_mov_b32 m0, s48
	s_nop 0
	global_load_lds_dwordx4 v[140:141], off
	s_waitcnt vmcnt(8)
	s_waitcnt lgkmcnt(0)
	s_setprio 1
	s_barrier
	v_mfma_f32_16x16x32_bf16 v[60:63], v[148:151], v[180:183], v[60:63]
	v_mfma_f32_16x16x32_bf16 v[52:55], v[156:159], v[180:183], v[52:55]
	v_mfma_f32_16x16x32_bf16 v[44:47], v[148:151], v[188:191], v[44:47]
	v_mfma_f32_16x16x32_bf16 v[36:39], v[156:159], v[188:191], v[36:39]
	v_mfma_f32_16x16x32_bf16 v[28:31], v[148:151], v[202:205], v[28:31]
	v_mfma_f32_16x16x32_bf16 v[20:23], v[156:159], v[202:205], v[20:23]
	v_mfma_f32_16x16x32_bf16 v[12:15], v[148:151], v[212:215], v[12:15]
	v_mfma_f32_16x16x32_bf16 v[4:7], v[156:159], v[212:215], v[4:7]
	v_mfma_f32_16x16x32_bf16 v[60:63], v[152:155], v[184:187], v[60:63]
	v_mfma_f32_16x16x32_bf16 v[52:55], v[160:163], v[184:187], v[52:55]
	v_mfma_f32_16x16x32_bf16 v[44:47], v[152:155], v[196:199], v[44:47]
	v_mfma_f32_16x16x32_bf16 v[36:39], v[160:163], v[196:199], v[36:39]
	v_mfma_f32_16x16x32_bf16 v[28:31], v[152:155], v[206:209], v[28:31]
	v_mfma_f32_16x16x32_bf16 v[20:23], v[160:163], v[206:209], v[20:23]
	v_mfma_f32_16x16x32_bf16 v[12:15], v[152:155], v[226:229], v[12:15]
	v_mfma_f32_16x16x32_bf16 v[4:7], v[160:163], v[226:229], v[4:7]
	v_mfma_f32_16x16x32_bf16 v[56:59], v[164:167], v[180:183], v[56:59]
	v_mfma_f32_16x16x32_bf16 v[48:51], v[172:175], v[180:183], v[48:51]
	v_mfma_f32_16x16x32_bf16 v[40:43], v[164:167], v[188:191], v[40:43]
	v_mfma_f32_16x16x32_bf16 v[32:35], v[172:175], v[188:191], v[32:35]
	v_mfma_f32_16x16x32_bf16 v[24:27], v[164:167], v[202:205], v[24:27]
	v_mfma_f32_16x16x32_bf16 v[16:19], v[172:175], v[202:205], v[16:19]
	v_mfma_f32_16x16x32_bf16 v[8:11], v[164:167], v[212:215], v[8:11]
	v_mfma_f32_16x16x32_bf16 v[0:3], v[172:175], v[212:215], v[0:3]
	v_mfma_f32_16x16x32_bf16 v[56:59], v[168:171], v[184:187], v[56:59]
	v_mfma_f32_16x16x32_bf16 v[48:51], v[176:179], v[184:187], v[48:51]
	v_mfma_f32_16x16x32_bf16 v[40:43], v[168:171], v[196:199], v[40:43]
	v_mfma_f32_16x16x32_bf16 v[32:35], v[176:179], v[196:199], v[32:35]
	v_mfma_f32_16x16x32_bf16 v[24:27], v[168:171], v[206:209], v[24:27]
	v_mfma_f32_16x16x32_bf16 v[16:19], v[176:179], v[206:209], v[16:19]
	v_mfma_f32_16x16x32_bf16 v[8:11], v[168:171], v[226:229], v[8:11]
	v_mfma_f32_16x16x32_bf16 v[0:3], v[176:179], v[226:229], v[0:3]
	s_setprio 0
	s_barrier
	s_add_i32 s55, s55, 2
	s_add_u32 s53, s53, 0x100
	s_addc_u32 s54, s54, 0
	s_add_u32 s30, s30, 0x100
	s_addc_u32 s31, s31, 0
	s_cmp_gt_u32 s55, 29
	s_cbranch_scc0 .LBB0_779
	s_and_b64 vcc, exec, s[18:19]
	s_cbranch_vccz .LBB0_782
	s_barrier

; #define PG8_STAGE(bufoff, gbase, voff) do { _Pragma("unroll") for (int _i = 0; _i < 2; ++_i) \
;         __builtin_amdgcn_global_load_lds((const unsigned*)((const char*)(gbase) + (voff)[_i]), (PG8_LAS unsigned*)(lds + (bufoff) + ldsw + _i * 8192), 16, 0, 0); } while (0)
; #define PG8_LDA(dst, b, h) do { _Pragma("unroll") for (int m = 0; m < 4; ++m) _Pragma("unroll") for (int k = 0; k < 2; ++k) dst[m][k] = *(const PG8_LAS bf16x8*)(lds + PG8_SA(b, h) + aoff + m * 2048 + k * 1024); } while (0)
; #define PG8_LDB(dst, b, h) do { _Pragma("unroll") for (int n = 0; n < 2; ++n) _Pragma("unroll") for (int k = 0; k < 2; ++k) dst[n][k] = *(const PG8_LAS bf16x8*)(lds + PG8_SB(b, h) + boff + n * 2048 + k * 1024); } while (0)
; #define PG8_MMA(ai, bj, At, Bt) do { __builtin_amdgcn_s_setprio(1); _Pragma("unroll") for (int m = 0; m < 4; ++m) _Pragma("unroll") for (int n = 0; n < 2; ++n) _Pragma("unroll") for (int k = 0; k < 2; ++k) \
;         acc[ai][bj][m][n] = __builtin_amdgcn_mfma_f32_16x16x32_bf16(Bt[n][k], At[m][k], acc[ai][bj][m][n], 0, 0, 0); __builtin_amdgcn_s_setprio(0); } while (0)
; #define PG8_WAIT_V(n) asm volatile("s_waitcnt vmcnt(" #n ")" ::: "memory")
; #define PG8_WAIT_L(n) asm volatile("s_waitcnt lgkmcnt(" #n ")" ::: "memory")
; template <class Epi, class Sched, bool ALIGN_EPI, bool SP2, int KK, int LDA, int APN>
; __device__ __forceinline__ void gemm_phase(PG8_LAS unsigned char* lds, const Gemm g, const Sched& S, const Epi& E, const int wid) {
;     ...
;             const bool last = (t == nt - 2);
;             const char* a1 = cA + (size_t)(t + 1) * kstep;
;             const char* a2 = last ? nA : cA + (size_t)(t + 2) * kstep; const char* b2 = last ? nB : cB + (size_t)(t + 2) * kstep;
;             const char* a3 = a2 + kstep; const char* b3 = b2 + kstep;
;             if (last && has_next) S.a_ready(nxt);
;             if constexpr (SP2) {
;             PG8_LDB(B0, 0, 0); PG8_LDB(B1, 0, 1); PG8_SCHED; PG8_LDA(At, 0, 0); PG8_STAGE(PG8_SA(1, 1), a1 + hstepA, voffA);
;             PG8_WAIT_V(8); PG8_WAIT_L(0); PG8_BAR; PG8_MMA(0, 0, At, B0); PG8_MMA(0, 1, At, B1); PG8_BAR; PG8_SCHED;
;             PG8_LDA(At, 0, 1); PG8_STAGE(PG8_SB(0, 0), b2, voffB); PG8_STAGE(PG8_SB(0, 1), b2 + hstep, voffB); PG8_STAGE(PG8_SA(0, 0), a2, voffA);
;             PG8_WAIT_V(8); PG8_WAIT_L(0); PG8_BAR; PG8_MMA(1, 0, At, B0); PG8_MMA(1, 1, At, B1); PG8_BAR; PG8_SCHED;
.LBB0_860:
	s_add_u32 s30, s16, s28
	s_addc_u32 s31, s17, s29
	s_add_u32 s30, s30, 0x100
	s_addc_u32 s31, s31, 0
	s_add_u32 s61, s59, s28
	s_addc_u32 s66, s60, s29
	s_add_i32 s67, 0, 0x10000
	s_cmpk_eq_i32 s28, 0x2b00
	s_cselect_b32 s49, s43, s31
	s_cselect_b32 s48, s42, s30
	s_cselect_b32 s31, s27, s66
	s_cselect_b32 s30, s26, s61
	s_add_i32 s61, 0, 0x14000
	v_add_u32_e32 v146, s67, v174
	v_add_u32_e32 v179, s61, v174
	ds_read_b128 v[134:137], v146
	ds_read_b128 v[138:141], v146 offset:1024
	ds_read_b128 v[142:145], v146 offset:2048
	ds_read_b128 v[146:149], v146 offset:3072
	ds_read_b128 v[150:153], v179
	ds_read_b128 v[164:167], v179 offset:1024
	ds_read_b128 v[168:171], v179 offset:2048
	ds_read_b128 v[180:183], v179 offset:3072
	v_lshl_add_u64 v[192:193], v[132:133], 0, s[28:29]
	s_add_i32 m0, s55, 0xc000
	ds_read_b128 v[184:187], v176
	ds_read_b128 v[188:191], v176 offset:1024
	ds_read_b128 v[196:199], v176 offset:2048
	ds_read_b128 v[202:205], v176 offset:3072
	ds_read_b128 v[206:209], v176 offset:4096
	ds_read_b128 v[212:215], v176 offset:5120
	ds_read_b128 v[226:229], v176 offset:6144
	ds_read_b128 v[230:233], v176 offset:7168
	global_load_lds_dwordx4 v[192:193], off
	v_lshl_add_u64 v[192:193], v[130:131], 0, s[28:29]
	s_add_i32 m0, s55, 0xe000
	s_nop 0
	global_load_lds_dwordx4 v[192:193], off
	s_waitcnt vmcnt(8)
	s_waitcnt lgkmcnt(0)
	s_setprio 1
	s_barrier
	v_mfma_f32_16x16x32_bf16 v[0:3], v[134:137], v[184:187], v[0:3]
	v_mfma_f32_16x16x32_bf16 v[4:7], v[142:145], v[184:187], v[4:7]
	v_mfma_f32_16x16x32_bf16 v[16:19], v[134:137], v[196:199], v[16:19]
	v_mfma_f32_16x16x32_bf16 v[20:23], v[142:145], v[196:199], v[20:23]
	v_mfma_f32_16x16x32_bf16 v[32:35], v[134:137], v[206:209], v[32:35]
	v_mfma_f32_16x16x32_bf16 v[36:39], v[142:145], v[206:209], v[36:39]
	v_mfma_f32_16x16x32_bf16 v[48:51], v[134:137], v[226:229], v[48:51]
	v_mfma_f32_16x16x32_bf16 v[52:55], v[142:145], v[226:229], v[52:55]
	v_mfma_f32_16x16x32_bf16 v[0:3], v[138:141], v[188:191], v[0:3]
	v_mfma_f32_16x16x32_bf16 v[4:7], v[146:149], v[188:191], v[4:7]
	v_mfma_f32_16x16x32_bf16 v[16:19], v[138:141], v[202:205], v[16:19]
	v_mfma_f32_16x16x32_bf16 v[20:23], v[146:149], v[202:205], v[20:23]
	v_mfma_f32_16x16x32_bf16 v[32:35], v[138:141], v[212:215], v[32:35]
	v_mfma_f32_16x16x32_bf16 v[36:39], v[146:149], v[212:215], v[36:39]
	v_mfma_f32_16x16x32_bf16 v[48:51], v[138:141], v[230:233], v[48:51]
	v_mfma_f32_16x16x32_bf16 v[52:55], v[146:149], v[230:233], v[52:55]
	v_mfma_f32_16x16x32_bf16 v[8:11], v[150:153], v[184:187], v[8:11]
	v_mfma_f32_16x16x32_bf16 v[12:15], v[168:171], v[184:187], v[12:15]
	v_mfma_f32_16x16x32_bf16 v[24:27], v[150:153], v[196:199], v[24:27]
	v_mfma_f32_16x16x32_bf16 v[28:31], v[168:171], v[196:199], v[28:31]
	v_mfma_f32_16x16x32_bf16 v[40:43], v[150:153], v[206:209], v[40:43]
	v_mfma_f32_16x16x32_bf16 v[44:47], v[168:171], v[206:209], v[44:47]
	v_mfma_f32_16x16x32_bf16 v[56:59], v[150:153], v[226:229], v[56:59]
	v_mfma_f32_16x16x32_bf16 v[60:63], v[168:171], v[226:229], v[60:63]
	v_mfma_f32_16x16x32_bf16 v[8:11], v[164:167], v[188:191], v[8:11]
	v_mfma_f32_16x16x32_bf16 v[12:15], v[180:183], v[188:191], v[12:15]
	v_mfma_f32_16x16x32_bf16 v[24:27], v[164:167], v[202:205], v[24:27]
	v_mfma_f32_16x16x32_bf16 v[28:31], v[180:183], v[202:205], v[28:31]
	v_mfma_f32_16x16x32_bf16 v[40:43], v[164:167], v[212:215], v[40:43]
	v_mfma_f32_16x16x32_bf16 v[44:47], v[180:183], v[212:215], v[44:47]
	v_mfma_f32_16x16x32_bf16 v[56:59], v[164:167], v[230:233], v[56:59]
	v_mfma_f32_16x16x32_bf16 v[60:63], v[180:183], v[230:233], v[60:63]
	s_setprio 0
	s_barrier
	s_add_i32 s66, s67, s54
	v_lshl_add_u64 v[192:193], s[30:31], 0, v[96:97]
	s_mov_b32 m0, s66
	ds_read_b128 v[184:187], v176 offset:16384
	ds_read_b128 v[188:191], v176 offset:17408
	ds_read_b128 v[196:199], v176 offset:18432
	ds_read_b128 v[202:205], v176 offset:19456
	ds_read_b128 v[206:209], v176 offset:20480
	ds_read_b128 v[212:215], v176 offset:21504
	ds_read_b128 v[226:229], v176 offset:22528
	ds_read_b128 v[230:233], v176 offset:23552
	global_load_lds_dwordx4 v[192:193], off
	s_add_i32 m0, s66, 0x2000
	s_add_u32 s66, s30, 0x160000
	v_lshl_add_u64 v[216:217], s[30:31], 0, v[158:159]
	s_addc_u32 s67, s31, 0
	s_add_i32 s61, s61, s54
	global_load_lds_dwordx4 v[216:217], off
	v_lshl_add_u64 v[234:235], s[66:67], 0, v[96:97]
	s_mov_b32 m0, s61
	v_lshl_add_u64 v[236:237], s[48:49], 0, v[156:157]
	global_load_lds_dwordx4 v[234:235], off
	v_lshl_add_u64 v[234:235], s[66:67], 0, v[158:159]
	s_add_i32 m0, s61, 0x2000
	s_nop 0
	global_load_lds_dwordx4 v[234:235], off
	v_lshl_add_u64 v[234:235], s[48:49], 0, v[154:155]
	s_mov_b32 m0, s55
	s_nop 0
	global_load_lds_dwordx4 v[234:235], off
	s_mov_b32 m0, s56
	s_nop 0
	global_load_lds_dwordx4 v[236:237], off
	s_waitcnt vmcnt(8)
	s_waitcnt lgkmcnt(0)
	s_setprio 1
	s_barrier
; #define PG8_STAGE(bufoff, gbase, voff) do { _Pragma("unroll") for (int _i = 0; _i < 2; ++_i) \
;         __builtin_amdgcn_global_load_lds((const unsigned*)((const char*)(gbase) + (voff)[_i]), (PG8_LAS unsigned*)(lds + (bufoff) + ldsw + _i * 8192), 16, 0, 0); } while (0)
; #define PG8_LDA(dst, b, h) do { _Pragma("unroll") for (int m = 0; m < 4; ++m) _Pragma("unroll") for (int k = 0; k < 2; ++k) dst[m][k] = *(const PG8_LAS bf16x8*)(lds + PG8_SA(b, h) + aoff + m * 2048 + k * 1024); } while (0)
; #define PG8_LDB(dst, b, h) do { _Pragma("unroll") for (int n = 0; n < 2; ++n) _Pragma("unroll") for (int k = 0; k < 2; ++k) dst[n][k] = *(const PG8_LAS bf16x8*)(lds + PG8_SB(b, h) + boff + n * 2048 + k * 1024); } while (0)
; #define PG8_MMA(ai, bj, At, Bt) do { __builtin_amdgcn_s_setprio(1); _Pragma("unroll") for (int m = 0; m < 4; ++m) _Pragma("unroll") for (int n = 0; n < 2; ++n) _Pragma("unroll") for (int k = 0; k < 2; ++k) \
;         acc[ai][bj][m][n] = __builtin_amdgcn_mfma_f32_16x16x32_bf16(Bt[n][k], At[m][k], acc[ai][bj][m][n], 0, 0, 0); __builtin_amdgcn_s_setprio(0); } while (0)
; #define PG8_WAIT_V(n) asm volatile("s_waitcnt vmcnt(" #n ")" ::: "memory")
; #define PG8_WAIT_L(n) asm volatile("s_waitcnt lgkmcnt(" #n ")" ::: "memory")
; #define PG8_BAR __builtin_amdgcn_s_barrier()
; #define PG8_SCHED __builtin_amdgcn_sched_barrier(0)
; template <class Epi, class Sched, bool ALIGN_EPI, bool SP2, int KK, int LDA, int APN>
; __device__ __forceinline__ void gemm_phase(PG8_LAS unsigned char* lds, const Gemm g, const Sched& S, const Epi& E, const int wid) {
;     ...
;             PG8_WAIT_V(8); PG8_WAIT_L(0); PG8_BAR; PG8_MMA(1, 0, At, B0); PG8_MMA(1, 1, At, B1); PG8_BAR; PG8_SCHED;
;             PG8_LDB(B0, 1, 0); PG8_LDB(B1, 1, 1); PG8_SCHED; PG8_LDA(At, 1, 0); PG8_STAGE(PG8_SA(0, 1), a2 + hstepA, voffA);
;             PG8_WAIT_V(8); PG8_WAIT_L(0); PG8_BAR; PG8_MMA(0, 0, At, B0); PG8_MMA(0, 1, At, B1); PG8_BAR; PG8_SCHED;
	v_mfma_f32_16x16x32_bf16 v[64:67], v[134:137], v[184:187], v[64:67]
	v_mfma_f32_16x16x32_bf16 v[68:71], v[142:145], v[184:187], v[68:71]
	v_mfma_f32_16x16x32_bf16 v[80:83], v[134:137], v[196:199], v[80:83]
	v_mfma_f32_16x16x32_bf16 v[84:87], v[142:145], v[196:199], v[84:87]
	v_mfma_f32_16x16x32_bf16 v[98:101], v[134:137], v[206:209], v[98:101]
	v_mfma_f32_16x16x32_bf16 v[102:105], v[142:145], v[206:209], v[102:105]
	v_mfma_f32_16x16x32_bf16 v[114:117], v[134:137], v[226:229], v[114:117]
	v_mfma_f32_16x16x32_bf16 v[118:121], v[142:145], v[226:229], v[118:121]
	v_mfma_f32_16x16x32_bf16 v[64:67], v[138:141], v[188:191], v[64:67]
	v_mfma_f32_16x16x32_bf16 v[68:71], v[146:149], v[188:191], v[68:71]
	v_mfma_f32_16x16x32_bf16 v[80:83], v[138:141], v[202:205], v[80:83]
	v_mfma_f32_16x16x32_bf16 v[84:87], v[146:149], v[202:205], v[84:87]
	v_mfma_f32_16x16x32_bf16 v[98:101], v[138:141], v[212:215], v[98:101]
	v_mfma_f32_16x16x32_bf16 v[102:105], v[146:149], v[212:215], v[102:105]
	v_mfma_f32_16x16x32_bf16 v[114:117], v[138:141], v[230:233], v[114:117]
	v_mfma_f32_16x16x32_bf16 v[118:121], v[146:149], v[230:233], v[118:121]
	v_mfma_f32_16x16x32_bf16 v[72:75], v[150:153], v[184:187], v[72:75]
	v_mfma_f32_16x16x32_bf16 v[76:79], v[168:171], v[184:187], v[76:79]
	v_mfma_f32_16x16x32_bf16 v[88:91], v[150:153], v[196:199], v[88:91]
	v_mfma_f32_16x16x32_bf16 v[92:95], v[168:171], v[196:199], v[92:95]
	v_mfma_f32_16x16x32_bf16 v[106:109], v[150:153], v[206:209], v[106:109]
	v_mfma_f32_16x16x32_bf16 v[110:113], v[168:171], v[206:209], v[110:113]
	v_mfma_f32_16x16x32_bf16 v[122:125], v[150:153], v[226:229], v[122:125]
	v_mfma_f32_16x16x32_bf16 v[126:129], v[168:171], v[226:229], v[126:129]
	v_mfma_f32_16x16x32_bf16 v[72:75], v[164:167], v[188:191], v[72:75]
	v_mfma_f32_16x16x32_bf16 v[76:79], v[180:183], v[188:191], v[76:79]
	v_mfma_f32_16x16x32_bf16 v[88:91], v[164:167], v[202:205], v[88:91]
	v_mfma_f32_16x16x32_bf16 v[92:95], v[180:183], v[202:205], v[92:95]
	v_mfma_f32_16x16x32_bf16 v[106:109], v[164:167], v[212:215], v[106:109]
	v_mfma_f32_16x16x32_bf16 v[110:113], v[180:183], v[212:215], v[110:113]
	v_mfma_f32_16x16x32_bf16 v[122:125], v[164:167], v[230:233], v[122:125]
	v_mfma_f32_16x16x32_bf16 v[126:129], v[180:183], v[230:233], v[126:129]
	s_setprio 0
	s_barrier
	s_add_i32 s61, 0, 0x18000
	s_add_i32 s66, 0, 0x1c000
	v_add_u32_e32 v146, s61, v174
	v_add_u32_e32 v179, s66, v174
	ds_read_b128 v[134:137], v146
	ds_read_b128 v[138:141], v146 offset:1024
	ds_read_b128 v[142:145], v146 offset:2048
	ds_read_b128 v[146:149], v146 offset:3072
	ds_read_b128 v[150:153], v179
	ds_read_b128 v[164:167], v179 offset:1024
	ds_read_b128 v[168:171], v179 offset:2048
	ds_read_b128 v[180:183], v179 offset:3072
	s_add_u32 s48, s48, 0x160000
	s_addc_u32 s49, s49, 0
	s_mov_b32 m0, s57
	v_lshl_add_u64 v[238:239], s[48:49], 0, v[154:155]
	ds_read_b128 v[184:187], v176 offset:32768
	ds_read_b128 v[188:191], v176 offset:33792
	ds_read_b128 v[196:199], v176 offset:34816
	ds_read_b128 v[202:205], v176 offset:35840
	ds_read_b128 v[206:209], v176 offset:36864
	ds_read_b128 v[212:215], v176 offset:37888
	ds_read_b128 v[226:229], v176 offset:38912
	ds_read_b128 v[230:233], v176 offset:39936
	global_load_lds_dwordx4 v[238:239], off
	v_lshl_add_u64 v[238:239], s[48:49], 0, v[156:157]
	s_mov_b32 m0, s58
	s_nop 0
	global_load_lds_dwordx4 v[238:239], off
	s_waitcnt vmcnt(8)
	s_waitcnt lgkmcnt(0)
	s_setprio 1
	s_barrier
	v_mfma_f32_16x16x32_bf16 v[0:3], v[134:137], v[184:187], v[0:3]
	v_mfma_f32_16x16x32_bf16 v[4:7], v[142:145], v[184:187], v[4:7]
	v_mfma_f32_16x16x32_bf16 v[16:19], v[134:137], v[196:199], v[16:19]
	v_mfma_f32_16x16x32_bf16 v[20:23], v[142:145], v[196:199], v[20:23]
	v_mfma_f32_16x16x32_bf16 v[32:35], v[134:137], v[206:209], v[32:35]
	v_mfma_f32_16x16x32_bf16 v[36:39], v[142:145], v[206:209], v[36:39]
	v_mfma_f32_16x16x32_bf16 v[48:51], v[134:137], v[226:229], v[48:51]
	v_mfma_f32_16x16x32_bf16 v[52:55], v[142:145], v[226:229], v[52:55]
	v_mfma_f32_16x16x32_bf16 v[0:3], v[138:141], v[188:191], v[0:3]
	v_mfma_f32_16x16x32_bf16 v[4:7], v[146:149], v[188:191], v[4:7]
	v_mfma_f32_16x16x32_bf16 v[16:19], v[138:141], v[202:205], v[16:19]
	v_mfma_f32_16x16x32_bf16 v[20:23], v[146:149], v[202:205], v[20:23]
	v_mfma_f32_16x16x32_bf16 v[32:35], v[138:141], v[212:215], v[32:35]
	v_mfma_f32_16x16x32_bf16 v[36:39], v[146:149], v[212:215], v[36:39]
	v_mfma_f32_16x16x32_bf16 v[48:51], v[138:141], v[230:233], v[48:51]
	v_mfma_f32_16x16x32_bf16 v[52:55], v[146:149], v[230:233], v[52:55]
	v_mfma_f32_16x16x32_bf16 v[8:11], v[150:153], v[184:187], v[8:11]
	v_mfma_f32_16x16x32_bf16 v[12:15], v[168:171], v[184:187], v[12:15]
	v_mfma_f32_16x16x32_bf16 v[24:27], v[150:153], v[196:199], v[24:27]
	v_mfma_f32_16x16x32_bf16 v[28:31], v[168:171], v[196:199], v[28:31]
	v_mfma_f32_16x16x32_bf16 v[40:43], v[150:153], v[206:209], v[40:43]
	v_mfma_f32_16x16x32_bf16 v[44:47], v[168:171], v[206:209], v[44:47]
	v_mfma_f32_16x16x32_bf16 v[56:59], v[150:153], v[226:229], v[56:59]
	v_mfma_f32_16x16x32_bf16 v[60:63], v[168:171], v[226:229], v[60:63]
	v_mfma_f32_16x16x32_bf16 v[8:11], v[164:167], v[188:191], v[8:11]
	v_mfma_f32_16x16x32_bf16 v[12:15], v[180:183], v[188:191], v[12:15]
	v_mfma_f32_16x16x32_bf16 v[24:27], v[164:167], v[202:205], v[24:27]
	v_mfma_f32_16x16x32_bf16 v[28:31], v[180:183], v[202:205], v[28:31]
	v_mfma_f32_16x16x32_bf16 v[40:43], v[164:167], v[212:215], v[40:43]
	v_mfma_f32_16x16x32_bf16 v[44:47], v[180:183], v[212:215], v[44:47]
	v_mfma_f32_16x16x32_bf16 v[56:59], v[164:167], v[230:233], v[56:59]
	v_mfma_f32_16x16x32_bf16 v[60:63], v[180:183], v[230:233], v[60:63]
	s_setprio 0
	s_barrier
; #define PG8_STAGE(bufoff, gbase, voff) do { _Pragma("unroll") for (int _i = 0; _i < 2; ++_i) \
;         __builtin_amdgcn_global_load_lds((const unsigned*)((const char*)(gbase) + (voff)[_i]), (PG8_LAS unsigned*)(lds + (bufoff) + ldsw + _i * 8192), 16, 0, 0); } while (0)
; #define PG8_LDA(dst, b, h) do { _Pragma("unroll") for (int m = 0; m < 4; ++m) _Pragma("unroll") for (int k = 0; k < 2; ++k) dst[m][k] = *(const PG8_LAS bf16x8*)(lds + PG8_SA(b, h) + aoff + m * 2048 + k * 1024); } while (0)
; #define PG8_MMA(ai, bj, At, Bt) do { __builtin_amdgcn_s_setprio(1); _Pragma("unroll") for (int m = 0; m < 4; ++m) _Pragma("unroll") for (int n = 0; n < 2; ++n) _Pragma("unroll") for (int k = 0; k < 2; ++k) \
;         acc[ai][bj][m][n] = __builtin_amdgcn_mfma_f32_16x16x32_bf16(Bt[n][k], At[m][k], acc[ai][bj][m][n], 0, 0, 0); __builtin_amdgcn_s_setprio(0); } while (0)
; #define PG8_WAIT_V(n) asm volatile("s_waitcnt vmcnt(" #n ")" ::: "memory")
; #define PG8_WAIT_L(n) asm volatile("s_waitcnt lgkmcnt(" #n ")" ::: "memory")
; #define PG8_BAR __builtin_amdgcn_s_barrier()
; #define PG8_SCHED __builtin_amdgcn_sched_barrier(0)
; template <class Epi, class Sched, bool ALIGN_EPI, bool SP2, int KK, int LDA, int APN>
; __device__ __forceinline__ void gemm_phase(PG8_LAS unsigned char* lds, const Gemm g, const Sched& S, const Epi& E, const int wid) {
;     ...
;         for (int t = 0; t < nt; t += 2) {
;             const bool last = (t == nt - 2);
;             const char* a1 = cA + (size_t)(t + 1) * kstep;
;             const char* a2 = last ? nA : cA + (size_t)(t + 2) * kstep; const char* b2 = last ? nB : cB + (size_t)(t + 2) * kstep;
;             const char* a3 = a2 + kstep; const char* b3 = b2 + kstep;
;     ...
;             PG8_LDA(At, 1, 1); PG8_STAGE(PG8_SB(1, 0), b3, voffB); PG8_STAGE(PG8_SB(1, 1), b3 + hstep, voffB); PG8_STAGE(PG8_SA(1, 0), a3, voffA);
;             PG8_WAIT_V(8); PG8_WAIT_L(0); PG8_BAR; PG8_MMA(1, 0, At, B0); PG8_MMA(1, 1, At, B1); PG8_BAR; PG8_SCHED;
	s_add_i32 s48, s61, s54
	v_lshl_add_u64 v[192:193], v[192:193], 0, s[22:23]
	s_mov_b32 m0, s48
	ds_read_b128 v[184:187], v176 offset:49152
	ds_read_b128 v[188:191], v176 offset:50176
	ds_read_b128 v[196:199], v176 offset:51200
	ds_read_b128 v[202:205], v176 offset:52224
	ds_read_b128 v[206:209], v176 offset:53248
	ds_read_b128 v[212:215], v176 offset:54272
	ds_read_b128 v[226:229], v176 offset:55296
	ds_read_b128 v[230:233], v176 offset:56320
	global_load_lds_dwordx4 v[192:193], off
	s_add_i32 m0, s48, 0x2000
	s_add_u32 s30, s30, 0x160080
	v_lshl_add_u64 v[192:193], v[216:217], 0, s[22:23]
	s_addc_u32 s31, s31, 0
	s_add_i32 s48, s66, s54
	global_load_lds_dwordx4 v[192:193], off
	v_lshl_add_u64 v[192:193], s[30:31], 0, v[96:97]
	s_mov_b32 m0, s48
	s_nop 0
	global_load_lds_dwordx4 v[192:193], off
	v_lshl_add_u64 v[192:193], s[30:31], 0, v[158:159]
	s_add_i32 m0, s48, 0x2000
	s_nop 0
	global_load_lds_dwordx4 v[192:193], off
	v_lshl_add_u64 v[192:193], v[234:235], 0, s[22:23]
	s_mov_b32 m0, s7
	s_nop 0
	global_load_lds_dwordx4 v[192:193], off
	v_lshl_add_u64 v[192:193], v[236:237], 0, s[22:23]
	s_mov_b32 m0, s8
	s_nop 0
	global_load_lds_dwordx4 v[192:193], off
	s_waitcnt vmcnt(8)
	s_waitcnt lgkmcnt(0)
	s_setprio 1
	s_barrier
	v_mfma_f32_16x16x32_bf16 v[64:67], v[134:137], v[184:187], v[64:67]
	v_mfma_f32_16x16x32_bf16 v[68:71], v[142:145], v[184:187], v[68:71]
	v_mfma_f32_16x16x32_bf16 v[80:83], v[134:137], v[196:199], v[80:83]
	v_mfma_f32_16x16x32_bf16 v[84:87], v[142:145], v[196:199], v[84:87]
	v_mfma_f32_16x16x32_bf16 v[98:101], v[134:137], v[206:209], v[98:101]
	v_mfma_f32_16x16x32_bf16 v[102:105], v[142:145], v[206:209], v[102:105]
	v_mfma_f32_16x16x32_bf16 v[114:117], v[134:137], v[226:229], v[114:117]
	v_mfma_f32_16x16x32_bf16 v[118:121], v[142:145], v[226:229], v[118:121]
	v_mfma_f32_16x16x32_bf16 v[64:67], v[138:141], v[188:191], v[64:67]
	v_mfma_f32_16x16x32_bf16 v[68:71], v[146:149], v[188:191], v[68:71]
	v_mfma_f32_16x16x32_bf16 v[80:83], v[138:141], v[202:205], v[80:83]
	v_mfma_f32_16x16x32_bf16 v[84:87], v[146:149], v[202:205], v[84:87]
	v_mfma_f32_16x16x32_bf16 v[98:101], v[138:141], v[212:215], v[98:101]
	v_mfma_f32_16x16x32_bf16 v[102:105], v[146:149], v[212:215], v[102:105]
	v_mfma_f32_16x16x32_bf16 v[114:117], v[138:141], v[230:233], v[114:117]
	v_mfma_f32_16x16x32_bf16 v[118:121], v[146:149], v[230:233], v[118:121]
	v_mfma_f32_16x16x32_bf16 v[72:75], v[150:153], v[184:187], v[72:75]
	v_mfma_f32_16x16x32_bf16 v[76:79], v[168:171], v[184:187], v[76:79]
	v_mfma_f32_16x16x32_bf16 v[88:91], v[150:153], v[196:199], v[88:91]
	v_mfma_f32_16x16x32_bf16 v[92:95], v[168:171], v[196:199], v[92:95]
	v_mfma_f32_16x16x32_bf16 v[106:109], v[150:153], v[206:209], v[106:109]
	v_mfma_f32_16x16x32_bf16 v[110:113], v[168:171], v[206:209], v[110:113]
	v_mfma_f32_16x16x32_bf16 v[122:125], v[150:153], v[226:229], v[122:125]
	v_mfma_f32_16x16x32_bf16 v[126:129], v[168:171], v[226:229], v[126:129]
	v_mfma_f32_16x16x32_bf16 v[72:75], v[164:167], v[188:191], v[72:75]
	v_mfma_f32_16x16x32_bf16 v[76:79], v[180:183], v[188:191], v[76:79]
	v_mfma_f32_16x16x32_bf16 v[88:91], v[164:167], v[202:205], v[88:91]
	v_mfma_f32_16x16x32_bf16 v[92:95], v[180:183], v[202:205], v[92:95]
	v_mfma_f32_16x16x32_bf16 v[106:109], v[164:167], v[212:215], v[106:109]
	v_mfma_f32_16x16x32_bf16 v[110:113], v[180:183], v[212:215], v[110:113]
	v_mfma_f32_16x16x32_bf16 v[122:125], v[164:167], v[230:233], v[122:125]
	v_mfma_f32_16x16x32_bf16 v[126:129], v[180:183], v[230:233], v[126:129]
	s_setprio 0
	s_barrier
	s_add_i32 s3, s3, 2
	s_add_u32 s28, s28, 0x100
	s_addc_u32 s29, s29, 0
	s_cmpk_gt_u32 s3, 0x55
	s_cbranch_scc0 .LBB0_860
	s_and_b64 vcc, exec, s[18:19]
	s_cbranch_vccz .LBB0_863
	s_barrier
